# MFMA accumulate chains, chain boundaries share src0 (first operand) instead of src1
# baseline (speedup 1.0000x reference)
; #define PG8_STAGE(bufoff, gbase, voff) do { _Pragma("unroll") for (int _i = 0; _i < 2; ++_i) \
;         __builtin_amdgcn_global_load_lds((const unsigned*)((const char*)(gbase) + (voff)[_i]), (LAS unsigned*)(lds + (bufoff) + ldsw + _i * 8192), 16, 0, 0); } while (0)
; #define PG8_LDA(dst, b, h) do { _Pragma("unroll") for (int m = 0; m < 4; ++m) _Pragma("unroll") for (int k = 0; k < 2; ++k) dst[m][k] = *(const LAS bf16x8*)(lds + PG8_SA(b, h) + aoff + m * 2048 + k * 1024); } while (0)
; #define PG8_LDB(dst, b, h) do { _Pragma("unroll") for (int n = 0; n < 2; ++n) _Pragma("unroll") for (int k = 0; k < 2; ++k) dst[n][k] = *(const LAS bf16x8*)(lds + PG8_SB(b, h) + boff + n * 2048 + k * 1024); } while (0)
; #define PG8_MMA(ai, bj, At, Bt) do { __builtin_amdgcn_s_setprio(1); _Pragma("unroll") for (int m = 0; m < 4; ++m) _Pragma("unroll") for (int n = 0; n < 2; ++n) _Pragma("unroll") for (int k = 0; k < 2; ++k) \
;         acc[ai][bj][m][n] = __builtin_amdgcn_mfma_f32_16x16x32_bf16(Bt[n][k], At[m][k], acc[ai][bj][m][n], 0, 0, 0); __builtin_amdgcn_s_setprio(0); } while (0)
; #define PG8_WAIT_V(n) asm volatile("s_waitcnt vmcnt(" #n ")" ::: "memory")
; #define PG8_WAIT_L(n) asm volatile("s_waitcnt lgkmcnt(" #n ")" ::: "memory")
; #define PG8_BAR __builtin_amdgcn_s_barrier()
; #define PG8_SCHED __builtin_amdgcn_sched_barrier(0)
; template <class Epi>
; __device__ __forceinline__ void gemm_phase(LAS unsigned char* lds, const Gemm g, const StaticOrder& S, const Epi& E) {
;     ...
;             const char* a2 = last ? nA : cA + (size_t)(t + 2) * kstep; const char* b2 = last ? nB : cB + (size_t)(t + 2) * kstep;
;             const char* a3 = a2 + kstep; const char* b3 = b2 + kstep;
;             PG8_LDB(B0, 0, 0); PG8_LDB(B1, 0, 1); PG8_SCHED; PG8_LDA(At, 0, 0); PG8_STAGE(PG8_SA(1, 1), a1 + hstepA, voffA);
;             PG8_WAIT_V(8); PG8_WAIT_L(0); PG8_BAR; PG8_MMA(0, 0, At, B0); PG8_MMA(0, 1, At, B1); PG8_BAR; PG8_SCHED;
;             PG8_LDA(At, 0, 1); PG8_STAGE(PG8_SB(0, 0), b2, voffB); PG8_STAGE(PG8_SB(0, 1), b2 + hstepB, voffB); PG8_STAGE(PG8_SA(0, 0), a2, voffA);
.LBB0_245:
	ds_read_b128 v[152:155], v148
	ds_read_b128 v[156:159], v148 offset:1024
	ds_read_b128 v[160:163], v148 offset:2048
	ds_read_b128 v[164:167], v148 offset:3072
	ds_read_b128 v[168:171], v149
	ds_read_b128 v[172:175], v149 offset:1024
	ds_read_b128 v[176:179], v149 offset:2048
	ds_read_b128 v[180:183], v149 offset:3072
	s_add_i32 s64, s26, 2
	s_add_u32 s27, s24, 0xfff80080
	s_addc_u32 s30, s25, -1
	s_cmp_eq_u32 s54, s26
	s_cselect_b32 s26, s61, s62
	s_cselect_b32 s31, s15, s30
	s_cselect_b32 s30, s17, s27
	s_cselect_b32 s27, s60, s63
	v_lshl_add_u64 v[220:221], s[24:25], 0, v[138:139]
	s_add_i32 m0, s44, 0xc000
	ds_read_b128 v[184:187], v150
	ds_read_b128 v[188:191], v150 offset:1024
	ds_read_b128 v[192:195], v150 offset:2048
	ds_read_b128 v[196:199], v150 offset:3072
	ds_read_b128 v[200:203], v150 offset:4096
	ds_read_b128 v[208:211], v150 offset:5120
	ds_read_b128 v[212:215], v150 offset:6144
	ds_read_b128 v[216:219], v150 offset:7168
	global_load_lds_dwordx4 v[220:221], off
	v_lshl_add_u64 v[220:221], s[24:25], 0, v[140:141]
	s_add_i32 m0, s44, 0xe000
	s_nop 0
	global_load_lds_dwordx4 v[220:221], off
	s_waitcnt vmcnt(8)
	s_waitcnt lgkmcnt(0)
	s_barrier
	s_setprio 1
	s_waitcnt lgkmcnt(0)
	v_mfma_f32_16x16x32_bf16 v[120:123], v[152:155], v[184:187], v[120:123]
	v_mfma_f32_16x16x32_bf16 v[120:123], v[156:159], v[188:191], v[120:123]
	v_mfma_f32_16x16x32_bf16 v[108:111], v[156:159], v[196:199], v[108:111]
	v_mfma_f32_16x16x32_bf16 v[108:111], v[152:155], v[192:195], v[108:111]
	v_mfma_f32_16x16x32_bf16 v[92:95], v[152:155], v[200:203], v[92:95]
	v_mfma_f32_16x16x32_bf16 v[92:95], v[156:159], v[208:211], v[92:95]
	v_mfma_f32_16x16x32_bf16 v[76:79], v[156:159], v[216:219], v[76:79]
	v_mfma_f32_16x16x32_bf16 v[76:79], v[152:155], v[212:215], v[76:79]
	v_mfma_f32_16x16x32_bf16 v[68:71], v[160:163], v[212:215], v[68:71]
	v_mfma_f32_16x16x32_bf16 v[68:71], v[164:167], v[216:219], v[68:71]
	v_mfma_f32_16x16x32_bf16 v[84:87], v[164:167], v[208:211], v[84:87]
	v_mfma_f32_16x16x32_bf16 v[84:87], v[160:163], v[200:203], v[84:87]
	v_mfma_f32_16x16x32_bf16 v[100:103], v[160:163], v[192:195], v[100:103]
	v_mfma_f32_16x16x32_bf16 v[100:103], v[164:167], v[196:199], v[100:103]
	v_mfma_f32_16x16x32_bf16 v[116:119], v[164:167], v[188:191], v[116:119]
	v_mfma_f32_16x16x32_bf16 v[116:119], v[160:163], v[184:187], v[116:119]
	s_setprio 0
	s_setprio 1
	v_mfma_f32_16x16x32_bf16 v[124:127], v[168:171], v[184:187], v[124:127]
	v_mfma_f32_16x16x32_bf16 v[124:127], v[172:175], v[188:191], v[124:127]
	v_mfma_f32_16x16x32_bf16 v[104:107], v[172:175], v[196:199], v[104:107]
	v_mfma_f32_16x16x32_bf16 v[104:107], v[168:171], v[192:195], v[104:107]
	v_mfma_f32_16x16x32_bf16 v[88:91], v[168:171], v[200:203], v[88:91]
	v_mfma_f32_16x16x32_bf16 v[88:91], v[172:175], v[208:211], v[88:91]
	v_mfma_f32_16x16x32_bf16 v[72:75], v[172:175], v[216:219], v[72:75]
	v_mfma_f32_16x16x32_bf16 v[72:75], v[168:171], v[212:215], v[72:75]
	v_mfma_f32_16x16x32_bf16 v[64:67], v[176:179], v[212:215], v[64:67]
	v_mfma_f32_16x16x32_bf16 v[64:67], v[180:183], v[216:219], v[64:67]
	v_mfma_f32_16x16x32_bf16 v[80:83], v[180:183], v[208:211], v[80:83]
	v_mfma_f32_16x16x32_bf16 v[80:83], v[176:179], v[200:203], v[80:83]
	v_mfma_f32_16x16x32_bf16 v[96:99], v[176:179], v[192:195], v[96:99]
	v_mfma_f32_16x16x32_bf16 v[96:99], v[180:183], v[196:199], v[96:99]
	v_mfma_f32_16x16x32_bf16 v[112:115], v[180:183], v[188:191], v[112:115]
	v_mfma_f32_16x16x32_bf16 v[112:115], v[176:179], v[184:187], v[112:115]
	s_setprio 0
	s_barrier
	s_add_i32 s65, s57, s33
	v_lshl_add_u64 v[220:221], s[26:27], 0, v[132:133]
	s_mov_b32 m0, s65
	ds_read_b128 v[184:187], v150 offset:16384
	ds_read_b128 v[188:191], v150 offset:17408
	ds_read_b128 v[192:195], v150 offset:18432
	ds_read_b128 v[196:199], v150 offset:19456
	ds_read_b128 v[200:203], v150 offset:20480
	ds_read_b128 v[208:211], v150 offset:21504
	ds_read_b128 v[212:215], v150 offset:22528
	ds_read_b128 v[216:219], v150 offset:23552
	global_load_lds_dwordx4 v[220:221], off
	s_add_i32 m0, s65, 0x2000
	s_add_u32 s66, s26, 0x80000
	v_lshl_add_u64 v[222:223], s[26:27], 0, v[128:129]
	s_addc_u32 s67, s27, 0
	s_add_i32 s65, s58, s33
	global_load_lds_dwordx4 v[222:223], off
	v_lshl_add_u64 v[224:225], s[66:67], 0, v[132:133]
	s_mov_b32 m0, s65
	v_lshl_add_u64 v[226:227], s[30:31], 0, v[130:131]
	global_load_lds_dwordx4 v[224:225], off
	v_lshl_add_u64 v[224:225], s[66:67], 0, v[128:129]
	s_add_i32 m0, s65, 0x2000
	s_nop 0
	global_load_lds_dwordx4 v[224:225], off
	v_lshl_add_u64 v[224:225], s[30:31], 0, v[134:135]
	s_mov_b32 m0, s44
	s_nop 0
	global_load_lds_dwordx4 v[224:225], off
	s_mov_b32 m0, s45
	s_nop 0
	global_load_lds_dwordx4 v[226:227], off
	s_waitcnt vmcnt(8)
	s_waitcnt lgkmcnt(0)
	s_barrier
; #define PG8_STAGE(bufoff, gbase, voff) do { _Pragma("unroll") for (int _i = 0; _i < 2; ++_i) \
;         __builtin_amdgcn_global_load_lds((const unsigned*)((const char*)(gbase) + (voff)[_i]), (LAS unsigned*)(lds + (bufoff) + ldsw + _i * 8192), 16, 0, 0); } while (0)
; #define PG8_LDA(dst, b, h) do { _Pragma("unroll") for (int m = 0; m < 4; ++m) _Pragma("unroll") for (int k = 0; k < 2; ++k) dst[m][k] = *(const LAS bf16x8*)(lds + PG8_SA(b, h) + aoff + m * 2048 + k * 1024); } while (0)
; #define PG8_LDB(dst, b, h) do { _Pragma("unroll") for (int n = 0; n < 2; ++n) _Pragma("unroll") for (int k = 0; k < 2; ++k) dst[n][k] = *(const LAS bf16x8*)(lds + PG8_SB(b, h) + boff + n * 2048 + k * 1024); } while (0)
; #define PG8_MMA(ai, bj, At, Bt) do { __builtin_amdgcn_s_setprio(1); _Pragma("unroll") for (int m = 0; m < 4; ++m) _Pragma("unroll") for (int n = 0; n < 2; ++n) _Pragma("unroll") for (int k = 0; k < 2; ++k) \
;         acc[ai][bj][m][n] = __builtin_amdgcn_mfma_f32_16x16x32_bf16(Bt[n][k], At[m][k], acc[ai][bj][m][n], 0, 0, 0); __builtin_amdgcn_s_setprio(0); } while (0)
; #define PG8_WAIT_V(n) asm volatile("s_waitcnt vmcnt(" #n ")" ::: "memory")
; #define PG8_WAIT_L(n) asm volatile("s_waitcnt lgkmcnt(" #n ")" ::: "memory")
; #define PG8_BAR __builtin_amdgcn_s_barrier()
; #define PG8_SCHED __builtin_amdgcn_sched_barrier(0)
; template <class Epi>
; __device__ __forceinline__ void gemm_phase(LAS unsigned char* lds, const Gemm g, const StaticOrder& S, const Epi& E) {
;     ...
;             PG8_WAIT_V(8); PG8_WAIT_L(0); PG8_BAR; PG8_MMA(1, 0, At, B0); PG8_MMA(1, 1, At, B1); PG8_BAR; PG8_SCHED;
;             PG8_LDB(B0, 1, 0); PG8_LDB(B1, 1, 1); PG8_SCHED; PG8_LDA(At, 1, 0); PG8_STAGE(PG8_SA(0, 1), a2 + hstepA, voffA);
;             PG8_WAIT_V(8); PG8_WAIT_L(0); PG8_BAR; PG8_MMA(0, 0, At, B0); PG8_MMA(0, 1, At, B1); PG8_BAR; PG8_SCHED;
;             PG8_LDA(At, 1, 1); PG8_STAGE(PG8_SB(1, 0), b3, voffB); PG8_STAGE(PG8_SB(1, 1), b3 + hstepB, voffB); PG8_STAGE(PG8_SA(1, 0), a3, voffA);
	s_setprio 1
	s_waitcnt lgkmcnt(0)
	v_mfma_f32_16x16x32_bf16 v[60:63], v[152:155], v[184:187], v[60:63]
	v_mfma_f32_16x16x32_bf16 v[60:63], v[156:159], v[188:191], v[60:63]
	v_mfma_f32_16x16x32_bf16 v[44:47], v[156:159], v[196:199], v[44:47]
	v_mfma_f32_16x16x32_bf16 v[44:47], v[152:155], v[192:195], v[44:47]
	v_mfma_f32_16x16x32_bf16 v[28:31], v[152:155], v[200:203], v[28:31]
	v_mfma_f32_16x16x32_bf16 v[28:31], v[156:159], v[208:211], v[28:31]
	v_mfma_f32_16x16x32_bf16 v[12:15], v[156:159], v[216:219], v[12:15]
	v_mfma_f32_16x16x32_bf16 v[12:15], v[152:155], v[212:215], v[12:15]
	v_mfma_f32_16x16x32_bf16 v[4:7], v[160:163], v[212:215], v[4:7]
	v_mfma_f32_16x16x32_bf16 v[4:7], v[164:167], v[216:219], v[4:7]
	v_mfma_f32_16x16x32_bf16 v[20:23], v[164:167], v[208:211], v[20:23]
	v_mfma_f32_16x16x32_bf16 v[20:23], v[160:163], v[200:203], v[20:23]
	v_mfma_f32_16x16x32_bf16 v[36:39], v[160:163], v[192:195], v[36:39]
	v_mfma_f32_16x16x32_bf16 v[36:39], v[164:167], v[196:199], v[36:39]
	v_mfma_f32_16x16x32_bf16 v[52:55], v[164:167], v[188:191], v[52:55]
	v_mfma_f32_16x16x32_bf16 v[52:55], v[160:163], v[184:187], v[52:55]
	s_setprio 0
	s_setprio 1
	v_mfma_f32_16x16x32_bf16 v[56:59], v[168:171], v[184:187], v[56:59]
	v_mfma_f32_16x16x32_bf16 v[56:59], v[172:175], v[188:191], v[56:59]
	v_mfma_f32_16x16x32_bf16 v[40:43], v[172:175], v[196:199], v[40:43]
	v_mfma_f32_16x16x32_bf16 v[40:43], v[168:171], v[192:195], v[40:43]
	v_mfma_f32_16x16x32_bf16 v[24:27], v[168:171], v[200:203], v[24:27]
	v_mfma_f32_16x16x32_bf16 v[24:27], v[172:175], v[208:211], v[24:27]
	v_mfma_f32_16x16x32_bf16 v[8:11], v[172:175], v[216:219], v[8:11]
	v_mfma_f32_16x16x32_bf16 v[8:11], v[168:171], v[212:215], v[8:11]
	v_mfma_f32_16x16x32_bf16 v[0:3], v[176:179], v[212:215], v[0:3]
	v_mfma_f32_16x16x32_bf16 v[0:3], v[180:183], v[216:219], v[0:3]
	v_mfma_f32_16x16x32_bf16 v[16:19], v[180:183], v[208:211], v[16:19]
	v_mfma_f32_16x16x32_bf16 v[16:19], v[176:179], v[200:203], v[16:19]
	v_mfma_f32_16x16x32_bf16 v[32:35], v[176:179], v[192:195], v[32:35]
	v_mfma_f32_16x16x32_bf16 v[32:35], v[180:183], v[196:199], v[32:35]
	v_mfma_f32_16x16x32_bf16 v[48:51], v[180:183], v[188:191], v[48:51]
	v_mfma_f32_16x16x32_bf16 v[48:51], v[176:179], v[184:187], v[48:51]
	s_setprio 0
	s_barrier
	s_add_i32 s65, 0, 0x18000
	v_add_u32_e32 v151, s65, v146
	s_add_i32 s66, 0, 0x1c000
	ds_read_b128 v[152:155], v151
	ds_read_b128 v[156:159], v151 offset:1024
	ds_read_b128 v[160:163], v151 offset:2048
	ds_read_b128 v[164:167], v151 offset:3072
	v_add_u32_e32 v151, s66, v146
	ds_read_b128 v[168:171], v151
	ds_read_b128 v[172:175], v151 offset:1024
	ds_read_b128 v[176:179], v151 offset:2048
	ds_read_b128 v[180:183], v151 offset:3072
	s_add_u32 s30, s30, 0x80000
	s_addc_u32 s31, s31, 0
	s_mov_b32 m0, s46
	v_lshl_add_u64 v[230:231], s[30:31], 0, v[134:135]
	ds_read_b128 v[184:187], v150 offset:32768
	ds_read_b128 v[188:191], v150 offset:33792
	ds_read_b128 v[192:195], v150 offset:34816
	ds_read_b128 v[196:199], v150 offset:35840
	ds_read_b128 v[200:203], v150 offset:36864
	ds_read_b128 v[208:211], v150 offset:37888
	ds_read_b128 v[212:215], v150 offset:38912
	ds_read_b128 v[216:219], v150 offset:39936
	global_load_lds_dwordx4 v[230:231], off
	v_lshl_add_u64 v[230:231], s[30:31], 0, v[130:131]
	s_mov_b32 m0, s47
	s_nop 0
	global_load_lds_dwordx4 v[230:231], off
	s_waitcnt vmcnt(8)
	s_waitcnt lgkmcnt(0)
	s_barrier
	s_setprio 1
	s_waitcnt lgkmcnt(0)
	v_mfma_f32_16x16x32_bf16 v[120:123], v[152:155], v[184:187], v[120:123]
	v_mfma_f32_16x16x32_bf16 v[120:123], v[156:159], v[188:191], v[120:123]
	v_mfma_f32_16x16x32_bf16 v[108:111], v[156:159], v[196:199], v[108:111]
	v_mfma_f32_16x16x32_bf16 v[108:111], v[152:155], v[192:195], v[108:111]
	v_mfma_f32_16x16x32_bf16 v[92:95], v[152:155], v[200:203], v[92:95]
	v_mfma_f32_16x16x32_bf16 v[92:95], v[156:159], v[208:211], v[92:95]
	v_mfma_f32_16x16x32_bf16 v[76:79], v[156:159], v[216:219], v[76:79]
	v_mfma_f32_16x16x32_bf16 v[76:79], v[152:155], v[212:215], v[76:79]
	v_mfma_f32_16x16x32_bf16 v[68:71], v[160:163], v[212:215], v[68:71]
	v_mfma_f32_16x16x32_bf16 v[68:71], v[164:167], v[216:219], v[68:71]
	v_mfma_f32_16x16x32_bf16 v[84:87], v[164:167], v[208:211], v[84:87]
	v_mfma_f32_16x16x32_bf16 v[84:87], v[160:163], v[200:203], v[84:87]
	v_mfma_f32_16x16x32_bf16 v[100:103], v[160:163], v[192:195], v[100:103]
	v_mfma_f32_16x16x32_bf16 v[100:103], v[164:167], v[196:199], v[100:103]
	v_mfma_f32_16x16x32_bf16 v[116:119], v[164:167], v[188:191], v[116:119]
	v_mfma_f32_16x16x32_bf16 v[116:119], v[160:163], v[184:187], v[116:119]
	s_setprio 0
	s_setprio 1
	v_mfma_f32_16x16x32_bf16 v[124:127], v[168:171], v[184:187], v[124:127]
	v_mfma_f32_16x16x32_bf16 v[124:127], v[172:175], v[188:191], v[124:127]
	v_mfma_f32_16x16x32_bf16 v[104:107], v[172:175], v[196:199], v[104:107]
	v_mfma_f32_16x16x32_bf16 v[104:107], v[168:171], v[192:195], v[104:107]
	v_mfma_f32_16x16x32_bf16 v[88:91], v[168:171], v[200:203], v[88:91]
	v_mfma_f32_16x16x32_bf16 v[88:91], v[172:175], v[208:211], v[88:91]
	v_mfma_f32_16x16x32_bf16 v[72:75], v[172:175], v[216:219], v[72:75]
	v_mfma_f32_16x16x32_bf16 v[72:75], v[168:171], v[212:215], v[72:75]
	v_mfma_f32_16x16x32_bf16 v[64:67], v[176:179], v[212:215], v[64:67]
	v_mfma_f32_16x16x32_bf16 v[64:67], v[180:183], v[216:219], v[64:67]
	v_mfma_f32_16x16x32_bf16 v[80:83], v[180:183], v[208:211], v[80:83]
	v_mfma_f32_16x16x32_bf16 v[80:83], v[176:179], v[200:203], v[80:83]
	v_mfma_f32_16x16x32_bf16 v[96:99], v[176:179], v[192:195], v[96:99]
	v_mfma_f32_16x16x32_bf16 v[96:99], v[180:183], v[196:199], v[96:99]
	v_mfma_f32_16x16x32_bf16 v[112:115], v[180:183], v[188:191], v[112:115]
	v_mfma_f32_16x16x32_bf16 v[112:115], v[176:179], v[184:187], v[112:115]
	s_setprio 0
	s_barrier
; #define PG8_STAGE(bufoff, gbase, voff) do { _Pragma("unroll") for (int _i = 0; _i < 2; ++_i) \
;         __builtin_amdgcn_global_load_lds((const unsigned*)((const char*)(gbase) + (voff)[_i]), (LAS unsigned*)(lds + (bufoff) + ldsw + _i * 8192), 16, 0, 0); } while (0)
; #define PG8_LDA(dst, b, h) do { _Pragma("unroll") for (int m = 0; m < 4; ++m) _Pragma("unroll") for (int k = 0; k < 2; ++k) dst[m][k] = *(const LAS bf16x8*)(lds + PG8_SA(b, h) + aoff + m * 2048 + k * 1024); } while (0)
; #define PG8_MMA(ai, bj, At, Bt) do { __builtin_amdgcn_s_setprio(1); _Pragma("unroll") for (int m = 0; m < 4; ++m) _Pragma("unroll") for (int n = 0; n < 2; ++n) _Pragma("unroll") for (int k = 0; k < 2; ++k) \
;         acc[ai][bj][m][n] = __builtin_amdgcn_mfma_f32_16x16x32_bf16(Bt[n][k], At[m][k], acc[ai][bj][m][n], 0, 0, 0); __builtin_amdgcn_s_setprio(0); } while (0)
; #define PG8_WAIT_V(n) asm volatile("s_waitcnt vmcnt(" #n ")" ::: "memory")
; #define PG8_WAIT_L(n) asm volatile("s_waitcnt lgkmcnt(" #n ")" ::: "memory")
; #define PG8_BAR __builtin_amdgcn_s_barrier()
; #define PG8_SCHED __builtin_amdgcn_sched_barrier(0)
; template <class Epi>
; __device__ __forceinline__ void gemm_phase(LAS unsigned char* lds, const Gemm g, const StaticOrder& S, const Epi& E) {
;     ...
;             PG8_LDA(At, 1, 1); PG8_STAGE(PG8_SB(1, 0), b3, voffB); PG8_STAGE(PG8_SB(1, 1), b3 + hstepB, voffB); PG8_STAGE(PG8_SA(1, 0), a3, voffA);
;             PG8_WAIT_V(8); PG8_WAIT_L(0); PG8_BAR; PG8_MMA(1, 0, At, B0); PG8_MMA(1, 1, At, B1); PG8_BAR; PG8_SCHED;
;         }
	s_add_i32 s30, s65, s33
	v_lshl_add_u64 v[220:221], v[220:221], 0, s[8:9]
	s_mov_b32 m0, s30
	ds_read_b128 v[184:187], v150 offset:49152
	ds_read_b128 v[188:191], v150 offset:50176
	ds_read_b128 v[192:195], v150 offset:51200
	ds_read_b128 v[196:199], v150 offset:52224
	ds_read_b128 v[200:203], v150 offset:53248
	ds_read_b128 v[208:211], v150 offset:54272
	ds_read_b128 v[212:215], v150 offset:55296
	ds_read_b128 v[216:219], v150 offset:56320
	global_load_lds_dwordx4 v[220:221], off
	s_add_i32 m0, s30, 0x2000
	s_add_u32 s26, s26, 0x80080
	v_lshl_add_u64 v[220:221], v[222:223], 0, s[8:9]
	s_addc_u32 s27, s27, 0
	s_add_i32 s30, s66, s33
	global_load_lds_dwordx4 v[220:221], off
	v_lshl_add_u64 v[220:221], s[26:27], 0, v[132:133]
	s_mov_b32 m0, s30
	s_nop 0
	global_load_lds_dwordx4 v[220:221], off
	v_lshl_add_u64 v[220:221], s[26:27], 0, v[128:129]
	s_add_i32 m0, s30, 0x2000
	s_nop 0
	global_load_lds_dwordx4 v[220:221], off
	v_lshl_add_u64 v[220:221], v[224:225], 0, s[8:9]
	s_mov_b32 m0, s52
	s_nop 0
	global_load_lds_dwordx4 v[220:221], off
	v_lshl_add_u64 v[220:221], v[226:227], 0, s[8:9]
	s_mov_b32 m0, s53
	s_nop 0
	global_load_lds_dwordx4 v[220:221], off
	s_waitcnt vmcnt(8)
	s_waitcnt lgkmcnt(0)
	s_barrier
	s_setprio 1
	s_waitcnt lgkmcnt(0)
	v_mfma_f32_16x16x32_bf16 v[60:63], v[152:155], v[184:187], v[60:63]
	v_mfma_f32_16x16x32_bf16 v[60:63], v[156:159], v[188:191], v[60:63]
	v_mfma_f32_16x16x32_bf16 v[44:47], v[156:159], v[196:199], v[44:47]
	v_mfma_f32_16x16x32_bf16 v[44:47], v[152:155], v[192:195], v[44:47]
	v_mfma_f32_16x16x32_bf16 v[28:31], v[152:155], v[200:203], v[28:31]
	v_mfma_f32_16x16x32_bf16 v[28:31], v[156:159], v[208:211], v[28:31]
	v_mfma_f32_16x16x32_bf16 v[12:15], v[156:159], v[216:219], v[12:15]
	v_mfma_f32_16x16x32_bf16 v[12:15], v[152:155], v[212:215], v[12:15]
	v_mfma_f32_16x16x32_bf16 v[4:7], v[160:163], v[212:215], v[4:7]
	v_mfma_f32_16x16x32_bf16 v[4:7], v[164:167], v[216:219], v[4:7]
	v_mfma_f32_16x16x32_bf16 v[20:23], v[164:167], v[208:211], v[20:23]
	v_mfma_f32_16x16x32_bf16 v[20:23], v[160:163], v[200:203], v[20:23]
	v_mfma_f32_16x16x32_bf16 v[36:39], v[160:163], v[192:195], v[36:39]
	v_mfma_f32_16x16x32_bf16 v[36:39], v[164:167], v[196:199], v[36:39]
	v_mfma_f32_16x16x32_bf16 v[52:55], v[164:167], v[188:191], v[52:55]
	v_mfma_f32_16x16x32_bf16 v[52:55], v[160:163], v[184:187], v[52:55]
	s_setprio 0
	s_setprio 1
	v_mfma_f32_16x16x32_bf16 v[56:59], v[168:171], v[184:187], v[56:59]
	v_mfma_f32_16x16x32_bf16 v[56:59], v[172:175], v[188:191], v[56:59]
	v_mfma_f32_16x16x32_bf16 v[40:43], v[172:175], v[196:199], v[40:43]
	v_mfma_f32_16x16x32_bf16 v[40:43], v[168:171], v[192:195], v[40:43]
	v_mfma_f32_16x16x32_bf16 v[24:27], v[168:171], v[200:203], v[24:27]
	v_mfma_f32_16x16x32_bf16 v[24:27], v[172:175], v[208:211], v[24:27]
	v_mfma_f32_16x16x32_bf16 v[8:11], v[172:175], v[216:219], v[8:11]
	v_mfma_f32_16x16x32_bf16 v[8:11], v[168:171], v[212:215], v[8:11]
	v_mfma_f32_16x16x32_bf16 v[0:3], v[176:179], v[212:215], v[0:3]
	v_mfma_f32_16x16x32_bf16 v[0:3], v[180:183], v[216:219], v[0:3]
	v_mfma_f32_16x16x32_bf16 v[16:19], v[180:183], v[208:211], v[16:19]
	v_mfma_f32_16x16x32_bf16 v[16:19], v[176:179], v[200:203], v[16:19]
	v_mfma_f32_16x16x32_bf16 v[32:35], v[176:179], v[192:195], v[32:35]
	v_mfma_f32_16x16x32_bf16 v[32:35], v[180:183], v[196:199], v[32:35]
	v_mfma_f32_16x16x32_bf16 v[48:51], v[180:183], v[188:191], v[48:51]
	v_mfma_f32_16x16x32_bf16 v[48:51], v[176:179], v[184:187], v[48:51]
	s_setprio 0
	s_barrier
	s_add_u32 s24, s24, 0x100
	s_addc_u32 s25, s25, 0
	s_add_u32 s62, s62, 0x100
	s_addc_u32 s63, s63, 0
	s_cmp_ge_i32 s64, s49
	s_mov_b32 s26, s64
	s_cbranch_scc0 .LBB0_245

; #define PG8_STAGE(bufoff, gbase, voff) do { _Pragma("unroll") for (int _i = 0; _i < 2; ++_i) \
;         __builtin_amdgcn_global_load_lds((const unsigned*)((const char*)(gbase) + (voff)[_i]), (LAS unsigned*)(lds + (bufoff) + ldsw + _i * 8192), 16, 0, 0); } while (0)
; #define PG8_LDA(dst, b, h) do { _Pragma("unroll") for (int m = 0; m < 4; ++m) _Pragma("unroll") for (int k = 0; k < 2; ++k) dst[m][k] = *(const LAS bf16x8*)(lds + PG8_SA(b, h) + aoff + m * 2048 + k * 1024); } while (0)
; #define PG8_LDB(dst, b, h) do { _Pragma("unroll") for (int n = 0; n < 2; ++n) _Pragma("unroll") for (int k = 0; k < 2; ++k) dst[n][k] = *(const LAS bf16x8*)(lds + PG8_SB(b, h) + boff + n * 2048 + k * 1024); } while (0)
; #define PG8_MMA(ai, bj, At, Bt) do { __builtin_amdgcn_s_setprio(1); _Pragma("unroll") for (int m = 0; m < 4; ++m) _Pragma("unroll") for (int n = 0; n < 2; ++n) _Pragma("unroll") for (int k = 0; k < 2; ++k) \
;         acc[ai][bj][m][n] = __builtin_amdgcn_mfma_f32_16x16x32_bf16(Bt[n][k], At[m][k], acc[ai][bj][m][n], 0, 0, 0); __builtin_amdgcn_s_setprio(0); } while (0)
; #define PG8_WAIT_V(n) asm volatile("s_waitcnt vmcnt(" #n ")" ::: "memory")
; #define PG8_WAIT_L(n) asm volatile("s_waitcnt lgkmcnt(" #n ")" ::: "memory")
; #define PG8_BAR __builtin_amdgcn_s_barrier()
; #define PG8_SCHED __builtin_amdgcn_sched_barrier(0)
; template <class Epi>
; __device__ __forceinline__ void gemm_phase(LAS unsigned char* lds, const Gemm g, const StaticOrder& S, const Epi& E) {
;     ...
;             const char* a2 = last ? nA : cA + (size_t)(t + 2) * kstep; const char* b2 = last ? nB : cB + (size_t)(t + 2) * kstep;
;             const char* a3 = a2 + kstep; const char* b3 = b2 + kstep;
;             PG8_LDB(B0, 0, 0); PG8_LDB(B1, 0, 1); PG8_SCHED; PG8_LDA(At, 0, 0); PG8_STAGE(PG8_SA(1, 1), a1 + hstepA, voffA);
;             PG8_WAIT_V(8); PG8_WAIT_L(0); PG8_BAR; PG8_MMA(0, 0, At, B0); PG8_MMA(0, 1, At, B1); PG8_BAR; PG8_SCHED;
;             PG8_LDA(At, 0, 1); PG8_STAGE(PG8_SB(0, 0), b2, voffB); PG8_STAGE(PG8_SB(0, 1), b2 + hstepB, voffB); PG8_STAGE(PG8_SA(0, 0), a2, voffA);
.LBB0_445:
	ds_read_b128 v[148:151], v218
	ds_read_b128 v[152:155], v218 offset:1024
	ds_read_b128 v[156:159], v218 offset:2048
	ds_read_b128 v[160:163], v218 offset:3072
	ds_read_b128 v[164:167], v219
	ds_read_b128 v[168:171], v219 offset:1024
	ds_read_b128 v[172:175], v219 offset:2048
	ds_read_b128 v[176:179], v219 offset:3072
	s_add_i32 s65, s34, 2
	s_add_u32 s30, s4, 0x100
	s_addc_u32 s31, s5, 0
	s_cmp_eq_u32 s49, s34
	s_cselect_b32 s34, s26, s1
	s_cselect_b32 s37, s11, s31
	s_cselect_b32 s36, s10, s30
	s_cselect_b32 s35, s27, s64
	v_lshl_add_u64 v[216:217], s[4:5], 0, v[140:141]
	s_add_i32 m0, s41, 0xc000
	ds_read_b128 v[180:183], v220
	ds_read_b128 v[184:187], v220 offset:1024
	ds_read_b128 v[188:191], v220 offset:2048
	ds_read_b128 v[192:195], v220 offset:3072
	ds_read_b128 v[196:199], v220 offset:4096
	ds_read_b128 v[200:203], v220 offset:5120
	ds_read_b128 v[208:211], v220 offset:6144
	ds_read_b128 v[212:215], v220 offset:7168
	global_load_lds_dwordx4 v[216:217], off
	v_lshl_add_u64 v[216:217], s[4:5], 0, v[142:143]
	s_add_i32 m0, s41, 0xe000
	s_nop 0
	global_load_lds_dwordx4 v[216:217], off
	s_waitcnt vmcnt(8)
	s_waitcnt lgkmcnt(0)
	s_barrier
	s_setprio 1
	s_waitcnt lgkmcnt(0)
	v_mfma_f32_16x16x32_bf16 v[124:127], v[148:151], v[180:183], v[124:127]
	v_mfma_f32_16x16x32_bf16 v[124:127], v[152:155], v[184:187], v[124:127]
	v_mfma_f32_16x16x32_bf16 v[116:119], v[152:155], v[192:195], v[116:119]
	v_mfma_f32_16x16x32_bf16 v[116:119], v[148:151], v[188:191], v[116:119]
	v_mfma_f32_16x16x32_bf16 v[104:107], v[148:151], v[196:199], v[104:107]
	v_mfma_f32_16x16x32_bf16 v[104:107], v[152:155], v[200:203], v[104:107]
	v_mfma_f32_16x16x32_bf16 v[88:91], v[152:155], v[212:215], v[88:91]
	v_mfma_f32_16x16x32_bf16 v[88:91], v[148:151], v[208:211], v[88:91]
	v_mfma_f32_16x16x32_bf16 v[80:83], v[156:159], v[208:211], v[80:83]
	v_mfma_f32_16x16x32_bf16 v[80:83], v[160:163], v[212:215], v[80:83]
	v_mfma_f32_16x16x32_bf16 v[96:99], v[160:163], v[200:203], v[96:99]
	v_mfma_f32_16x16x32_bf16 v[96:99], v[156:159], v[196:199], v[96:99]
	v_mfma_f32_16x16x32_bf16 v[112:115], v[156:159], v[188:191], v[112:115]
	v_mfma_f32_16x16x32_bf16 v[112:115], v[160:163], v[192:195], v[112:115]
	v_mfma_f32_16x16x32_bf16 v[120:123], v[160:163], v[184:187], v[120:123]
	v_mfma_f32_16x16x32_bf16 v[120:123], v[156:159], v[180:183], v[120:123]
	s_setprio 0
	s_setprio 1
	v_mfma_f32_16x16x32_bf16 v[108:111], v[164:167], v[180:183], v[108:111]
	v_mfma_f32_16x16x32_bf16 v[108:111], v[168:171], v[184:187], v[108:111]
	v_mfma_f32_16x16x32_bf16 v[92:95], v[168:171], v[192:195], v[92:95]
	v_mfma_f32_16x16x32_bf16 v[92:95], v[164:167], v[188:191], v[92:95]
	v_mfma_f32_16x16x32_bf16 v[76:79], v[164:167], v[196:199], v[76:79]
	v_mfma_f32_16x16x32_bf16 v[76:79], v[168:171], v[200:203], v[76:79]
	v_mfma_f32_16x16x32_bf16 v[68:71], v[168:171], v[212:215], v[68:71]
	v_mfma_f32_16x16x32_bf16 v[68:71], v[164:167], v[208:211], v[68:71]
	v_mfma_f32_16x16x32_bf16 v[64:67], v[172:175], v[208:211], v[64:67]
	v_mfma_f32_16x16x32_bf16 v[64:67], v[176:179], v[212:215], v[64:67]
	v_mfma_f32_16x16x32_bf16 v[72:75], v[176:179], v[200:203], v[72:75]
	v_mfma_f32_16x16x32_bf16 v[72:75], v[172:175], v[196:199], v[72:75]
	v_mfma_f32_16x16x32_bf16 v[84:87], v[172:175], v[188:191], v[84:87]
	v_mfma_f32_16x16x32_bf16 v[84:87], v[176:179], v[192:195], v[84:87]
	v_mfma_f32_16x16x32_bf16 v[100:103], v[176:179], v[184:187], v[100:103]
	v_mfma_f32_16x16x32_bf16 v[100:103], v[172:175], v[180:183], v[100:103]
	s_setprio 0
	s_barrier
	s_add_i32 s4, s54, s40
	v_lshl_add_u64 v[216:217], s[34:35], 0, v[130:131]
	s_mov_b32 m0, s4
	ds_read_b128 v[180:183], v220 offset:16384
	ds_read_b128 v[184:187], v220 offset:17408
	ds_read_b128 v[188:191], v220 offset:18432
	ds_read_b128 v[192:195], v220 offset:19456
	ds_read_b128 v[196:199], v220 offset:20480
	ds_read_b128 v[200:203], v220 offset:21504
	ds_read_b128 v[208:211], v220 offset:22528
	ds_read_b128 v[212:215], v220 offset:23552
	global_load_lds_dwordx4 v[216:217], off
	s_add_i32 m0, s4, 0x2000
	s_add_u32 s4, s34, 0x158000
	v_lshl_add_u64 v[222:223], s[34:35], 0, v[134:135]
	s_addc_u32 s5, s35, 0
	s_add_i32 s66, s55, s40
	global_load_lds_dwordx4 v[222:223], off
	v_lshl_add_u64 v[224:225], s[4:5], 0, v[130:131]
	s_mov_b32 m0, s66
	v_lshl_add_u64 v[226:227], s[36:37], 0, v[132:133]
	global_load_lds_dwordx4 v[224:225], off
	v_lshl_add_u64 v[224:225], s[4:5], 0, v[134:135]
	s_add_i32 m0, s66, 0x2000
	s_nop 0
	global_load_lds_dwordx4 v[224:225], off
	v_lshl_add_u64 v[224:225], s[36:37], 0, v[128:129]
	s_mov_b32 m0, s41
	s_nop 0
	global_load_lds_dwordx4 v[224:225], off
	s_mov_b32 m0, s42
	s_nop 0
	global_load_lds_dwordx4 v[226:227], off
	s_waitcnt vmcnt(8)
	s_waitcnt lgkmcnt(0)
	s_barrier
; #define PG8_STAGE(bufoff, gbase, voff) do { _Pragma("unroll") for (int _i = 0; _i < 2; ++_i) \
;         __builtin_amdgcn_global_load_lds((const unsigned*)((const char*)(gbase) + (voff)[_i]), (LAS unsigned*)(lds + (bufoff) + ldsw + _i * 8192), 16, 0, 0); } while (0)
; #define PG8_LDA(dst, b, h) do { _Pragma("unroll") for (int m = 0; m < 4; ++m) _Pragma("unroll") for (int k = 0; k < 2; ++k) dst[m][k] = *(const LAS bf16x8*)(lds + PG8_SA(b, h) + aoff + m * 2048 + k * 1024); } while (0)
; #define PG8_LDB(dst, b, h) do { _Pragma("unroll") for (int n = 0; n < 2; ++n) _Pragma("unroll") for (int k = 0; k < 2; ++k) dst[n][k] = *(const LAS bf16x8*)(lds + PG8_SB(b, h) + boff + n * 2048 + k * 1024); } while (0)
; #define PG8_MMA(ai, bj, At, Bt) do { __builtin_amdgcn_s_setprio(1); _Pragma("unroll") for (int m = 0; m < 4; ++m) _Pragma("unroll") for (int n = 0; n < 2; ++n) _Pragma("unroll") for (int k = 0; k < 2; ++k) \
;         acc[ai][bj][m][n] = __builtin_amdgcn_mfma_f32_16x16x32_bf16(Bt[n][k], At[m][k], acc[ai][bj][m][n], 0, 0, 0); __builtin_amdgcn_s_setprio(0); } while (0)
; #define PG8_WAIT_V(n) asm volatile("s_waitcnt vmcnt(" #n ")" ::: "memory")
; #define PG8_WAIT_L(n) asm volatile("s_waitcnt lgkmcnt(" #n ")" ::: "memory")
; #define PG8_BAR __builtin_amdgcn_s_barrier()
; #define PG8_SCHED __builtin_amdgcn_sched_barrier(0)
; template <class Epi>
; __device__ __forceinline__ void gemm_phase(LAS unsigned char* lds, const Gemm g, const StaticOrder& S, const Epi& E) {
;     ...
;             PG8_WAIT_V(8); PG8_WAIT_L(0); PG8_BAR; PG8_MMA(1, 0, At, B0); PG8_MMA(1, 1, At, B1); PG8_BAR; PG8_SCHED;
;             PG8_LDB(B0, 1, 0); PG8_LDB(B1, 1, 1); PG8_SCHED; PG8_LDA(At, 1, 0); PG8_STAGE(PG8_SA(0, 1), a2 + hstepA, voffA);
;             PG8_WAIT_V(8); PG8_WAIT_L(0); PG8_BAR; PG8_MMA(0, 0, At, B0); PG8_MMA(0, 1, At, B1); PG8_BAR; PG8_SCHED;
;             PG8_LDA(At, 1, 1); PG8_STAGE(PG8_SB(1, 0), b3, voffB); PG8_STAGE(PG8_SB(1, 1), b3 + hstepB, voffB); PG8_STAGE(PG8_SA(1, 0), a3, voffA);
	s_setprio 1
	s_waitcnt lgkmcnt(0)
	v_mfma_f32_16x16x32_bf16 v[60:63], v[148:151], v[180:183], v[60:63]
	v_mfma_f32_16x16x32_bf16 v[60:63], v[152:155], v[184:187], v[60:63]
	v_mfma_f32_16x16x32_bf16 v[52:55], v[152:155], v[192:195], v[52:55]
	v_mfma_f32_16x16x32_bf16 v[52:55], v[148:151], v[188:191], v[52:55]
	v_mfma_f32_16x16x32_bf16 v[40:43], v[148:151], v[196:199], v[40:43]
	v_mfma_f32_16x16x32_bf16 v[40:43], v[152:155], v[200:203], v[40:43]
	v_mfma_f32_16x16x32_bf16 v[24:27], v[152:155], v[212:215], v[24:27]
	v_mfma_f32_16x16x32_bf16 v[24:27], v[148:151], v[208:211], v[24:27]
	v_mfma_f32_16x16x32_bf16 v[16:19], v[156:159], v[208:211], v[16:19]
	v_mfma_f32_16x16x32_bf16 v[16:19], v[160:163], v[212:215], v[16:19]
	v_mfma_f32_16x16x32_bf16 v[32:35], v[160:163], v[200:203], v[32:35]
	v_mfma_f32_16x16x32_bf16 v[32:35], v[156:159], v[196:199], v[32:35]
	v_mfma_f32_16x16x32_bf16 v[48:51], v[156:159], v[188:191], v[48:51]
	v_mfma_f32_16x16x32_bf16 v[48:51], v[160:163], v[192:195], v[48:51]
	v_mfma_f32_16x16x32_bf16 v[56:59], v[160:163], v[184:187], v[56:59]
	v_mfma_f32_16x16x32_bf16 v[56:59], v[156:159], v[180:183], v[56:59]
	s_setprio 0
	s_setprio 1
	v_mfma_f32_16x16x32_bf16 v[44:47], v[164:167], v[180:183], v[44:47]
	v_mfma_f32_16x16x32_bf16 v[44:47], v[168:171], v[184:187], v[44:47]
	v_mfma_f32_16x16x32_bf16 v[28:31], v[168:171], v[192:195], v[28:31]
	v_mfma_f32_16x16x32_bf16 v[28:31], v[164:167], v[188:191], v[28:31]
	v_mfma_f32_16x16x32_bf16 v[12:15], v[164:167], v[196:199], v[12:15]
	v_mfma_f32_16x16x32_bf16 v[12:15], v[168:171], v[200:203], v[12:15]
	v_mfma_f32_16x16x32_bf16 v[4:7], v[168:171], v[212:215], v[4:7]
	v_mfma_f32_16x16x32_bf16 v[4:7], v[164:167], v[208:211], v[4:7]
	v_mfma_f32_16x16x32_bf16 v[0:3], v[172:175], v[208:211], v[0:3]
	v_mfma_f32_16x16x32_bf16 v[0:3], v[176:179], v[212:215], v[0:3]
	v_mfma_f32_16x16x32_bf16 v[8:11], v[176:179], v[200:203], v[8:11]
	v_mfma_f32_16x16x32_bf16 v[8:11], v[172:175], v[196:199], v[8:11]
	v_mfma_f32_16x16x32_bf16 v[20:23], v[172:175], v[188:191], v[20:23]
	v_mfma_f32_16x16x32_bf16 v[20:23], v[176:179], v[192:195], v[20:23]
	v_mfma_f32_16x16x32_bf16 v[36:39], v[176:179], v[184:187], v[36:39]
	v_mfma_f32_16x16x32_bf16 v[36:39], v[172:175], v[180:183], v[36:39]
	s_setprio 0
	s_barrier
	s_add_i32 s66, 0, 0x18000
	s_add_i32 s67, 0, 0x1c000
	v_add_u32_e32 v160, s66, v207
	v_add_u32_e32 v176, s67, v207
	ds_read_b128 v[148:151], v160
	ds_read_b128 v[152:155], v160 offset:1024
	ds_read_b128 v[156:159], v160 offset:2048
	ds_read_b128 v[160:163], v160 offset:3072
	ds_read_b128 v[164:167], v176
	ds_read_b128 v[168:171], v176 offset:1024
	ds_read_b128 v[172:175], v176 offset:2048
	ds_read_b128 v[176:179], v176 offset:3072
	s_add_u32 s4, s36, 0x158000
	s_addc_u32 s5, s37, 0
	s_mov_b32 m0, s43
	v_lshl_add_u64 v[230:231], s[4:5], 0, v[128:129]
	ds_read_b128 v[180:183], v220 offset:32768
	ds_read_b128 v[184:187], v220 offset:33792
	ds_read_b128 v[188:191], v220 offset:34816
	ds_read_b128 v[192:195], v220 offset:35840
	ds_read_b128 v[196:199], v220 offset:36864
	ds_read_b128 v[200:203], v220 offset:37888
	ds_read_b128 v[208:211], v220 offset:38912
	ds_read_b128 v[212:215], v220 offset:39936
	global_load_lds_dwordx4 v[230:231], off
	v_lshl_add_u64 v[230:231], s[4:5], 0, v[132:133]
	s_mov_b32 m0, s44
	s_nop 0
	global_load_lds_dwordx4 v[230:231], off
	s_waitcnt vmcnt(8)
	s_waitcnt lgkmcnt(0)
	s_barrier
	s_setprio 1
	s_waitcnt lgkmcnt(0)
	v_mfma_f32_16x16x32_bf16 v[124:127], v[148:151], v[180:183], v[124:127]
	v_mfma_f32_16x16x32_bf16 v[124:127], v[152:155], v[184:187], v[124:127]
	v_mfma_f32_16x16x32_bf16 v[116:119], v[152:155], v[192:195], v[116:119]
	v_mfma_f32_16x16x32_bf16 v[116:119], v[148:151], v[188:191], v[116:119]
	v_mfma_f32_16x16x32_bf16 v[104:107], v[148:151], v[196:199], v[104:107]
	v_mfma_f32_16x16x32_bf16 v[104:107], v[152:155], v[200:203], v[104:107]
	v_mfma_f32_16x16x32_bf16 v[88:91], v[152:155], v[212:215], v[88:91]
	v_mfma_f32_16x16x32_bf16 v[88:91], v[148:151], v[208:211], v[88:91]
	v_mfma_f32_16x16x32_bf16 v[80:83], v[156:159], v[208:211], v[80:83]
	v_mfma_f32_16x16x32_bf16 v[80:83], v[160:163], v[212:215], v[80:83]
	v_mfma_f32_16x16x32_bf16 v[96:99], v[160:163], v[200:203], v[96:99]
	v_mfma_f32_16x16x32_bf16 v[96:99], v[156:159], v[196:199], v[96:99]
	v_mfma_f32_16x16x32_bf16 v[112:115], v[156:159], v[188:191], v[112:115]
	v_mfma_f32_16x16x32_bf16 v[112:115], v[160:163], v[192:195], v[112:115]
	v_mfma_f32_16x16x32_bf16 v[120:123], v[160:163], v[184:187], v[120:123]
	v_mfma_f32_16x16x32_bf16 v[120:123], v[156:159], v[180:183], v[120:123]
	s_setprio 0
	s_setprio 1
	v_mfma_f32_16x16x32_bf16 v[108:111], v[164:167], v[180:183], v[108:111]
	v_mfma_f32_16x16x32_bf16 v[108:111], v[168:171], v[184:187], v[108:111]
	v_mfma_f32_16x16x32_bf16 v[92:95], v[168:171], v[192:195], v[92:95]
	v_mfma_f32_16x16x32_bf16 v[92:95], v[164:167], v[188:191], v[92:95]
	v_mfma_f32_16x16x32_bf16 v[76:79], v[164:167], v[196:199], v[76:79]
	v_mfma_f32_16x16x32_bf16 v[76:79], v[168:171], v[200:203], v[76:79]
	v_mfma_f32_16x16x32_bf16 v[68:71], v[168:171], v[212:215], v[68:71]
	v_mfma_f32_16x16x32_bf16 v[68:71], v[164:167], v[208:211], v[68:71]
	v_mfma_f32_16x16x32_bf16 v[64:67], v[172:175], v[208:211], v[64:67]
	v_mfma_f32_16x16x32_bf16 v[64:67], v[176:179], v[212:215], v[64:67]
	v_mfma_f32_16x16x32_bf16 v[72:75], v[176:179], v[200:203], v[72:75]
	v_mfma_f32_16x16x32_bf16 v[72:75], v[172:175], v[196:199], v[72:75]
	v_mfma_f32_16x16x32_bf16 v[84:87], v[172:175], v[188:191], v[84:87]
	v_mfma_f32_16x16x32_bf16 v[84:87], v[176:179], v[192:195], v[84:87]
	v_mfma_f32_16x16x32_bf16 v[100:103], v[176:179], v[184:187], v[100:103]
	v_mfma_f32_16x16x32_bf16 v[100:103], v[172:175], v[180:183], v[100:103]
	s_setprio 0
	s_barrier
; #define PG8_STAGE(bufoff, gbase, voff) do { _Pragma("unroll") for (int _i = 0; _i < 2; ++_i) \
;         __builtin_amdgcn_global_load_lds((const unsigned*)((const char*)(gbase) + (voff)[_i]), (LAS unsigned*)(lds + (bufoff) + ldsw + _i * 8192), 16, 0, 0); } while (0)
; #define PG8_LDA(dst, b, h) do { _Pragma("unroll") for (int m = 0; m < 4; ++m) _Pragma("unroll") for (int k = 0; k < 2; ++k) dst[m][k] = *(const LAS bf16x8*)(lds + PG8_SA(b, h) + aoff + m * 2048 + k * 1024); } while (0)
; #define PG8_MMA(ai, bj, At, Bt) do { __builtin_amdgcn_s_setprio(1); _Pragma("unroll") for (int m = 0; m < 4; ++m) _Pragma("unroll") for (int n = 0; n < 2; ++n) _Pragma("unroll") for (int k = 0; k < 2; ++k) \
;         acc[ai][bj][m][n] = __builtin_amdgcn_mfma_f32_16x16x32_bf16(Bt[n][k], At[m][k], acc[ai][bj][m][n], 0, 0, 0); __builtin_amdgcn_s_setprio(0); } while (0)
; #define PG8_WAIT_V(n) asm volatile("s_waitcnt vmcnt(" #n ")" ::: "memory")
; #define PG8_WAIT_L(n) asm volatile("s_waitcnt lgkmcnt(" #n ")" ::: "memory")
; #define PG8_BAR __builtin_amdgcn_s_barrier()
; #define PG8_SCHED __builtin_amdgcn_sched_barrier(0)
; template <class Epi>
; __device__ __forceinline__ void gemm_phase(LAS unsigned char* lds, const Gemm g, const StaticOrder& S, const Epi& E) {
;     ...
;             PG8_LDA(At, 1, 1); PG8_STAGE(PG8_SB(1, 0), b3, voffB); PG8_STAGE(PG8_SB(1, 1), b3 + hstepB, voffB); PG8_STAGE(PG8_SA(1, 0), a3, voffA);
;             PG8_WAIT_V(8); PG8_WAIT_L(0); PG8_BAR; PG8_MMA(1, 0, At, B0); PG8_MMA(1, 1, At, B1); PG8_BAR; PG8_SCHED;
;         }
	s_add_i32 s4, s66, s40
	v_lshl_add_u64 v[216:217], v[216:217], 0, s[16:17]
	s_mov_b32 m0, s4
	ds_read_b128 v[180:183], v220 offset:49152
	ds_read_b128 v[184:187], v220 offset:50176
	ds_read_b128 v[188:191], v220 offset:51200
	ds_read_b128 v[192:195], v220 offset:52224
	ds_read_b128 v[196:199], v220 offset:53248
	ds_read_b128 v[200:203], v220 offset:54272
	ds_read_b128 v[208:211], v220 offset:55296
	ds_read_b128 v[212:215], v220 offset:56320
	global_load_lds_dwordx4 v[216:217], off
	s_add_i32 m0, s4, 0x2000
	s_add_u32 s4, s34, 0x158080
	v_lshl_add_u64 v[216:217], v[222:223], 0, s[16:17]
	s_addc_u32 s5, s35, 0
	s_add_i32 s34, s67, s40
	global_load_lds_dwordx4 v[216:217], off
	v_lshl_add_u64 v[216:217], s[4:5], 0, v[130:131]
	s_mov_b32 m0, s34
	s_nop 0
	global_load_lds_dwordx4 v[216:217], off
	v_lshl_add_u64 v[216:217], s[4:5], 0, v[134:135]
	s_add_i32 m0, s34, 0x2000
	s_nop 0
	global_load_lds_dwordx4 v[216:217], off
	v_lshl_add_u64 v[216:217], v[224:225], 0, s[16:17]
	s_mov_b32 m0, s47
	s_nop 0
	global_load_lds_dwordx4 v[216:217], off
	v_lshl_add_u64 v[216:217], v[226:227], 0, s[16:17]
	s_mov_b32 m0, s48
	s_nop 0
	global_load_lds_dwordx4 v[216:217], off
	s_waitcnt vmcnt(8)
	s_waitcnt lgkmcnt(0)
	s_barrier
	s_setprio 1
	s_waitcnt lgkmcnt(0)
	v_mfma_f32_16x16x32_bf16 v[60:63], v[148:151], v[180:183], v[60:63]
	v_mfma_f32_16x16x32_bf16 v[60:63], v[152:155], v[184:187], v[60:63]
	v_mfma_f32_16x16x32_bf16 v[52:55], v[152:155], v[192:195], v[52:55]
	v_mfma_f32_16x16x32_bf16 v[52:55], v[148:151], v[188:191], v[52:55]
	v_mfma_f32_16x16x32_bf16 v[40:43], v[148:151], v[196:199], v[40:43]
	v_mfma_f32_16x16x32_bf16 v[40:43], v[152:155], v[200:203], v[40:43]
	v_mfma_f32_16x16x32_bf16 v[24:27], v[152:155], v[212:215], v[24:27]
	v_mfma_f32_16x16x32_bf16 v[24:27], v[148:151], v[208:211], v[24:27]
	v_mfma_f32_16x16x32_bf16 v[16:19], v[156:159], v[208:211], v[16:19]
	v_mfma_f32_16x16x32_bf16 v[16:19], v[160:163], v[212:215], v[16:19]
	v_mfma_f32_16x16x32_bf16 v[32:35], v[160:163], v[200:203], v[32:35]
	v_mfma_f32_16x16x32_bf16 v[32:35], v[156:159], v[196:199], v[32:35]
	v_mfma_f32_16x16x32_bf16 v[48:51], v[156:159], v[188:191], v[48:51]
	v_mfma_f32_16x16x32_bf16 v[48:51], v[160:163], v[192:195], v[48:51]
	v_mfma_f32_16x16x32_bf16 v[56:59], v[160:163], v[184:187], v[56:59]
	v_mfma_f32_16x16x32_bf16 v[56:59], v[156:159], v[180:183], v[56:59]
	s_setprio 0
	s_setprio 1
	v_mfma_f32_16x16x32_bf16 v[44:47], v[164:167], v[180:183], v[44:47]
	v_mfma_f32_16x16x32_bf16 v[44:47], v[168:171], v[184:187], v[44:47]
	v_mfma_f32_16x16x32_bf16 v[28:31], v[168:171], v[192:195], v[28:31]
	v_mfma_f32_16x16x32_bf16 v[28:31], v[164:167], v[188:191], v[28:31]
	v_mfma_f32_16x16x32_bf16 v[12:15], v[164:167], v[196:199], v[12:15]
	v_mfma_f32_16x16x32_bf16 v[12:15], v[168:171], v[200:203], v[12:15]
	v_mfma_f32_16x16x32_bf16 v[4:7], v[168:171], v[212:215], v[4:7]
	v_mfma_f32_16x16x32_bf16 v[4:7], v[164:167], v[208:211], v[4:7]
	v_mfma_f32_16x16x32_bf16 v[0:3], v[172:175], v[208:211], v[0:3]
	v_mfma_f32_16x16x32_bf16 v[0:3], v[176:179], v[212:215], v[0:3]
	v_mfma_f32_16x16x32_bf16 v[8:11], v[176:179], v[200:203], v[8:11]
	v_mfma_f32_16x16x32_bf16 v[8:11], v[172:175], v[196:199], v[8:11]
	v_mfma_f32_16x16x32_bf16 v[20:23], v[172:175], v[188:191], v[20:23]
	v_mfma_f32_16x16x32_bf16 v[20:23], v[176:179], v[192:195], v[20:23]
	v_mfma_f32_16x16x32_bf16 v[36:39], v[176:179], v[184:187], v[36:39]
	v_mfma_f32_16x16x32_bf16 v[36:39], v[172:175], v[180:183], v[36:39]
	s_setprio 0
	s_barrier
	s_add_u32 s1, s1, 0x100
	s_addc_u32 s64, s64, 0
	s_cmp_ge_i32 s65, s46
	s_mov_b64 s[4:5], s[30:31]
	s_mov_b32 s34, s65
	s_cbranch_scc0 .LBB0_445
	v_pk_mul_f32 v[164:165], v[126:127], 0.5 op_sel_hi:[1,0]
	v_pk_mul_f32 v[200:201], v[124:125], 0.5 op_sel_hi:[1,0]
	v_pk_mul_f32 v[202:203], v[122:123], 0.5 op_sel_hi:[1,0]
	v_pk_mul_f32 v[208:209], v[120:121], 0.5 op_sel_hi:[1,0]
	v_pk_mul_f32 v[210:211], v[110:111], 0.5 op_sel_hi:[1,0]
	v_pk_mul_f32 v[212:213], v[108:109], 0.5 op_sel_hi:[1,0]
	v_pk_mul_f32 v[214:215], v[102:103], 0.5 op_sel_hi:[1,0]
	v_pk_mul_f32 v[216:217], v[100:101], 0.5 op_sel_hi:[1,0]
	v_pk_mul_f32 v[188:189], v[118:119], 0.5 op_sel_hi:[1,0]
	v_pk_mul_f32 v[186:187], v[116:117], 0.5 op_sel_hi:[1,0]
	v_pk_mul_f32 v[184:185], v[114:115], 0.5 op_sel_hi:[1,0]
	v_pk_mul_f32 v[182:183], v[112:113], 0.5 op_sel_hi:[1,0]
	v_pk_mul_f32 v[196:197], v[94:95], 0.5 op_sel_hi:[1,0]
	v_pk_mul_f32 v[194:195], v[92:93], 0.5 op_sel_hi:[1,0]
	v_pk_mul_f32 v[192:193], v[86:87], 0.5 op_sel_hi:[1,0]
	v_pk_mul_f32 v[190:191], v[84:85], 0.5 op_sel_hi:[1,0]
	v_pk_mul_f32 v[166:167], v[106:107], 0.5 op_sel_hi:[1,0]
	v_pk_mul_f32 v[168:169], v[104:105], 0.5 op_sel_hi:[1,0]
	v_pk_mul_f32 v[170:171], v[98:99], 0.5 op_sel_hi:[1,0]
	v_pk_mul_f32 v[172:173], v[96:97], 0.5 op_sel_hi:[1,0]
	v_pk_mul_f32 v[174:175], v[78:79], 0.5 op_sel_hi:[1,0]
	v_pk_mul_f32 v[176:177], v[76:77], 0.5 op_sel_hi:[1,0]
	v_pk_mul_f32 v[178:179], v[74:75], 0.5 op_sel_hi:[1,0]
	v_pk_mul_f32 v[180:181], v[72:73], 0.5 op_sel_hi:[1,0]
	v_pk_mul_f32 v[154:155], v[90:91], 0.5 op_sel_hi:[1,0]
	v_pk_mul_f32 v[152:153], v[88:89], 0.5 op_sel_hi:[1,0]
	v_pk_mul_f32 v[150:151], v[82:83], 0.5 op_sel_hi:[1,0]
	v_pk_mul_f32 v[148:149], v[80:81], 0.5 op_sel_hi:[1,0]
	v_pk_mul_f32 v[162:163], v[70:71], 0.5 op_sel_hi:[1,0]
	v_pk_mul_f32 v[160:161], v[68:69], 0.5 op_sel_hi:[1,0]
	v_pk_mul_f32 v[158:159], v[66:67], 0.5 op_sel_hi:[1,0]
	v_pk_mul_f32 v[156:157], v[64:65], 0.5 op_sel_hi:[1,0]
	v_pk_mul_f32 v[112:113], v[62:63], 0.5 op_sel_hi:[1,0]
	v_pk_mul_f32 v[114:115], v[60:61], 0.5 op_sel_hi:[1,0]
	v_pk_mul_f32 v[116:117], v[58:59], 0.5 op_sel_hi:[1,0]
	v_pk_mul_f32 v[118:119], v[56:57], 0.5 op_sel_hi:[1,0]
	v_pk_mul_f32 v[120:121], v[46:47], 0.5 op_sel_hi:[1,0]
	v_pk_mul_f32 v[122:123], v[44:45], 0.5 op_sel_hi:[1,0]
	v_pk_mul_f32 v[124:125], v[38:39], 0.5 op_sel_hi:[1,0]
	v_pk_mul_f32 v[126:127], v[36:37], 0.5 op_sel_hi:[1,0]
	v_pk_mul_f32 v[102:103], v[54:55], 0.5 op_sel_hi:[1,0]
	v_pk_mul_f32 v[100:101], v[52:53], 0.5 op_sel_hi:[1,0]
	v_pk_mul_f32 v[98:99], v[50:51], 0.5 op_sel_hi:[1,0]
	v_pk_mul_f32 v[96:97], v[48:49], 0.5 op_sel_hi:[1,0]
	v_pk_mul_f32 v[110:111], v[30:31], 0.5 op_sel_hi:[1,0]
	v_pk_mul_f32 v[108:109], v[28:29], 0.5 op_sel_hi:[1,0]
	v_pk_mul_f32 v[106:107], v[22:23], 0.5 op_sel_hi:[1,0]
	v_pk_mul_f32 v[104:105], v[20:21], 0.5 op_sel_hi:[1,0]
	v_pk_mul_f32 v[86:87], v[42:43], 0.5 op_sel_hi:[1,0]
	v_pk_mul_f32 v[84:85], v[40:41], 0.5 op_sel_hi:[1,0]
	v_pk_mul_f32 v[82:83], v[34:35], 0.5 op_sel_hi:[1,0]
	v_pk_mul_f32 v[80:81], v[32:33], 0.5 op_sel_hi:[1,0]
	v_pk_mul_f32 v[94:95], v[14:15], 0.5 op_sel_hi:[1,0]
	v_pk_mul_f32 v[92:93], v[12:13], 0.5 op_sel_hi:[1,0]
	v_pk_mul_f32 v[90:91], v[10:11], 0.5 op_sel_hi:[1,0]
	v_pk_mul_f32 v[88:89], v[8:9], 0.5 op_sel_hi:[1,0]
	v_pk_mul_f32 v[70:71], v[26:27], 0.5 op_sel_hi:[1,0]
	v_pk_mul_f32 v[68:69], v[24:25], 0.5 op_sel_hi:[1,0]
	v_pk_mul_f32 v[66:67], v[18:19], 0.5 op_sel_hi:[1,0]
	v_pk_mul_f32 v[64:65], v[16:17], 0.5 op_sel_hi:[1,0]
	v_pk_mul_f32 v[78:79], v[6:7], 0.5 op_sel_hi:[1,0]
	v_pk_mul_f32 v[76:77], v[4:5], 0.5 op_sel_hi:[1,0]
	v_pk_mul_f32 v[74:75], v[2:3], 0.5 op_sel_hi:[1,0]
	v_pk_mul_f32 v[72:73], v[0:1], 0.5 op_sel_hi:[1,0]

; #define PG8_STAGE(bufoff, gbase, voff) do { _Pragma("unroll") for (int _i = 0; _i < 2; ++_i) \
;         __builtin_amdgcn_global_load_lds((const unsigned*)((const char*)(gbase) + (voff)[_i]), (LAS unsigned*)(lds + (bufoff) + ldsw + _i * 8192), 16, 0, 0); } while (0)
; #define PG8_LDA(dst, b, h) do { _Pragma("unroll") for (int m = 0; m < 4; ++m) _Pragma("unroll") for (int k = 0; k < 2; ++k) dst[m][k] = *(const LAS bf16x8*)(lds + PG8_SA(b, h) + aoff + m * 2048 + k * 1024); } while (0)
; #define PG8_LDB(dst, b, h) do { _Pragma("unroll") for (int n = 0; n < 2; ++n) _Pragma("unroll") for (int k = 0; k < 2; ++k) dst[n][k] = *(const LAS bf16x8*)(lds + PG8_SB(b, h) + boff + n * 2048 + k * 1024); } while (0)
; #define PG8_MMA(ai, bj, At, Bt) do { __builtin_amdgcn_s_setprio(1); _Pragma("unroll") for (int m = 0; m < 4; ++m) _Pragma("unroll") for (int n = 0; n < 2; ++n) _Pragma("unroll") for (int k = 0; k < 2; ++k) \
;         acc[ai][bj][m][n] = __builtin_amdgcn_mfma_f32_16x16x32_bf16(Bt[n][k], At[m][k], acc[ai][bj][m][n], 0, 0, 0); __builtin_amdgcn_s_setprio(0); } while (0)
; #define PG8_WAIT_V(n) asm volatile("s_waitcnt vmcnt(" #n ")" ::: "memory")
; #define PG8_WAIT_L(n) asm volatile("s_waitcnt lgkmcnt(" #n ")" ::: "memory")
; #define PG8_BAR __builtin_amdgcn_s_barrier()
; #define PG8_SCHED __builtin_amdgcn_sched_barrier(0)
; template <class Epi>
; __device__ __forceinline__ void gemm_phase(LAS unsigned char* lds, const Gemm g, const StaticOrder& S, const Epi& E) {
;     ...
;             const char* a2 = last ? nA : cA + (size_t)(t + 2) * kstep; const char* b2 = last ? nB : cB + (size_t)(t + 2) * kstep;
;             const char* a3 = a2 + kstep; const char* b3 = b2 + kstep;
;             PG8_LDB(B0, 0, 0); PG8_LDB(B1, 0, 1); PG8_SCHED; PG8_LDA(At, 0, 0); PG8_STAGE(PG8_SA(1, 1), a1 + hstepA, voffA);
;             PG8_WAIT_V(8); PG8_WAIT_L(0); PG8_BAR; PG8_MMA(0, 0, At, B0); PG8_MMA(0, 1, At, B1); PG8_BAR; PG8_SCHED;
;             PG8_LDA(At, 0, 1); PG8_STAGE(PG8_SB(0, 0), b2, voffB); PG8_STAGE(PG8_SB(0, 1), b2 + hstepB, voffB); PG8_STAGE(PG8_SA(0, 0), a2, voffA);
.LBB0_541:
	ds_read_b128 v[148:151], v155
	ds_read_b128 v[160:163], v155 offset:1024
	ds_read_b128 v[164:167], v155 offset:2048
	ds_read_b128 v[168:171], v155 offset:3072
	ds_read_b128 v[172:175], v156
	ds_read_b128 v[176:179], v156 offset:1024
	ds_read_b128 v[180:183], v156 offset:2048
	ds_read_b128 v[184:187], v156 offset:3072
	s_add_i32 s35, s26, 2
	s_add_u32 s27, s8, 0xfff80080
	s_addc_u32 s30, s9, -1
	s_cmp_eq_u32 s49, s26
	s_cselect_b32 s26, s21, s33
	s_cselect_b32 s31, s1, s30
	s_cselect_b32 s30, s5, s27
	s_cselect_b32 s27, s19, s34
	v_lshl_add_u64 v[224:225], s[8:9], 0, v[140:141]
	s_add_i32 m0, s39, 0xc000
	ds_read_b128 v[188:191], v157
	ds_read_b128 v[192:195], v157 offset:1024
	ds_read_b128 v[196:199], v157 offset:2048
	ds_read_b128 v[200:203], v157 offset:3072
	ds_read_b128 v[208:211], v157 offset:4096
	ds_read_b128 v[212:215], v157 offset:5120
	ds_read_b128 v[216:219], v157 offset:6144
	ds_read_b128 v[220:223], v157 offset:7168
	global_load_lds_dwordx4 v[224:225], off
	v_lshl_add_u64 v[224:225], s[8:9], 0, v[142:143]
	s_add_i32 m0, s39, 0xe000
	s_nop 0
	global_load_lds_dwordx4 v[224:225], off
	s_waitcnt vmcnt(8)
	s_waitcnt lgkmcnt(0)
	s_barrier
	s_setprio 1
	s_waitcnt lgkmcnt(0)
	v_mfma_f32_16x16x32_bf16 v[120:123], v[148:151], v[188:191], v[120:123]
	v_mfma_f32_16x16x32_bf16 v[120:123], v[160:163], v[192:195], v[120:123]
	v_mfma_f32_16x16x32_bf16 v[108:111], v[160:163], v[200:203], v[108:111]
	v_mfma_f32_16x16x32_bf16 v[108:111], v[148:151], v[196:199], v[108:111]
	v_mfma_f32_16x16x32_bf16 v[92:95], v[148:151], v[208:211], v[92:95]
	v_mfma_f32_16x16x32_bf16 v[92:95], v[160:163], v[212:215], v[92:95]
	v_mfma_f32_16x16x32_bf16 v[76:79], v[160:163], v[220:223], v[76:79]
	v_mfma_f32_16x16x32_bf16 v[76:79], v[148:151], v[216:219], v[76:79]
	v_mfma_f32_16x16x32_bf16 v[72:75], v[164:167], v[216:219], v[72:75]
	v_mfma_f32_16x16x32_bf16 v[72:75], v[168:171], v[220:223], v[72:75]
	v_mfma_f32_16x16x32_bf16 v[88:91], v[168:171], v[212:215], v[88:91]
	v_mfma_f32_16x16x32_bf16 v[88:91], v[164:167], v[208:211], v[88:91]
	v_mfma_f32_16x16x32_bf16 v[104:107], v[164:167], v[196:199], v[104:107]
	v_mfma_f32_16x16x32_bf16 v[104:107], v[168:171], v[200:203], v[104:107]
	v_mfma_f32_16x16x32_bf16 v[124:127], v[168:171], v[192:195], v[124:127]
	v_mfma_f32_16x16x32_bf16 v[124:127], v[164:167], v[188:191], v[124:127]
	s_setprio 0
	s_setprio 1
	v_mfma_f32_16x16x32_bf16 v[116:119], v[172:175], v[188:191], v[116:119]
	v_mfma_f32_16x16x32_bf16 v[116:119], v[176:179], v[192:195], v[116:119]
	v_mfma_f32_16x16x32_bf16 v[100:103], v[176:179], v[200:203], v[100:103]
	v_mfma_f32_16x16x32_bf16 v[100:103], v[172:175], v[196:199], v[100:103]
	v_mfma_f32_16x16x32_bf16 v[84:87], v[172:175], v[208:211], v[84:87]
	v_mfma_f32_16x16x32_bf16 v[84:87], v[176:179], v[212:215], v[84:87]
	v_mfma_f32_16x16x32_bf16 v[68:71], v[176:179], v[220:223], v[68:71]
	v_mfma_f32_16x16x32_bf16 v[68:71], v[172:175], v[216:219], v[68:71]
	v_mfma_f32_16x16x32_bf16 v[64:67], v[180:183], v[216:219], v[64:67]
	v_mfma_f32_16x16x32_bf16 v[64:67], v[184:187], v[220:223], v[64:67]
	v_mfma_f32_16x16x32_bf16 v[80:83], v[184:187], v[212:215], v[80:83]
	v_mfma_f32_16x16x32_bf16 v[80:83], v[180:183], v[208:211], v[80:83]
	v_mfma_f32_16x16x32_bf16 v[96:99], v[180:183], v[196:199], v[96:99]
	v_mfma_f32_16x16x32_bf16 v[96:99], v[184:187], v[200:203], v[96:99]
	v_mfma_f32_16x16x32_bf16 v[112:115], v[184:187], v[192:195], v[112:115]
	v_mfma_f32_16x16x32_bf16 v[112:115], v[180:183], v[188:191], v[112:115]
	s_setprio 0
	s_barrier
	s_add_i32 s58, s54, s38
	v_lshl_add_u64 v[224:225], s[26:27], 0, v[130:131]
	s_mov_b32 m0, s58
	ds_read_b128 v[188:191], v157 offset:16384
	ds_read_b128 v[192:195], v157 offset:17408
	ds_read_b128 v[196:199], v157 offset:18432
	ds_read_b128 v[200:203], v157 offset:19456
	ds_read_b128 v[208:211], v157 offset:20480
	ds_read_b128 v[212:215], v157 offset:21504
	ds_read_b128 v[216:219], v157 offset:22528
	ds_read_b128 v[220:223], v157 offset:23552
	global_load_lds_dwordx4 v[224:225], off
	s_add_i32 m0, s58, 0x2000
	s_add_u32 s58, s26, 0x80000
	v_lshl_add_u64 v[226:227], s[26:27], 0, v[134:135]
	s_addc_u32 s59, s27, 0
	s_add_i32 s60, s55, s38
	global_load_lds_dwordx4 v[226:227], off
	v_lshl_add_u64 v[230:231], s[58:59], 0, v[130:131]
	s_mov_b32 m0, s60
	v_lshl_add_u64 v[232:233], s[30:31], 0, v[132:133]
	global_load_lds_dwordx4 v[230:231], off
	v_lshl_add_u64 v[230:231], s[58:59], 0, v[134:135]
	s_add_i32 m0, s60, 0x2000
	s_nop 0
	global_load_lds_dwordx4 v[230:231], off
	v_lshl_add_u64 v[230:231], s[30:31], 0, v[128:129]
	s_mov_b32 m0, s39
	s_nop 0
	global_load_lds_dwordx4 v[230:231], off
	s_mov_b32 m0, s40
	s_nop 0
	global_load_lds_dwordx4 v[232:233], off
	s_waitcnt vmcnt(8)
	s_waitcnt lgkmcnt(0)
	s_barrier
; #define PG8_STAGE(bufoff, gbase, voff) do { _Pragma("unroll") for (int _i = 0; _i < 2; ++_i) \
;         __builtin_amdgcn_global_load_lds((const unsigned*)((const char*)(gbase) + (voff)[_i]), (LAS unsigned*)(lds + (bufoff) + ldsw + _i * 8192), 16, 0, 0); } while (0)
; #define PG8_LDA(dst, b, h) do { _Pragma("unroll") for (int m = 0; m < 4; ++m) _Pragma("unroll") for (int k = 0; k < 2; ++k) dst[m][k] = *(const LAS bf16x8*)(lds + PG8_SA(b, h) + aoff + m * 2048 + k * 1024); } while (0)
; #define PG8_LDB(dst, b, h) do { _Pragma("unroll") for (int n = 0; n < 2; ++n) _Pragma("unroll") for (int k = 0; k < 2; ++k) dst[n][k] = *(const LAS bf16x8*)(lds + PG8_SB(b, h) + boff + n * 2048 + k * 1024); } while (0)
; #define PG8_MMA(ai, bj, At, Bt) do { __builtin_amdgcn_s_setprio(1); _Pragma("unroll") for (int m = 0; m < 4; ++m) _Pragma("unroll") for (int n = 0; n < 2; ++n) _Pragma("unroll") for (int k = 0; k < 2; ++k) \
;         acc[ai][bj][m][n] = __builtin_amdgcn_mfma_f32_16x16x32_bf16(Bt[n][k], At[m][k], acc[ai][bj][m][n], 0, 0, 0); __builtin_amdgcn_s_setprio(0); } while (0)
; #define PG8_WAIT_V(n) asm volatile("s_waitcnt vmcnt(" #n ")" ::: "memory")
; #define PG8_WAIT_L(n) asm volatile("s_waitcnt lgkmcnt(" #n ")" ::: "memory")
; #define PG8_BAR __builtin_amdgcn_s_barrier()
; #define PG8_SCHED __builtin_amdgcn_sched_barrier(0)
; template <class Epi>
; __device__ __forceinline__ void gemm_phase(LAS unsigned char* lds, const Gemm g, const StaticOrder& S, const Epi& E) {
;     ...
;             PG8_WAIT_V(8); PG8_WAIT_L(0); PG8_BAR; PG8_MMA(1, 0, At, B0); PG8_MMA(1, 1, At, B1); PG8_BAR; PG8_SCHED;
;             PG8_LDB(B0, 1, 0); PG8_LDB(B1, 1, 1); PG8_SCHED; PG8_LDA(At, 1, 0); PG8_STAGE(PG8_SA(0, 1), a2 + hstepA, voffA);
;             PG8_WAIT_V(8); PG8_WAIT_L(0); PG8_BAR; PG8_MMA(0, 0, At, B0); PG8_MMA(0, 1, At, B1); PG8_BAR; PG8_SCHED;
;             PG8_LDA(At, 1, 1); PG8_STAGE(PG8_SB(1, 0), b3, voffB); PG8_STAGE(PG8_SB(1, 1), b3 + hstepB, voffB); PG8_STAGE(PG8_SA(1, 0), a3, voffA);
	s_setprio 1
	s_waitcnt lgkmcnt(0)
	v_mfma_f32_16x16x32_bf16 v[60:63], v[148:151], v[188:191], v[60:63]
	v_mfma_f32_16x16x32_bf16 v[60:63], v[160:163], v[192:195], v[60:63]
	v_mfma_f32_16x16x32_bf16 v[44:47], v[160:163], v[200:203], v[44:47]
	v_mfma_f32_16x16x32_bf16 v[44:47], v[148:151], v[196:199], v[44:47]
	v_mfma_f32_16x16x32_bf16 v[28:31], v[148:151], v[208:211], v[28:31]
	v_mfma_f32_16x16x32_bf16 v[28:31], v[160:163], v[212:215], v[28:31]
	v_mfma_f32_16x16x32_bf16 v[12:15], v[160:163], v[220:223], v[12:15]
	v_mfma_f32_16x16x32_bf16 v[12:15], v[148:151], v[216:219], v[12:15]
	v_mfma_f32_16x16x32_bf16 v[8:11], v[164:167], v[216:219], v[8:11]
	v_mfma_f32_16x16x32_bf16 v[8:11], v[168:171], v[220:223], v[8:11]
	v_mfma_f32_16x16x32_bf16 v[24:27], v[168:171], v[212:215], v[24:27]
	v_mfma_f32_16x16x32_bf16 v[24:27], v[164:167], v[208:211], v[24:27]
	v_mfma_f32_16x16x32_bf16 v[40:43], v[164:167], v[196:199], v[40:43]
	v_mfma_f32_16x16x32_bf16 v[40:43], v[168:171], v[200:203], v[40:43]
	v_mfma_f32_16x16x32_bf16 v[56:59], v[168:171], v[192:195], v[56:59]
	v_mfma_f32_16x16x32_bf16 v[56:59], v[164:167], v[188:191], v[56:59]
	s_setprio 0
	s_setprio 1
	v_mfma_f32_16x16x32_bf16 v[52:55], v[172:175], v[188:191], v[52:55]
	v_mfma_f32_16x16x32_bf16 v[52:55], v[176:179], v[192:195], v[52:55]
	v_mfma_f32_16x16x32_bf16 v[36:39], v[176:179], v[200:203], v[36:39]
	v_mfma_f32_16x16x32_bf16 v[36:39], v[172:175], v[196:199], v[36:39]
	v_mfma_f32_16x16x32_bf16 v[20:23], v[172:175], v[208:211], v[20:23]
	v_mfma_f32_16x16x32_bf16 v[20:23], v[176:179], v[212:215], v[20:23]
	v_mfma_f32_16x16x32_bf16 v[4:7], v[176:179], v[220:223], v[4:7]
	v_mfma_f32_16x16x32_bf16 v[4:7], v[172:175], v[216:219], v[4:7]
	v_mfma_f32_16x16x32_bf16 v[0:3], v[180:183], v[216:219], v[0:3]
	v_mfma_f32_16x16x32_bf16 v[0:3], v[184:187], v[220:223], v[0:3]
	v_mfma_f32_16x16x32_bf16 v[16:19], v[184:187], v[212:215], v[16:19]
	v_mfma_f32_16x16x32_bf16 v[16:19], v[180:183], v[208:211], v[16:19]
	v_mfma_f32_16x16x32_bf16 v[32:35], v[180:183], v[196:199], v[32:35]
	v_mfma_f32_16x16x32_bf16 v[32:35], v[184:187], v[200:203], v[32:35]
	v_mfma_f32_16x16x32_bf16 v[48:51], v[184:187], v[192:195], v[48:51]
	v_mfma_f32_16x16x32_bf16 v[48:51], v[180:183], v[188:191], v[48:51]
	s_setprio 0
	s_barrier
	s_add_i32 s58, 0, 0x18000
	v_add_u32_e32 v136, s58, v154
	s_add_i32 s59, 0, 0x1c000
	ds_read_b128 v[148:151], v136
	ds_read_b128 v[160:163], v136 offset:1024
	ds_read_b128 v[164:167], v136 offset:2048
	ds_read_b128 v[168:171], v136 offset:3072
	v_add_u32_e32 v136, s59, v154
	ds_read_b128 v[172:175], v136
	ds_read_b128 v[176:179], v136 offset:1024
	ds_read_b128 v[180:183], v136 offset:2048
	ds_read_b128 v[184:187], v136 offset:3072
	s_add_u32 s30, s30, 0x80000
	s_addc_u32 s31, s31, 0
	s_mov_b32 m0, s41
	v_lshl_add_u64 v[234:235], s[30:31], 0, v[128:129]
	ds_read_b128 v[188:191], v157 offset:32768
	ds_read_b128 v[192:195], v157 offset:33792
	ds_read_b128 v[196:199], v157 offset:34816
	ds_read_b128 v[200:203], v157 offset:35840
	ds_read_b128 v[208:211], v157 offset:36864
	ds_read_b128 v[212:215], v157 offset:37888
	ds_read_b128 v[216:219], v157 offset:38912
	ds_read_b128 v[220:223], v157 offset:39936
	global_load_lds_dwordx4 v[234:235], off
	v_lshl_add_u64 v[234:235], s[30:31], 0, v[132:133]
	s_mov_b32 m0, s42
	s_nop 0
	global_load_lds_dwordx4 v[234:235], off
	s_waitcnt vmcnt(8)
	s_waitcnt lgkmcnt(0)
	s_barrier
	s_setprio 1
	s_waitcnt lgkmcnt(0)
	v_mfma_f32_16x16x32_bf16 v[120:123], v[148:151], v[188:191], v[120:123]
	v_mfma_f32_16x16x32_bf16 v[120:123], v[160:163], v[192:195], v[120:123]
	v_mfma_f32_16x16x32_bf16 v[108:111], v[160:163], v[200:203], v[108:111]
	v_mfma_f32_16x16x32_bf16 v[108:111], v[148:151], v[196:199], v[108:111]
	v_mfma_f32_16x16x32_bf16 v[92:95], v[148:151], v[208:211], v[92:95]
	v_mfma_f32_16x16x32_bf16 v[92:95], v[160:163], v[212:215], v[92:95]
	v_mfma_f32_16x16x32_bf16 v[76:79], v[160:163], v[220:223], v[76:79]
	v_mfma_f32_16x16x32_bf16 v[76:79], v[148:151], v[216:219], v[76:79]
	v_mfma_f32_16x16x32_bf16 v[72:75], v[164:167], v[216:219], v[72:75]
	v_mfma_f32_16x16x32_bf16 v[72:75], v[168:171], v[220:223], v[72:75]
	v_mfma_f32_16x16x32_bf16 v[88:91], v[168:171], v[212:215], v[88:91]
	v_mfma_f32_16x16x32_bf16 v[88:91], v[164:167], v[208:211], v[88:91]
	v_mfma_f32_16x16x32_bf16 v[104:107], v[164:167], v[196:199], v[104:107]
	v_mfma_f32_16x16x32_bf16 v[104:107], v[168:171], v[200:203], v[104:107]
	v_mfma_f32_16x16x32_bf16 v[124:127], v[168:171], v[192:195], v[124:127]
	v_mfma_f32_16x16x32_bf16 v[124:127], v[164:167], v[188:191], v[124:127]
	s_setprio 0
	s_setprio 1
	v_mfma_f32_16x16x32_bf16 v[116:119], v[172:175], v[188:191], v[116:119]
	v_mfma_f32_16x16x32_bf16 v[116:119], v[176:179], v[192:195], v[116:119]
	v_mfma_f32_16x16x32_bf16 v[100:103], v[176:179], v[200:203], v[100:103]
	v_mfma_f32_16x16x32_bf16 v[100:103], v[172:175], v[196:199], v[100:103]
	v_mfma_f32_16x16x32_bf16 v[84:87], v[172:175], v[208:211], v[84:87]
	v_mfma_f32_16x16x32_bf16 v[84:87], v[176:179], v[212:215], v[84:87]
	v_mfma_f32_16x16x32_bf16 v[68:71], v[176:179], v[220:223], v[68:71]
	v_mfma_f32_16x16x32_bf16 v[68:71], v[172:175], v[216:219], v[68:71]
	v_mfma_f32_16x16x32_bf16 v[64:67], v[180:183], v[216:219], v[64:67]
	v_mfma_f32_16x16x32_bf16 v[64:67], v[184:187], v[220:223], v[64:67]
	v_mfma_f32_16x16x32_bf16 v[80:83], v[184:187], v[212:215], v[80:83]
	v_mfma_f32_16x16x32_bf16 v[80:83], v[180:183], v[208:211], v[80:83]
	v_mfma_f32_16x16x32_bf16 v[96:99], v[180:183], v[196:199], v[96:99]
	v_mfma_f32_16x16x32_bf16 v[96:99], v[184:187], v[200:203], v[96:99]
	v_mfma_f32_16x16x32_bf16 v[112:115], v[184:187], v[192:195], v[112:115]
	v_mfma_f32_16x16x32_bf16 v[112:115], v[180:183], v[188:191], v[112:115]
	s_setprio 0
	s_barrier
; #define PG8_STAGE(bufoff, gbase, voff) do { _Pragma("unroll") for (int _i = 0; _i < 2; ++_i) \
;         __builtin_amdgcn_global_load_lds((const unsigned*)((const char*)(gbase) + (voff)[_i]), (LAS unsigned*)(lds + (bufoff) + ldsw + _i * 8192), 16, 0, 0); } while (0)
; #define PG8_LDA(dst, b, h) do { _Pragma("unroll") for (int m = 0; m < 4; ++m) _Pragma("unroll") for (int k = 0; k < 2; ++k) dst[m][k] = *(const LAS bf16x8*)(lds + PG8_SA(b, h) + aoff + m * 2048 + k * 1024); } while (0)
; #define PG8_MMA(ai, bj, At, Bt) do { __builtin_amdgcn_s_setprio(1); _Pragma("unroll") for (int m = 0; m < 4; ++m) _Pragma("unroll") for (int n = 0; n < 2; ++n) _Pragma("unroll") for (int k = 0; k < 2; ++k) \
;         acc[ai][bj][m][n] = __builtin_amdgcn_mfma_f32_16x16x32_bf16(Bt[n][k], At[m][k], acc[ai][bj][m][n], 0, 0, 0); __builtin_amdgcn_s_setprio(0); } while (0)
; #define PG8_WAIT_V(n) asm volatile("s_waitcnt vmcnt(" #n ")" ::: "memory")
; #define PG8_WAIT_L(n) asm volatile("s_waitcnt lgkmcnt(" #n ")" ::: "memory")
; #define PG8_BAR __builtin_amdgcn_s_barrier()
; #define PG8_SCHED __builtin_amdgcn_sched_barrier(0)
; template <class Epi>
; __device__ __forceinline__ void gemm_phase(LAS unsigned char* lds, const Gemm g, const StaticOrder& S, const Epi& E) {
;     ...
;             PG8_LDA(At, 1, 1); PG8_STAGE(PG8_SB(1, 0), b3, voffB); PG8_STAGE(PG8_SB(1, 1), b3 + hstepB, voffB); PG8_STAGE(PG8_SA(1, 0), a3, voffA);
;             PG8_WAIT_V(8); PG8_WAIT_L(0); PG8_BAR; PG8_MMA(1, 0, At, B0); PG8_MMA(1, 1, At, B1); PG8_BAR; PG8_SCHED;
;         }
	s_add_i32 s30, s58, s38
	v_lshl_add_u64 v[224:225], v[224:225], 0, s[12:13]
	s_mov_b32 m0, s30
	ds_read_b128 v[188:191], v157 offset:49152
	ds_read_b128 v[192:195], v157 offset:50176
	ds_read_b128 v[196:199], v157 offset:51200
	ds_read_b128 v[200:203], v157 offset:52224
	ds_read_b128 v[208:211], v157 offset:53248
	ds_read_b128 v[212:215], v157 offset:54272
	ds_read_b128 v[216:219], v157 offset:55296
	ds_read_b128 v[220:223], v157 offset:56320
	global_load_lds_dwordx4 v[224:225], off
	s_add_i32 m0, s30, 0x2000
	s_add_u32 s26, s26, 0x80080
	v_lshl_add_u64 v[224:225], v[226:227], 0, s[12:13]
	s_addc_u32 s27, s27, 0
	s_add_i32 s30, s59, s38
	global_load_lds_dwordx4 v[224:225], off
	v_lshl_add_u64 v[224:225], s[26:27], 0, v[130:131]
	s_mov_b32 m0, s30
	s_nop 0
	global_load_lds_dwordx4 v[224:225], off
	v_lshl_add_u64 v[224:225], s[26:27], 0, v[134:135]
	s_add_i32 m0, s30, 0x2000
	s_nop 0
	global_load_lds_dwordx4 v[224:225], off
	v_lshl_add_u64 v[224:225], v[230:231], 0, s[12:13]
	s_mov_b32 m0, s47
	s_nop 0
	global_load_lds_dwordx4 v[224:225], off
	v_lshl_add_u64 v[224:225], v[232:233], 0, s[12:13]
	s_mov_b32 m0, s48
	s_nop 0
	global_load_lds_dwordx4 v[224:225], off
	s_waitcnt vmcnt(8)
	s_waitcnt lgkmcnt(0)
	s_barrier
	s_setprio 1
	s_waitcnt lgkmcnt(0)
	v_mfma_f32_16x16x32_bf16 v[60:63], v[148:151], v[188:191], v[60:63]
	v_mfma_f32_16x16x32_bf16 v[60:63], v[160:163], v[192:195], v[60:63]
	v_mfma_f32_16x16x32_bf16 v[44:47], v[160:163], v[200:203], v[44:47]
	v_mfma_f32_16x16x32_bf16 v[44:47], v[148:151], v[196:199], v[44:47]
	v_mfma_f32_16x16x32_bf16 v[28:31], v[148:151], v[208:211], v[28:31]
	v_mfma_f32_16x16x32_bf16 v[28:31], v[160:163], v[212:215], v[28:31]
	v_mfma_f32_16x16x32_bf16 v[12:15], v[160:163], v[220:223], v[12:15]
	v_mfma_f32_16x16x32_bf16 v[12:15], v[148:151], v[216:219], v[12:15]
	v_mfma_f32_16x16x32_bf16 v[8:11], v[164:167], v[216:219], v[8:11]
	v_mfma_f32_16x16x32_bf16 v[8:11], v[168:171], v[220:223], v[8:11]
	v_mfma_f32_16x16x32_bf16 v[24:27], v[168:171], v[212:215], v[24:27]
	v_mfma_f32_16x16x32_bf16 v[24:27], v[164:167], v[208:211], v[24:27]
	v_mfma_f32_16x16x32_bf16 v[40:43], v[164:167], v[196:199], v[40:43]
	v_mfma_f32_16x16x32_bf16 v[40:43], v[168:171], v[200:203], v[40:43]
	v_mfma_f32_16x16x32_bf16 v[56:59], v[168:171], v[192:195], v[56:59]
	v_mfma_f32_16x16x32_bf16 v[56:59], v[164:167], v[188:191], v[56:59]
	s_setprio 0
	s_setprio 1
	v_mfma_f32_16x16x32_bf16 v[52:55], v[172:175], v[188:191], v[52:55]
	v_mfma_f32_16x16x32_bf16 v[52:55], v[176:179], v[192:195], v[52:55]
	v_mfma_f32_16x16x32_bf16 v[36:39], v[176:179], v[200:203], v[36:39]
	v_mfma_f32_16x16x32_bf16 v[36:39], v[172:175], v[196:199], v[36:39]
	v_mfma_f32_16x16x32_bf16 v[20:23], v[172:175], v[208:211], v[20:23]
	v_mfma_f32_16x16x32_bf16 v[20:23], v[176:179], v[212:215], v[20:23]
	v_mfma_f32_16x16x32_bf16 v[4:7], v[176:179], v[220:223], v[4:7]
	v_mfma_f32_16x16x32_bf16 v[4:7], v[172:175], v[216:219], v[4:7]
	v_mfma_f32_16x16x32_bf16 v[0:3], v[180:183], v[216:219], v[0:3]
	v_mfma_f32_16x16x32_bf16 v[0:3], v[184:187], v[220:223], v[0:3]
	v_mfma_f32_16x16x32_bf16 v[16:19], v[184:187], v[212:215], v[16:19]
	v_mfma_f32_16x16x32_bf16 v[16:19], v[180:183], v[208:211], v[16:19]
	v_mfma_f32_16x16x32_bf16 v[32:35], v[180:183], v[196:199], v[32:35]
	v_mfma_f32_16x16x32_bf16 v[32:35], v[184:187], v[200:203], v[32:35]
	v_mfma_f32_16x16x32_bf16 v[48:51], v[184:187], v[192:195], v[48:51]
	v_mfma_f32_16x16x32_bf16 v[48:51], v[180:183], v[188:191], v[48:51]
	s_setprio 0
	s_barrier
	s_add_u32 s8, s8, 0x100
	s_addc_u32 s9, s9, 0
	s_add_u32 s33, s33, 0x100
	s_addc_u32 s34, s34, 0
	s_cmp_ge_i32 s35, s44
	s_mov_b32 s26, s35
	s_cbranch_scc0 .LBB0_541

; #define PG8_STAGE(bufoff, gbase, voff) do { _Pragma("unroll") for (int _i = 0; _i < 2; ++_i) \
;         __builtin_amdgcn_global_load_lds((const unsigned*)((const char*)(gbase) + (voff)[_i]), (LAS unsigned*)(lds + (bufoff) + ldsw + _i * 8192), 16, 0, 0); } while (0)
; #define PG8_LDA(dst, b, h) do { _Pragma("unroll") for (int m = 0; m < 4; ++m) _Pragma("unroll") for (int k = 0; k < 2; ++k) dst[m][k] = *(const LAS bf16x8*)(lds + PG8_SA(b, h) + aoff + m * 2048 + k * 1024); } while (0)
; #define PG8_LDB(dst, b, h) do { _Pragma("unroll") for (int n = 0; n < 2; ++n) _Pragma("unroll") for (int k = 0; k < 2; ++k) dst[n][k] = *(const LAS bf16x8*)(lds + PG8_SB(b, h) + boff + n * 2048 + k * 1024); } while (0)
; #define PG8_MMA(ai, bj, At, Bt) do { __builtin_amdgcn_s_setprio(1); _Pragma("unroll") for (int m = 0; m < 4; ++m) _Pragma("unroll") for (int n = 0; n < 2; ++n) _Pragma("unroll") for (int k = 0; k < 2; ++k) \
;         acc[ai][bj][m][n] = __builtin_amdgcn_mfma_f32_16x16x32_bf16(Bt[n][k], At[m][k], acc[ai][bj][m][n], 0, 0, 0); __builtin_amdgcn_s_setprio(0); } while (0)
; #define PG8_WAIT_V(n) asm volatile("s_waitcnt vmcnt(" #n ")" ::: "memory")
; #define PG8_WAIT_L(n) asm volatile("s_waitcnt lgkmcnt(" #n ")" ::: "memory")
; #define PG8_BAR __builtin_amdgcn_s_barrier()
; template <class Epi>
; __device__ __forceinline__ void gemm_phase(LAS unsigned char* lds, const Gemm g, const StaticOrder& S, const Epi& E) {
;     ...
;             const char* a2 = last ? nA : cA + (size_t)(t + 2) * kstep; const char* b2 = last ? nB : cB + (size_t)(t + 2) * kstep;
;             const char* a3 = a2 + kstep; const char* b3 = b2 + kstep;
;             PG8_LDB(B0, 0, 0); PG8_LDB(B1, 0, 1); PG8_SCHED; PG8_LDA(At, 0, 0); PG8_STAGE(PG8_SA(1, 1), a1 + hstepA, voffA);
;             PG8_WAIT_V(8); PG8_WAIT_L(0); PG8_BAR; PG8_MMA(0, 0, At, B0); PG8_MMA(0, 1, At, B1); PG8_BAR; PG8_SCHED;
;             PG8_LDA(At, 0, 1); PG8_STAGE(PG8_SB(0, 0), b2, voffB); PG8_STAGE(PG8_SB(0, 1), b2 + hstepB, voffB); PG8_STAGE(PG8_SA(0, 0), a2, voffA);
;             PG8_WAIT_V(8); PG8_WAIT_L(0); PG8_BAR; PG8_MMA(1, 0, At, B0); PG8_MMA(1, 1, At, B1); PG8_BAR; PG8_SCHED;
;             PG8_LDB(B0, 1, 0); PG8_LDB(B1, 1, 1); PG8_SCHED; PG8_LDA(At, 1, 0); PG8_STAGE(PG8_SA(0, 1), a2 + hstepA, voffA);
;             PG8_WAIT_V(8); PG8_WAIT_L(0); PG8_BAR; PG8_MMA(0, 0, At, B0); PG8_MMA(0, 1, At, B1); PG8_BAR; PG8_SCHED;
.LBB0_685:
	ds_read_b128 v[88:91], v85
	ds_read_b128 v[92:95], v85 offset:1024
	ds_read_b128 v[96:99], v85 offset:2048
	ds_read_b128 v[100:103], v85 offset:3072
	s_add_i32 s61, s34, 2
	s_add_u32 s8, s30, 0x100
	s_addc_u32 s9, s31, 0
	s_cmp_eq_u32 s53, s34
	s_cselect_b32 s34, s25, s59
	s_cselect_b32 s37, s27, s9
	s_cselect_b32 s36, s26, s8
	s_cselect_b32 s35, s17, s60
	v_lshl_add_u64 v[136:137], s[30:31], 0, v[76:77]
	s_add_i32 m0, s40, 0xc000
	ds_read_b128 v[104:107], v86
	ds_read_b128 v[108:111], v86 offset:1024
	ds_read_b128 v[112:115], v86 offset:2048
	ds_read_b128 v[116:119], v86 offset:3072
	ds_read_b128 v[120:123], v86 offset:4096
	ds_read_b128 v[124:127], v86 offset:5120
	ds_read_b128 v[128:131], v86 offset:6144
	ds_read_b128 v[132:135], v86 offset:7168
	global_load_lds_dwordx4 v[136:137], off
	v_lshl_add_u64 v[136:137], s[30:31], 0, v[78:79]
	s_add_i32 m0, s40, 0xe000
	s_nop 0
	global_load_lds_dwordx4 v[136:137], off
	s_waitcnt vmcnt(8)
	s_waitcnt lgkmcnt(0)
	s_barrier
	s_setprio 1
	s_waitcnt lgkmcnt(0)
	v_mfma_f32_16x16x32_bf16 v[60:63], v[88:91], v[104:107], v[60:63]
	v_mfma_f32_16x16x32_bf16 v[60:63], v[92:95], v[108:111], v[60:63]
	v_mfma_f32_16x16x32_bf16 v[52:55], v[92:95], v[116:119], v[52:55]
	v_mfma_f32_16x16x32_bf16 v[52:55], v[88:91], v[112:115], v[52:55]
	v_mfma_f32_16x16x32_bf16 v[44:47], v[88:91], v[120:123], v[44:47]
	v_mfma_f32_16x16x32_bf16 v[44:47], v[92:95], v[124:127], v[44:47]
	v_mfma_f32_16x16x32_bf16 v[36:39], v[92:95], v[132:135], v[36:39]
	v_mfma_f32_16x16x32_bf16 v[36:39], v[88:91], v[128:131], v[36:39]
	v_mfma_f32_16x16x32_bf16 v[32:35], v[96:99], v[128:131], v[32:35]
	v_mfma_f32_16x16x32_bf16 v[32:35], v[100:103], v[132:135], v[32:35]
	v_mfma_f32_16x16x32_bf16 v[40:43], v[100:103], v[124:127], v[40:43]
	v_mfma_f32_16x16x32_bf16 v[40:43], v[96:99], v[120:123], v[40:43]
	v_mfma_f32_16x16x32_bf16 v[48:51], v[96:99], v[112:115], v[48:51]
	v_mfma_f32_16x16x32_bf16 v[48:51], v[100:103], v[116:119], v[48:51]
	v_mfma_f32_16x16x32_bf16 v[56:59], v[100:103], v[108:111], v[56:59]
	v_mfma_f32_16x16x32_bf16 v[56:59], v[96:99], v[104:107], v[56:59]
	s_setprio 0
	s_setprio 1
	s_setprio 0
	s_barrier
	s_add_i32 s30, s56, s39
	v_lshl_add_u64 v[136:137], s[34:35], 0, v[66:67]
	s_mov_b32 m0, s30
	ds_read_b128 v[104:107], v86 offset:16384
	ds_read_b128 v[108:111], v86 offset:17408
	ds_read_b128 v[112:115], v86 offset:18432
	ds_read_b128 v[116:119], v86 offset:19456
	ds_read_b128 v[120:123], v86 offset:20480
	ds_read_b128 v[124:127], v86 offset:21504
	ds_read_b128 v[128:131], v86 offset:22528
	ds_read_b128 v[132:135], v86 offset:23552
	global_load_lds_dwordx4 v[136:137], off
	s_add_i32 m0, s30, 0x2000
	s_add_u32 s30, s34, 0x10000
	v_lshl_add_u64 v[138:139], s[34:35], 0, v[70:71]
	s_addc_u32 s31, s35, 0
	global_load_lds_dwordx4 v[138:139], off
	v_lshl_add_u64 v[140:141], s[30:31], 0, v[66:67]
	s_mov_b32 m0, s41
	v_lshl_add_u64 v[142:143], s[36:37], 0, v[68:69]
	global_load_lds_dwordx4 v[140:141], off
	v_lshl_add_u64 v[140:141], s[30:31], 0, v[70:71]
	s_mov_b32 m0, s42
	s_nop 0
	global_load_lds_dwordx4 v[140:141], off
	v_lshl_add_u64 v[140:141], s[36:37], 0, v[64:65]
	s_mov_b32 m0, s40
	s_nop 0
	global_load_lds_dwordx4 v[140:141], off
	s_mov_b32 m0, s43
	s_nop 0
	global_load_lds_dwordx4 v[142:143], off
	s_waitcnt vmcnt(8)
	s_waitcnt lgkmcnt(0)
	s_barrier
	s_setprio 1
	s_waitcnt lgkmcnt(0)
	v_mfma_f32_16x16x32_bf16 v[28:31], v[88:91], v[104:107], v[28:31]
	v_mfma_f32_16x16x32_bf16 v[28:31], v[92:95], v[108:111], v[28:31]
	v_mfma_f32_16x16x32_bf16 v[20:23], v[92:95], v[116:119], v[20:23]
	v_mfma_f32_16x16x32_bf16 v[20:23], v[88:91], v[112:115], v[20:23]
	v_mfma_f32_16x16x32_bf16 v[12:15], v[88:91], v[120:123], v[12:15]
	v_mfma_f32_16x16x32_bf16 v[12:15], v[92:95], v[124:127], v[12:15]
	v_mfma_f32_16x16x32_bf16 v[4:7], v[92:95], v[132:135], v[4:7]
	v_mfma_f32_16x16x32_bf16 v[4:7], v[88:91], v[128:131], v[4:7]
	v_mfma_f32_16x16x32_bf16 v[0:3], v[96:99], v[128:131], v[0:3]
	v_mfma_f32_16x16x32_bf16 v[0:3], v[100:103], v[132:135], v[0:3]
	v_mfma_f32_16x16x32_bf16 v[8:11], v[100:103], v[124:127], v[8:11]
	v_mfma_f32_16x16x32_bf16 v[8:11], v[96:99], v[120:123], v[8:11]
	v_mfma_f32_16x16x32_bf16 v[16:19], v[96:99], v[112:115], v[16:19]
	v_mfma_f32_16x16x32_bf16 v[16:19], v[100:103], v[116:119], v[16:19]
	v_mfma_f32_16x16x32_bf16 v[24:27], v[100:103], v[108:111], v[24:27]
	v_mfma_f32_16x16x32_bf16 v[24:27], v[96:99], v[104:107], v[24:27]
	s_setprio 0
	s_setprio 1
	s_setprio 0
	s_barrier
; #define PG8_STAGE(bufoff, gbase, voff) do { _Pragma("unroll") for (int _i = 0; _i < 2; ++_i) \
;         __builtin_amdgcn_global_load_lds((const unsigned*)((const char*)(gbase) + (voff)[_i]), (LAS unsigned*)(lds + (bufoff) + ldsw + _i * 8192), 16, 0, 0); } while (0)
; #define PG8_LDA(dst, b, h) do { _Pragma("unroll") for (int m = 0; m < 4; ++m) _Pragma("unroll") for (int k = 0; k < 2; ++k) dst[m][k] = *(const LAS bf16x8*)(lds + PG8_SA(b, h) + aoff + m * 2048 + k * 1024); } while (0)
; #define PG8_LDB(dst, b, h) do { _Pragma("unroll") for (int n = 0; n < 2; ++n) _Pragma("unroll") for (int k = 0; k < 2; ++k) dst[n][k] = *(const LAS bf16x8*)(lds + PG8_SB(b, h) + boff + n * 2048 + k * 1024); } while (0)
; #define PG8_MMA(ai, bj, At, Bt) do { __builtin_amdgcn_s_setprio(1); _Pragma("unroll") for (int m = 0; m < 4; ++m) _Pragma("unroll") for (int n = 0; n < 2; ++n) _Pragma("unroll") for (int k = 0; k < 2; ++k) \
;         acc[ai][bj][m][n] = __builtin_amdgcn_mfma_f32_16x16x32_bf16(Bt[n][k], At[m][k], acc[ai][bj][m][n], 0, 0, 0); __builtin_amdgcn_s_setprio(0); } while (0)
; #define PG8_WAIT_V(n) asm volatile("s_waitcnt vmcnt(" #n ")" ::: "memory")
; #define PG8_WAIT_L(n) asm volatile("s_waitcnt lgkmcnt(" #n ")" ::: "memory")
; #define PG8_BAR __builtin_amdgcn_s_barrier()
; #define PG8_SCHED __builtin_amdgcn_sched_barrier(0)
; template <class Epi>
; __device__ __forceinline__ void gemm_phase(LAS unsigned char* lds, const Gemm g, const StaticOrder& S, const Epi& E) {
;     ...
;             PG8_LDB(B0, 1, 0); PG8_LDB(B1, 1, 1); PG8_SCHED; PG8_LDA(At, 1, 0); PG8_STAGE(PG8_SA(0, 1), a2 + hstepA, voffA);
;             PG8_WAIT_V(8); PG8_WAIT_L(0); PG8_BAR; PG8_MMA(0, 0, At, B0); PG8_MMA(0, 1, At, B1); PG8_BAR; PG8_SCHED;
;             PG8_LDA(At, 1, 1); PG8_STAGE(PG8_SB(1, 0), b3, voffB); PG8_STAGE(PG8_SB(1, 1), b3 + hstepB, voffB); PG8_STAGE(PG8_SA(1, 0), a3, voffA);
;             PG8_WAIT_V(8); PG8_WAIT_L(0); PG8_BAR; PG8_MMA(1, 0, At, B0); PG8_MMA(1, 1, At, B1); PG8_BAR; PG8_SCHED;
	s_add_i32 s62, 0, 0x18000
	v_add_u32_e32 v87, s62, v84
	ds_read_b128 v[88:91], v87
	ds_read_b128 v[92:95], v87 offset:1024
	ds_read_b128 v[96:99], v87 offset:2048
	ds_read_b128 v[100:103], v87 offset:3072
	s_add_u32 s30, s36, 0x18000
	s_addc_u32 s31, s37, 0
	s_mov_b32 m0, s44
	v_lshl_add_u64 v[144:145], s[30:31], 0, v[64:65]
	ds_read_b128 v[104:107], v86 offset:32768
	ds_read_b128 v[108:111], v86 offset:33792
	ds_read_b128 v[112:115], v86 offset:34816
	ds_read_b128 v[116:119], v86 offset:35840
	ds_read_b128 v[120:123], v86 offset:36864
	ds_read_b128 v[124:127], v86 offset:37888
	ds_read_b128 v[128:131], v86 offset:38912
	ds_read_b128 v[132:135], v86 offset:39936
	global_load_lds_dwordx4 v[144:145], off
	v_lshl_add_u64 v[144:145], s[30:31], 0, v[68:69]
	s_mov_b32 m0, s45
	s_nop 0
	global_load_lds_dwordx4 v[144:145], off
	s_waitcnt vmcnt(8)
	s_waitcnt lgkmcnt(0)
	s_barrier
	s_setprio 1
	s_waitcnt lgkmcnt(0)
	v_mfma_f32_16x16x32_bf16 v[60:63], v[88:91], v[104:107], v[60:63]
	v_mfma_f32_16x16x32_bf16 v[60:63], v[92:95], v[108:111], v[60:63]
	v_mfma_f32_16x16x32_bf16 v[52:55], v[92:95], v[116:119], v[52:55]
	v_mfma_f32_16x16x32_bf16 v[52:55], v[88:91], v[112:115], v[52:55]
	v_mfma_f32_16x16x32_bf16 v[44:47], v[88:91], v[120:123], v[44:47]
	v_mfma_f32_16x16x32_bf16 v[44:47], v[92:95], v[124:127], v[44:47]
	v_mfma_f32_16x16x32_bf16 v[36:39], v[92:95], v[132:135], v[36:39]
	v_mfma_f32_16x16x32_bf16 v[36:39], v[88:91], v[128:131], v[36:39]
	v_mfma_f32_16x16x32_bf16 v[32:35], v[96:99], v[128:131], v[32:35]
	v_mfma_f32_16x16x32_bf16 v[32:35], v[100:103], v[132:135], v[32:35]
	v_mfma_f32_16x16x32_bf16 v[40:43], v[100:103], v[124:127], v[40:43]
	v_mfma_f32_16x16x32_bf16 v[40:43], v[96:99], v[120:123], v[40:43]
	v_mfma_f32_16x16x32_bf16 v[48:51], v[96:99], v[112:115], v[48:51]
	v_mfma_f32_16x16x32_bf16 v[48:51], v[100:103], v[116:119], v[48:51]
	v_mfma_f32_16x16x32_bf16 v[56:59], v[100:103], v[108:111], v[56:59]
	v_mfma_f32_16x16x32_bf16 v[56:59], v[96:99], v[104:107], v[56:59]
	s_setprio 0
	s_setprio 1
	s_setprio 0
	s_barrier
	s_add_i32 s30, s62, s39
	v_lshl_add_u64 v[136:137], v[136:137], 0, s[10:11]
	s_mov_b32 m0, s30
	ds_read_b128 v[104:107], v86 offset:49152
	ds_read_b128 v[108:111], v86 offset:50176
	ds_read_b128 v[112:115], v86 offset:51200
	ds_read_b128 v[116:119], v86 offset:52224
	ds_read_b128 v[120:123], v86 offset:53248
	ds_read_b128 v[124:127], v86 offset:54272
	ds_read_b128 v[128:131], v86 offset:55296
	ds_read_b128 v[132:135], v86 offset:56320
	global_load_lds_dwordx4 v[136:137], off
	s_add_i32 m0, s30, 0x2000
	s_add_u32 s30, s34, 0x10080
	v_lshl_add_u64 v[136:137], v[138:139], 0, s[10:11]
	s_addc_u32 s31, s35, 0
	global_load_lds_dwordx4 v[136:137], off
	v_lshl_add_u64 v[136:137], s[30:31], 0, v[66:67]
	s_mov_b32 m0, s49
	s_nop 0
	global_load_lds_dwordx4 v[136:137], off
	v_lshl_add_u64 v[136:137], s[30:31], 0, v[70:71]
	s_mov_b32 m0, s52
	s_nop 0
	global_load_lds_dwordx4 v[136:137], off
	v_lshl_add_u64 v[136:137], v[140:141], 0, s[10:11]
	s_mov_b32 m0, s47
	s_nop 0
	global_load_lds_dwordx4 v[136:137], off
	v_lshl_add_u64 v[136:137], v[142:143], 0, s[10:11]
	s_mov_b32 m0, s48
	s_nop 0
	global_load_lds_dwordx4 v[136:137], off
	s_waitcnt vmcnt(8)
	s_waitcnt lgkmcnt(0)
	s_barrier
	s_setprio 1
	s_waitcnt lgkmcnt(0)
	v_mfma_f32_16x16x32_bf16 v[28:31], v[88:91], v[104:107], v[28:31]
	v_mfma_f32_16x16x32_bf16 v[28:31], v[92:95], v[108:111], v[28:31]
	v_mfma_f32_16x16x32_bf16 v[20:23], v[92:95], v[116:119], v[20:23]
	v_mfma_f32_16x16x32_bf16 v[20:23], v[88:91], v[112:115], v[20:23]
	v_mfma_f32_16x16x32_bf16 v[12:15], v[88:91], v[120:123], v[12:15]
	v_mfma_f32_16x16x32_bf16 v[12:15], v[92:95], v[124:127], v[12:15]
	v_mfma_f32_16x16x32_bf16 v[4:7], v[92:95], v[132:135], v[4:7]
	v_mfma_f32_16x16x32_bf16 v[4:7], v[88:91], v[128:131], v[4:7]
	v_mfma_f32_16x16x32_bf16 v[0:3], v[96:99], v[128:131], v[0:3]
	v_mfma_f32_16x16x32_bf16 v[0:3], v[100:103], v[132:135], v[0:3]
	v_mfma_f32_16x16x32_bf16 v[8:11], v[100:103], v[124:127], v[8:11]
	v_mfma_f32_16x16x32_bf16 v[8:11], v[96:99], v[120:123], v[8:11]
	v_mfma_f32_16x16x32_bf16 v[16:19], v[96:99], v[112:115], v[16:19]
	v_mfma_f32_16x16x32_bf16 v[16:19], v[100:103], v[116:119], v[16:19]
	v_mfma_f32_16x16x32_bf16 v[24:27], v[100:103], v[108:111], v[24:27]
	v_mfma_f32_16x16x32_bf16 v[24:27], v[96:99], v[104:107], v[24:27]
	s_setprio 0
	s_setprio 1
	s_setprio 0
	s_barrier
	s_add_u32 s59, s59, 0x100
	s_addc_u32 s60, s60, 0
	s_cmp_ge_i32 s61, s46
	s_mov_b64 s[30:31], s[8:9]
	s_mov_b32 s34, s61
	s_cbranch_scc0 .LBB0_685

; #define PG8_STAGE(bufoff, gbase, voff) do { _Pragma("unroll") for (int _i = 0; _i < 2; ++_i) \
;         __builtin_amdgcn_global_load_lds((const unsigned*)((const char*)(gbase) + (voff)[_i]), (LAS unsigned*)(lds + (bufoff) + ldsw + _i * 8192), 16, 0, 0); } while (0)
; #define PG8_LDA(dst, b, h) do { _Pragma("unroll") for (int m = 0; m < 4; ++m) _Pragma("unroll") for (int k = 0; k < 2; ++k) dst[m][k] = *(const LAS bf16x8*)(lds + PG8_SA(b, h) + aoff + m * 2048 + k * 1024); } while (0)
; #define PG8_LDB(dst, b, h) do { _Pragma("unroll") for (int n = 0; n < 2; ++n) _Pragma("unroll") for (int k = 0; k < 2; ++k) dst[n][k] = *(const LAS bf16x8*)(lds + PG8_SB(b, h) + boff + n * 2048 + k * 1024); } while (0)
; #define PG8_MMA(ai, bj, At, Bt) do { __builtin_amdgcn_s_setprio(1); _Pragma("unroll") for (int m = 0; m < 4; ++m) _Pragma("unroll") for (int n = 0; n < 2; ++n) _Pragma("unroll") for (int k = 0; k < 2; ++k) \
;         acc[ai][bj][m][n] = __builtin_amdgcn_mfma_f32_16x16x32_bf16(Bt[n][k], At[m][k], acc[ai][bj][m][n], 0, 0, 0); __builtin_amdgcn_s_setprio(0); } while (0)
; #define PG8_WAIT_V(n) asm volatile("s_waitcnt vmcnt(" #n ")" ::: "memory")
; #define PG8_WAIT_L(n) asm volatile("s_waitcnt lgkmcnt(" #n ")" ::: "memory")
; #define PG8_BAR __builtin_amdgcn_s_barrier()
; #define PG8_SCHED __builtin_amdgcn_sched_barrier(0)
; template <class Epi>
; __device__ __forceinline__ void gemm_phase(LAS unsigned char* lds, const Gemm g, const StaticOrder& S, const Epi& E) {
;     ...
;             const bool last = (t == nt - 2);
;             const char* a1 = cA + (size_t)(t + 1) * kstep;
;             const char* a2 = last ? nA : cA + (size_t)(t + 2) * kstep; const char* b2 = last ? nB : cB + (size_t)(t + 2) * kstep;
;             const char* a3 = a2 + kstep; const char* b3 = b2 + kstep;
;             PG8_LDB(B0, 0, 0); PG8_LDB(B1, 0, 1); PG8_SCHED; PG8_LDA(At, 0, 0); PG8_STAGE(PG8_SA(1, 1), a1 + hstepA, voffA);
;             PG8_WAIT_V(8); PG8_WAIT_L(0); PG8_BAR; PG8_MMA(0, 0, At, B0); PG8_MMA(0, 1, At, B1); PG8_BAR; PG8_SCHED;
;             PG8_LDA(At, 0, 1); PG8_STAGE(PG8_SB(0, 0), b2, voffB); PG8_STAGE(PG8_SB(0, 1), b2 + hstepB, voffB); PG8_STAGE(PG8_SA(0, 0), a2, voffA);
;             PG8_WAIT_V(8); PG8_WAIT_L(0); PG8_BAR; PG8_MMA(1, 0, At, B0); PG8_MMA(1, 1, At, B1); PG8_BAR; PG8_SCHED;
.LBB0_834:
	ds_read_b128 v[156:159], v152
	ds_read_b128 v[160:163], v152 offset:1024
	ds_read_b128 v[164:167], v152 offset:2048
	ds_read_b128 v[168:171], v152 offset:3072
	ds_read_b128 v[172:175], v153
	ds_read_b128 v[176:179], v153 offset:1024
	ds_read_b128 v[180:183], v153 offset:2048
	ds_read_b128 v[184:187], v153 offset:3072
	s_add_i32 s49, s22, 2
	s_add_u32 s4, s0, 0x100
	s_addc_u32 s5, s1, 0
	s_cmp_eq_u32 s40, s22
	s_cselect_b32 s22, s20, s47
	s_cselect_b32 s25, s11, s5
	s_cselect_b32 s24, s10, s4
	s_cselect_b32 s23, s21, s48
	v_lshl_add_u64 v[224:225], s[0:1], 0, v[138:139]
	s_add_i32 m0, s29, 0xc000
	ds_read_b128 v[188:191], v154
	ds_read_b128 v[192:195], v154 offset:1024
	ds_read_b128 v[196:199], v154 offset:2048
	ds_read_b128 v[200:203], v154 offset:3072
	ds_read_b128 v[208:211], v154 offset:4096
	ds_read_b128 v[212:215], v154 offset:5120
	ds_read_b128 v[216:219], v154 offset:6144
	ds_read_b128 v[220:223], v154 offset:7168
	global_load_lds_dwordx4 v[224:225], off
	v_lshl_add_u64 v[224:225], s[0:1], 0, v[140:141]
	s_add_i32 m0, s29, 0xe000
	s_nop 0
	global_load_lds_dwordx4 v[224:225], off
	s_waitcnt vmcnt(8)
	s_waitcnt lgkmcnt(0)
	s_barrier
	s_setprio 1
	s_waitcnt lgkmcnt(0)
	v_mfma_f32_16x16x32_bf16 v[124:127], v[156:159], v[188:191], v[124:127]
	v_mfma_f32_16x16x32_bf16 v[124:127], v[160:163], v[192:195], v[124:127]
	v_mfma_f32_16x16x32_bf16 v[108:111], v[160:163], v[200:203], v[108:111]
	v_mfma_f32_16x16x32_bf16 v[108:111], v[156:159], v[196:199], v[108:111]
	v_mfma_f32_16x16x32_bf16 v[92:95], v[156:159], v[208:211], v[92:95]
	v_mfma_f32_16x16x32_bf16 v[92:95], v[160:163], v[212:215], v[92:95]
	v_mfma_f32_16x16x32_bf16 v[76:79], v[160:163], v[220:223], v[76:79]
	v_mfma_f32_16x16x32_bf16 v[76:79], v[156:159], v[216:219], v[76:79]
	v_mfma_f32_16x16x32_bf16 v[72:75], v[164:167], v[216:219], v[72:75]
	v_mfma_f32_16x16x32_bf16 v[72:75], v[168:171], v[220:223], v[72:75]
	v_mfma_f32_16x16x32_bf16 v[88:91], v[168:171], v[212:215], v[88:91]
	v_mfma_f32_16x16x32_bf16 v[88:91], v[164:167], v[208:211], v[88:91]
	v_mfma_f32_16x16x32_bf16 v[104:107], v[164:167], v[196:199], v[104:107]
	v_mfma_f32_16x16x32_bf16 v[104:107], v[168:171], v[200:203], v[104:107]
	v_mfma_f32_16x16x32_bf16 v[120:123], v[168:171], v[192:195], v[120:123]
	v_mfma_f32_16x16x32_bf16 v[120:123], v[164:167], v[188:191], v[120:123]
	s_setprio 0
	s_setprio 1
	v_mfma_f32_16x16x32_bf16 v[116:119], v[172:175], v[188:191], v[116:119]
	v_mfma_f32_16x16x32_bf16 v[116:119], v[176:179], v[192:195], v[116:119]
	v_mfma_f32_16x16x32_bf16 v[100:103], v[176:179], v[200:203], v[100:103]
	v_mfma_f32_16x16x32_bf16 v[100:103], v[172:175], v[196:199], v[100:103]
	v_mfma_f32_16x16x32_bf16 v[84:87], v[172:175], v[208:211], v[84:87]
	v_mfma_f32_16x16x32_bf16 v[84:87], v[176:179], v[212:215], v[84:87]
	v_mfma_f32_16x16x32_bf16 v[68:71], v[176:179], v[220:223], v[68:71]
	v_mfma_f32_16x16x32_bf16 v[68:71], v[172:175], v[216:219], v[68:71]
	v_mfma_f32_16x16x32_bf16 v[64:67], v[180:183], v[216:219], v[64:67]
	v_mfma_f32_16x16x32_bf16 v[64:67], v[184:187], v[220:223], v[64:67]
	v_mfma_f32_16x16x32_bf16 v[80:83], v[184:187], v[212:215], v[80:83]
	v_mfma_f32_16x16x32_bf16 v[80:83], v[180:183], v[208:211], v[80:83]
	v_mfma_f32_16x16x32_bf16 v[96:99], v[180:183], v[196:199], v[96:99]
	v_mfma_f32_16x16x32_bf16 v[96:99], v[184:187], v[200:203], v[96:99]
	v_mfma_f32_16x16x32_bf16 v[112:115], v[184:187], v[192:195], v[112:115]
	v_mfma_f32_16x16x32_bf16 v[112:115], v[180:183], v[188:191], v[112:115]
	s_setprio 0
	s_barrier
	s_add_i32 s0, s43, s28
	v_lshl_add_u64 v[224:225], s[22:23], 0, v[130:131]
	s_mov_b32 m0, s0
	ds_read_b128 v[188:191], v154 offset:16384
	ds_read_b128 v[192:195], v154 offset:17408
	ds_read_b128 v[196:199], v154 offset:18432
	ds_read_b128 v[200:203], v154 offset:19456
	ds_read_b128 v[208:211], v154 offset:20480
	ds_read_b128 v[212:215], v154 offset:21504
	ds_read_b128 v[216:219], v154 offset:22528
	ds_read_b128 v[220:223], v154 offset:23552
	global_load_lds_dwordx4 v[224:225], off
	s_add_i32 m0, s0, 0x2000
	s_add_u32 s0, s22, 0x18000
	v_lshl_add_u64 v[226:227], s[22:23], 0, v[134:135]
	s_addc_u32 s1, s23, 0
	s_add_i32 s50, s44, s28
	global_load_lds_dwordx4 v[226:227], off
	v_lshl_add_u64 v[230:231], s[0:1], 0, v[130:131]
	s_mov_b32 m0, s50
	v_lshl_add_u64 v[232:233], s[24:25], 0, v[132:133]
	global_load_lds_dwordx4 v[230:231], off
	v_lshl_add_u64 v[230:231], s[0:1], 0, v[134:135]
	s_add_i32 m0, s50, 0x2000
	s_nop 0
	global_load_lds_dwordx4 v[230:231], off
	v_lshl_add_u64 v[230:231], s[24:25], 0, v[128:129]
	s_mov_b32 m0, s29
	s_nop 0
	global_load_lds_dwordx4 v[230:231], off
	s_mov_b32 m0, s30
	s_nop 0
	global_load_lds_dwordx4 v[232:233], off
	s_waitcnt vmcnt(8)
	s_waitcnt lgkmcnt(0)
	s_barrier
; #define PG8_STAGE(bufoff, gbase, voff) do { _Pragma("unroll") for (int _i = 0; _i < 2; ++_i) \
;         __builtin_amdgcn_global_load_lds((const unsigned*)((const char*)(gbase) + (voff)[_i]), (LAS unsigned*)(lds + (bufoff) + ldsw + _i * 8192), 16, 0, 0); } while (0)
; #define PG8_LDA(dst, b, h) do { _Pragma("unroll") for (int m = 0; m < 4; ++m) _Pragma("unroll") for (int k = 0; k < 2; ++k) dst[m][k] = *(const LAS bf16x8*)(lds + PG8_SA(b, h) + aoff + m * 2048 + k * 1024); } while (0)
; #define PG8_LDB(dst, b, h) do { _Pragma("unroll") for (int n = 0; n < 2; ++n) _Pragma("unroll") for (int k = 0; k < 2; ++k) dst[n][k] = *(const LAS bf16x8*)(lds + PG8_SB(b, h) + boff + n * 2048 + k * 1024); } while (0)
; #define PG8_MMA(ai, bj, At, Bt) do { __builtin_amdgcn_s_setprio(1); _Pragma("unroll") for (int m = 0; m < 4; ++m) _Pragma("unroll") for (int n = 0; n < 2; ++n) _Pragma("unroll") for (int k = 0; k < 2; ++k) \
;         acc[ai][bj][m][n] = __builtin_amdgcn_mfma_f32_16x16x32_bf16(Bt[n][k], At[m][k], acc[ai][bj][m][n], 0, 0, 0); __builtin_amdgcn_s_setprio(0); } while (0)
; #define PG8_WAIT_V(n) asm volatile("s_waitcnt vmcnt(" #n ")" ::: "memory")
; #define PG8_WAIT_L(n) asm volatile("s_waitcnt lgkmcnt(" #n ")" ::: "memory")
; #define PG8_BAR __builtin_amdgcn_s_barrier()
; #define PG8_SCHED __builtin_amdgcn_sched_barrier(0)
; template <class Epi>
; __device__ __forceinline__ void gemm_phase(LAS unsigned char* lds, const Gemm g, const StaticOrder& S, const Epi& E) {
;     ...
;             PG8_WAIT_V(8); PG8_WAIT_L(0); PG8_BAR; PG8_MMA(1, 0, At, B0); PG8_MMA(1, 1, At, B1); PG8_BAR; PG8_SCHED;
;             PG8_LDB(B0, 1, 0); PG8_LDB(B1, 1, 1); PG8_SCHED; PG8_LDA(At, 1, 0); PG8_STAGE(PG8_SA(0, 1), a2 + hstepA, voffA);
;             PG8_WAIT_V(8); PG8_WAIT_L(0); PG8_BAR; PG8_MMA(0, 0, At, B0); PG8_MMA(0, 1, At, B1); PG8_BAR; PG8_SCHED;
	s_setprio 1
	s_waitcnt lgkmcnt(0)
	v_mfma_f32_16x16x32_bf16 v[60:63], v[156:159], v[188:191], v[60:63]
	v_mfma_f32_16x16x32_bf16 v[60:63], v[160:163], v[192:195], v[60:63]
	v_mfma_f32_16x16x32_bf16 v[44:47], v[160:163], v[200:203], v[44:47]
	v_mfma_f32_16x16x32_bf16 v[44:47], v[156:159], v[196:199], v[44:47]
	v_mfma_f32_16x16x32_bf16 v[28:31], v[156:159], v[208:211], v[28:31]
	v_mfma_f32_16x16x32_bf16 v[28:31], v[160:163], v[212:215], v[28:31]
	v_mfma_f32_16x16x32_bf16 v[12:15], v[160:163], v[220:223], v[12:15]
	v_mfma_f32_16x16x32_bf16 v[12:15], v[156:159], v[216:219], v[12:15]
	v_mfma_f32_16x16x32_bf16 v[8:11], v[164:167], v[216:219], v[8:11]
	v_mfma_f32_16x16x32_bf16 v[8:11], v[168:171], v[220:223], v[8:11]
	v_mfma_f32_16x16x32_bf16 v[24:27], v[168:171], v[212:215], v[24:27]
	v_mfma_f32_16x16x32_bf16 v[24:27], v[164:167], v[208:211], v[24:27]
	v_mfma_f32_16x16x32_bf16 v[40:43], v[164:167], v[196:199], v[40:43]
	v_mfma_f32_16x16x32_bf16 v[40:43], v[168:171], v[200:203], v[40:43]
	v_mfma_f32_16x16x32_bf16 v[56:59], v[168:171], v[192:195], v[56:59]
	v_mfma_f32_16x16x32_bf16 v[56:59], v[164:167], v[188:191], v[56:59]
	s_setprio 0
	s_setprio 1
	v_mfma_f32_16x16x32_bf16 v[52:55], v[172:175], v[188:191], v[52:55]
	v_mfma_f32_16x16x32_bf16 v[52:55], v[176:179], v[192:195], v[52:55]
	v_mfma_f32_16x16x32_bf16 v[36:39], v[176:179], v[200:203], v[36:39]
	v_mfma_f32_16x16x32_bf16 v[36:39], v[172:175], v[196:199], v[36:39]
	v_mfma_f32_16x16x32_bf16 v[20:23], v[172:175], v[208:211], v[20:23]
	v_mfma_f32_16x16x32_bf16 v[20:23], v[176:179], v[212:215], v[20:23]
	v_mfma_f32_16x16x32_bf16 v[4:7], v[176:179], v[220:223], v[4:7]
	v_mfma_f32_16x16x32_bf16 v[4:7], v[172:175], v[216:219], v[4:7]
	v_mfma_f32_16x16x32_bf16 v[0:3], v[180:183], v[216:219], v[0:3]
	v_mfma_f32_16x16x32_bf16 v[0:3], v[184:187], v[220:223], v[0:3]
	v_mfma_f32_16x16x32_bf16 v[16:19], v[184:187], v[212:215], v[16:19]
	v_mfma_f32_16x16x32_bf16 v[16:19], v[180:183], v[208:211], v[16:19]
	v_mfma_f32_16x16x32_bf16 v[32:35], v[180:183], v[196:199], v[32:35]
	v_mfma_f32_16x16x32_bf16 v[32:35], v[184:187], v[200:203], v[32:35]
	v_mfma_f32_16x16x32_bf16 v[48:51], v[184:187], v[192:195], v[48:51]
	v_mfma_f32_16x16x32_bf16 v[48:51], v[180:183], v[188:191], v[48:51]
	s_setprio 0
	s_barrier
	s_add_i32 s50, 0, 0x18000
	v_add_u32_e32 v136, s50, v149
	s_add_i32 s51, 0, 0x1c000
	ds_read_b128 v[156:159], v136
	ds_read_b128 v[160:163], v136 offset:1024
	ds_read_b128 v[164:167], v136 offset:2048
	ds_read_b128 v[168:171], v136 offset:3072
	v_add_u32_e32 v136, s51, v149
	ds_read_b128 v[172:175], v136
	ds_read_b128 v[176:179], v136 offset:1024
	ds_read_b128 v[180:183], v136 offset:2048
	ds_read_b128 v[184:187], v136 offset:3072
	s_add_u32 s0, s24, 0x18000
	s_addc_u32 s1, s25, 0
	s_mov_b32 m0, s31
	v_lshl_add_u64 v[234:235], s[0:1], 0, v[128:129]
	ds_read_b128 v[188:191], v154 offset:32768
	ds_read_b128 v[192:195], v154 offset:33792
	ds_read_b128 v[196:199], v154 offset:34816
	ds_read_b128 v[200:203], v154 offset:35840
	ds_read_b128 v[208:211], v154 offset:36864
	ds_read_b128 v[212:215], v154 offset:37888
	ds_read_b128 v[216:219], v154 offset:38912
	ds_read_b128 v[220:223], v154 offset:39936
	global_load_lds_dwordx4 v[234:235], off
	v_lshl_add_u64 v[234:235], s[0:1], 0, v[132:133]
	s_mov_b32 m0, s34
	s_nop 0
	global_load_lds_dwordx4 v[234:235], off
	s_waitcnt vmcnt(8)
	s_waitcnt lgkmcnt(0)
	s_barrier
	s_setprio 1
	s_waitcnt lgkmcnt(0)
	v_mfma_f32_16x16x32_bf16 v[124:127], v[156:159], v[188:191], v[124:127]
	v_mfma_f32_16x16x32_bf16 v[124:127], v[160:163], v[192:195], v[124:127]
	v_mfma_f32_16x16x32_bf16 v[108:111], v[160:163], v[200:203], v[108:111]
	v_mfma_f32_16x16x32_bf16 v[108:111], v[156:159], v[196:199], v[108:111]
	v_mfma_f32_16x16x32_bf16 v[92:95], v[156:159], v[208:211], v[92:95]
	v_mfma_f32_16x16x32_bf16 v[92:95], v[160:163], v[212:215], v[92:95]
	v_mfma_f32_16x16x32_bf16 v[76:79], v[160:163], v[220:223], v[76:79]
	v_mfma_f32_16x16x32_bf16 v[76:79], v[156:159], v[216:219], v[76:79]
	v_mfma_f32_16x16x32_bf16 v[72:75], v[164:167], v[216:219], v[72:75]
	v_mfma_f32_16x16x32_bf16 v[72:75], v[168:171], v[220:223], v[72:75]
	v_mfma_f32_16x16x32_bf16 v[88:91], v[168:171], v[212:215], v[88:91]
	v_mfma_f32_16x16x32_bf16 v[88:91], v[164:167], v[208:211], v[88:91]
	v_mfma_f32_16x16x32_bf16 v[104:107], v[164:167], v[196:199], v[104:107]
	v_mfma_f32_16x16x32_bf16 v[104:107], v[168:171], v[200:203], v[104:107]
	v_mfma_f32_16x16x32_bf16 v[120:123], v[168:171], v[192:195], v[120:123]
	v_mfma_f32_16x16x32_bf16 v[120:123], v[164:167], v[188:191], v[120:123]
	s_setprio 0
	s_setprio 1
	v_mfma_f32_16x16x32_bf16 v[116:119], v[172:175], v[188:191], v[116:119]
	v_mfma_f32_16x16x32_bf16 v[116:119], v[176:179], v[192:195], v[116:119]
	v_mfma_f32_16x16x32_bf16 v[100:103], v[176:179], v[200:203], v[100:103]
	v_mfma_f32_16x16x32_bf16 v[100:103], v[172:175], v[196:199], v[100:103]
	v_mfma_f32_16x16x32_bf16 v[84:87], v[172:175], v[208:211], v[84:87]
	v_mfma_f32_16x16x32_bf16 v[84:87], v[176:179], v[212:215], v[84:87]
	v_mfma_f32_16x16x32_bf16 v[68:71], v[176:179], v[220:223], v[68:71]
	v_mfma_f32_16x16x32_bf16 v[68:71], v[172:175], v[216:219], v[68:71]
	v_mfma_f32_16x16x32_bf16 v[64:67], v[180:183], v[216:219], v[64:67]
	v_mfma_f32_16x16x32_bf16 v[64:67], v[184:187], v[220:223], v[64:67]
	v_mfma_f32_16x16x32_bf16 v[80:83], v[184:187], v[212:215], v[80:83]
	v_mfma_f32_16x16x32_bf16 v[80:83], v[180:183], v[208:211], v[80:83]
	v_mfma_f32_16x16x32_bf16 v[96:99], v[180:183], v[196:199], v[96:99]
	v_mfma_f32_16x16x32_bf16 v[96:99], v[184:187], v[200:203], v[96:99]
	v_mfma_f32_16x16x32_bf16 v[112:115], v[184:187], v[192:195], v[112:115]
	v_mfma_f32_16x16x32_bf16 v[112:115], v[180:183], v[188:191], v[112:115]
	s_setprio 0
	s_barrier
; #define PG8_STAGE(bufoff, gbase, voff) do { _Pragma("unroll") for (int _i = 0; _i < 2; ++_i) \
;         __builtin_amdgcn_global_load_lds((const unsigned*)((const char*)(gbase) + (voff)[_i]), (LAS unsigned*)(lds + (bufoff) + ldsw + _i * 8192), 16, 0, 0); } while (0)
; #define PG8_LDA(dst, b, h) do { _Pragma("unroll") for (int m = 0; m < 4; ++m) _Pragma("unroll") for (int k = 0; k < 2; ++k) dst[m][k] = *(const LAS bf16x8*)(lds + PG8_SA(b, h) + aoff + m * 2048 + k * 1024); } while (0)
; #define PG8_MMA(ai, bj, At, Bt) do { __builtin_amdgcn_s_setprio(1); _Pragma("unroll") for (int m = 0; m < 4; ++m) _Pragma("unroll") for (int n = 0; n < 2; ++n) _Pragma("unroll") for (int k = 0; k < 2; ++k) \
;         acc[ai][bj][m][n] = __builtin_amdgcn_mfma_f32_16x16x32_bf16(Bt[n][k], At[m][k], acc[ai][bj][m][n], 0, 0, 0); __builtin_amdgcn_s_setprio(0); } while (0)
; #define PG8_WAIT_V(n) asm volatile("s_waitcnt vmcnt(" #n ")" ::: "memory")
; #define PG8_WAIT_L(n) asm volatile("s_waitcnt lgkmcnt(" #n ")" ::: "memory")
; #define PG8_BAR __builtin_amdgcn_s_barrier()
; #define PG8_SCHED __builtin_amdgcn_sched_barrier(0)
; template <class Epi>
; __device__ __forceinline__ void gemm_phase(LAS unsigned char* lds, const Gemm g, const StaticOrder& S, const Epi& E) {
;     ...
;             PG8_LDA(At, 1, 1); PG8_STAGE(PG8_SB(1, 0), b3, voffB); PG8_STAGE(PG8_SB(1, 1), b3 + hstepB, voffB); PG8_STAGE(PG8_SA(1, 0), a3, voffA);
;             PG8_WAIT_V(8); PG8_WAIT_L(0); PG8_BAR; PG8_MMA(1, 0, At, B0); PG8_MMA(1, 1, At, B1); PG8_BAR; PG8_SCHED;
	s_add_i32 s0, s50, s28
	v_lshl_add_u64 v[224:225], v[224:225], 0, s[14:15]
	s_mov_b32 m0, s0
	ds_read_b128 v[188:191], v154 offset:49152
	ds_read_b128 v[192:195], v154 offset:50176
	ds_read_b128 v[196:199], v154 offset:51200
	ds_read_b128 v[200:203], v154 offset:52224
	ds_read_b128 v[208:211], v154 offset:53248
	ds_read_b128 v[212:215], v154 offset:54272
	ds_read_b128 v[216:219], v154 offset:55296
	ds_read_b128 v[220:223], v154 offset:56320
	global_load_lds_dwordx4 v[224:225], off
	s_add_i32 m0, s0, 0x2000
	s_add_u32 s0, s22, 0x18080
	v_lshl_add_u64 v[224:225], v[226:227], 0, s[14:15]
	s_addc_u32 s1, s23, 0
	s_add_i32 s22, s51, s28
	global_load_lds_dwordx4 v[224:225], off
	v_lshl_add_u64 v[224:225], s[0:1], 0, v[130:131]
	s_mov_b32 m0, s22
	s_nop 0
	global_load_lds_dwordx4 v[224:225], off
	v_lshl_add_u64 v[224:225], s[0:1], 0, v[134:135]
	s_add_i32 m0, s22, 0x2000
	s_nop 0
	global_load_lds_dwordx4 v[224:225], off
	v_lshl_add_u64 v[224:225], v[230:231], 0, s[14:15]
	s_mov_b32 m0, s38
	s_nop 0
	global_load_lds_dwordx4 v[224:225], off
	v_lshl_add_u64 v[224:225], v[232:233], 0, s[14:15]
	s_mov_b32 m0, s39
	s_nop 0
	global_load_lds_dwordx4 v[224:225], off
	s_waitcnt vmcnt(8)
	s_waitcnt lgkmcnt(0)
	s_barrier
	s_setprio 1
	s_waitcnt lgkmcnt(0)
	v_mfma_f32_16x16x32_bf16 v[60:63], v[156:159], v[188:191], v[60:63]
	v_mfma_f32_16x16x32_bf16 v[60:63], v[160:163], v[192:195], v[60:63]
	v_mfma_f32_16x16x32_bf16 v[44:47], v[160:163], v[200:203], v[44:47]
	v_mfma_f32_16x16x32_bf16 v[44:47], v[156:159], v[196:199], v[44:47]
	v_mfma_f32_16x16x32_bf16 v[28:31], v[156:159], v[208:211], v[28:31]
	v_mfma_f32_16x16x32_bf16 v[28:31], v[160:163], v[212:215], v[28:31]
	v_mfma_f32_16x16x32_bf16 v[12:15], v[160:163], v[220:223], v[12:15]
	v_mfma_f32_16x16x32_bf16 v[12:15], v[156:159], v[216:219], v[12:15]
	v_mfma_f32_16x16x32_bf16 v[8:11], v[164:167], v[216:219], v[8:11]
	v_mfma_f32_16x16x32_bf16 v[8:11], v[168:171], v[220:223], v[8:11]
	v_mfma_f32_16x16x32_bf16 v[24:27], v[168:171], v[212:215], v[24:27]
	v_mfma_f32_16x16x32_bf16 v[24:27], v[164:167], v[208:211], v[24:27]
	v_mfma_f32_16x16x32_bf16 v[40:43], v[164:167], v[196:199], v[40:43]
	v_mfma_f32_16x16x32_bf16 v[40:43], v[168:171], v[200:203], v[40:43]
	v_mfma_f32_16x16x32_bf16 v[56:59], v[168:171], v[192:195], v[56:59]
	v_mfma_f32_16x16x32_bf16 v[56:59], v[164:167], v[188:191], v[56:59]
	s_setprio 0
	s_setprio 1
	v_mfma_f32_16x16x32_bf16 v[52:55], v[172:175], v[188:191], v[52:55]
	v_mfma_f32_16x16x32_bf16 v[52:55], v[176:179], v[192:195], v[52:55]
	v_mfma_f32_16x16x32_bf16 v[36:39], v[176:179], v[200:203], v[36:39]
	v_mfma_f32_16x16x32_bf16 v[36:39], v[172:175], v[196:199], v[36:39]
	v_mfma_f32_16x16x32_bf16 v[20:23], v[172:175], v[208:211], v[20:23]
	v_mfma_f32_16x16x32_bf16 v[20:23], v[176:179], v[212:215], v[20:23]
	v_mfma_f32_16x16x32_bf16 v[4:7], v[176:179], v[220:223], v[4:7]
	v_mfma_f32_16x16x32_bf16 v[4:7], v[172:175], v[216:219], v[4:7]
	v_mfma_f32_16x16x32_bf16 v[0:3], v[180:183], v[216:219], v[0:3]
	v_mfma_f32_16x16x32_bf16 v[0:3], v[184:187], v[220:223], v[0:3]
	v_mfma_f32_16x16x32_bf16 v[16:19], v[184:187], v[212:215], v[16:19]
	v_mfma_f32_16x16x32_bf16 v[16:19], v[180:183], v[208:211], v[16:19]
	v_mfma_f32_16x16x32_bf16 v[32:35], v[180:183], v[196:199], v[32:35]
	v_mfma_f32_16x16x32_bf16 v[32:35], v[184:187], v[200:203], v[32:35]
	v_mfma_f32_16x16x32_bf16 v[48:51], v[184:187], v[192:195], v[48:51]
	v_mfma_f32_16x16x32_bf16 v[48:51], v[180:183], v[188:191], v[48:51]
	s_setprio 0
	s_barrier
	s_add_u32 s47, s47, 0x100
	s_addc_u32 s48, s48, 0
	s_cmp_ge_i32 s49, s36
	s_mov_b64 s[0:1], s[4:5]
	s_mov_b32 s22, s49
	s_cbranch_scc0 .LBB0_834

; #define PG8_STAGE(bufoff, gbase, voff) do { _Pragma("unroll") for (int _i = 0; _i < 2; ++_i) \
;         __builtin_amdgcn_global_load_lds((const unsigned*)((const char*)(gbase) + (voff)[_i]), (LAS unsigned*)(lds + (bufoff) + ldsw + _i * 8192), 16, 0, 0); } while (0)
; #define PG8_LDA(dst, b, h) do { _Pragma("unroll") for (int m = 0; m < 4; ++m) _Pragma("unroll") for (int k = 0; k < 2; ++k) dst[m][k] = *(const LAS bf16x8*)(lds + PG8_SA(b, h) + aoff + m * 2048 + k * 1024); } while (0)
; #define PG8_LDB(dst, b, h) do { _Pragma("unroll") for (int n = 0; n < 2; ++n) _Pragma("unroll") for (int k = 0; k < 2; ++k) dst[n][k] = *(const LAS bf16x8*)(lds + PG8_SB(b, h) + boff + n * 2048 + k * 1024); } while (0)
; #define PG8_MMA(ai, bj, At, Bt) do { __builtin_amdgcn_s_setprio(1); _Pragma("unroll") for (int m = 0; m < 4; ++m) _Pragma("unroll") for (int n = 0; n < 2; ++n) _Pragma("unroll") for (int k = 0; k < 2; ++k) \
;         acc[ai][bj][m][n] = __builtin_amdgcn_mfma_f32_16x16x32_bf16(Bt[n][k], At[m][k], acc[ai][bj][m][n], 0, 0, 0); __builtin_amdgcn_s_setprio(0); } while (0)
; #define PG8_WAIT_V(n) asm volatile("s_waitcnt vmcnt(" #n ")" ::: "memory")
; #define PG8_WAIT_L(n) asm volatile("s_waitcnt lgkmcnt(" #n ")" ::: "memory")
; #define PG8_BAR __builtin_amdgcn_s_barrier()
; #define PG8_SCHED __builtin_amdgcn_sched_barrier(0)
; template <class Epi>
; __device__ __forceinline__ void gemm_phase(LAS unsigned char* lds, const Gemm g, const StaticOrder& S, const Epi& E) {
;     ...
;             const bool last = (t == nt - 2);
;             const char* a1 = cA + (size_t)(t + 1) * kstep;
;             const char* a2 = last ? nA : cA + (size_t)(t + 2) * kstep; const char* b2 = last ? nB : cB + (size_t)(t + 2) * kstep;
;             const char* a3 = a2 + kstep; const char* b3 = b2 + kstep;
;             PG8_LDB(B0, 0, 0); PG8_LDB(B1, 0, 1); PG8_SCHED; PG8_LDA(At, 0, 0); PG8_STAGE(PG8_SA(1, 1), a1 + hstepA, voffA);
;             PG8_WAIT_V(8); PG8_WAIT_L(0); PG8_BAR; PG8_MMA(0, 0, At, B0); PG8_MMA(0, 1, At, B1); PG8_BAR; PG8_SCHED;
;             PG8_LDA(At, 0, 1); PG8_STAGE(PG8_SB(0, 0), b2, voffB); PG8_STAGE(PG8_SB(0, 1), b2 + hstepB, voffB); PG8_STAGE(PG8_SA(0, 0), a2, voffA);
;             PG8_WAIT_V(8); PG8_WAIT_L(0); PG8_BAR; PG8_MMA(1, 0, At, B0); PG8_MMA(1, 1, At, B1); PG8_BAR; PG8_SCHED;
.LBB0_912:
	ds_read_b128 v[96:99], v230
	ds_read_b128 v[100:103], v230 offset:1024
	ds_read_b128 v[104:107], v230 offset:2048
	ds_read_b128 v[116:119], v230 offset:3072
	ds_read_b128 v[120:123], v231
	ds_read_b128 v[124:127], v231 offset:1024
	ds_read_b128 v[136:139], v231 offset:2048
	ds_read_b128 v[148:151], v231 offset:3072
	s_add_i32 s56, s24, 2
	s_add_u32 s25, s4, 0xfffc0080
	s_addc_u32 s26, s5, -1
	s_cmp_eq_u32 s44, s24
	s_cselect_b32 s24, s53, s54
	s_cselect_b32 s27, s17, s26
	s_cselect_b32 s26, s19, s25
	s_cselect_b32 s25, s33, s55
	v_lshl_add_u64 v[192:193], s[4:5], 0, v[220:221]
	s_add_i32 m0, s31, 0xc000
	ds_read_b128 v[160:163], v232
	ds_read_b128 v[164:167], v232 offset:1024
	ds_read_b128 v[168:171], v232 offset:2048
	ds_read_b128 v[172:175], v232 offset:3072
	ds_read_b128 v[176:179], v232 offset:4096
	ds_read_b128 v[180:183], v232 offset:5120
	ds_read_b128 v[184:187], v232 offset:6144
	ds_read_b128 v[188:191], v232 offset:7168
	global_load_lds_dwordx4 v[192:193], off
	v_lshl_add_u64 v[192:193], s[4:5], 0, v[222:223]
	s_add_i32 m0, s31, 0xe000
	s_nop 0
	global_load_lds_dwordx4 v[192:193], off
	s_waitcnt vmcnt(8)
	s_waitcnt lgkmcnt(0)
	s_barrier
	s_setprio 1
	s_waitcnt lgkmcnt(0)
	v_mfma_f32_16x16x32_bf16 v[156:159], v[96:99], v[160:163], v[156:159]
	v_mfma_f32_16x16x32_bf16 v[156:159], v[100:103], v[164:167], v[156:159]
	v_mfma_f32_16x16x32_bf16 v[132:135], v[100:103], v[172:175], v[132:135]
	v_mfma_f32_16x16x32_bf16 v[132:135], v[96:99], v[168:171], v[132:135]
	v_mfma_f32_16x16x32_bf16 v[92:95], v[96:99], v[176:179], v[92:95]
	v_mfma_f32_16x16x32_bf16 v[92:95], v[100:103], v[180:183], v[92:95]
	v_mfma_f32_16x16x32_bf16 v[76:79], v[100:103], v[188:191], v[76:79]
	v_mfma_f32_16x16x32_bf16 v[76:79], v[96:99], v[184:187], v[76:79]
	v_mfma_f32_16x16x32_bf16 v[72:75], v[104:107], v[184:187], v[72:75]
	v_mfma_f32_16x16x32_bf16 v[72:75], v[116:119], v[188:191], v[72:75]
	v_mfma_f32_16x16x32_bf16 v[88:91], v[116:119], v[180:183], v[88:91]
	v_mfma_f32_16x16x32_bf16 v[88:91], v[104:107], v[176:179], v[88:91]
	v_mfma_f32_16x16x32_bf16 v[128:131], v[104:107], v[168:171], v[128:131]
	v_mfma_f32_16x16x32_bf16 v[128:131], v[116:119], v[172:175], v[128:131]
	v_mfma_f32_16x16x32_bf16 v[152:155], v[116:119], v[164:167], v[152:155]
	v_mfma_f32_16x16x32_bf16 v[152:155], v[104:107], v[160:163], v[152:155]
	s_setprio 0
	s_setprio 1
	v_mfma_f32_16x16x32_bf16 v[144:147], v[120:123], v[160:163], v[144:147]
	v_mfma_f32_16x16x32_bf16 v[144:147], v[124:127], v[164:167], v[144:147]
	v_mfma_f32_16x16x32_bf16 v[112:115], v[124:127], v[172:175], v[112:115]
	v_mfma_f32_16x16x32_bf16 v[112:115], v[120:123], v[168:171], v[112:115]
	v_mfma_f32_16x16x32_bf16 v[84:87], v[120:123], v[176:179], v[84:87]
	v_mfma_f32_16x16x32_bf16 v[84:87], v[124:127], v[180:183], v[84:87]
	v_mfma_f32_16x16x32_bf16 v[68:71], v[124:127], v[188:191], v[68:71]
	v_mfma_f32_16x16x32_bf16 v[68:71], v[120:123], v[184:187], v[68:71]
	v_mfma_f32_16x16x32_bf16 v[64:67], v[136:139], v[184:187], v[64:67]
	v_mfma_f32_16x16x32_bf16 v[64:67], v[148:151], v[188:191], v[64:67]
	v_mfma_f32_16x16x32_bf16 v[80:83], v[148:151], v[180:183], v[80:83]
	v_mfma_f32_16x16x32_bf16 v[80:83], v[136:139], v[176:179], v[80:83]
	v_mfma_f32_16x16x32_bf16 v[108:111], v[136:139], v[168:171], v[108:111]
	v_mfma_f32_16x16x32_bf16 v[108:111], v[148:151], v[172:175], v[108:111]
	v_mfma_f32_16x16x32_bf16 v[140:143], v[148:151], v[164:167], v[140:143]
	v_mfma_f32_16x16x32_bf16 v[140:143], v[136:139], v[160:163], v[140:143]
	s_setprio 0
	s_barrier
	s_add_i32 s57, s47, s30
	v_lshl_add_u64 v[192:193], s[24:25], 0, v[210:211]
	s_mov_b32 m0, s57
	ds_read_b128 v[160:163], v232 offset:16384
	ds_read_b128 v[164:167], v232 offset:17408
	ds_read_b128 v[168:171], v232 offset:18432
	ds_read_b128 v[172:175], v232 offset:19456
	ds_read_b128 v[176:179], v232 offset:20480
	ds_read_b128 v[180:183], v232 offset:21504
	ds_read_b128 v[184:187], v232 offset:22528
	ds_read_b128 v[188:191], v232 offset:23552
	global_load_lds_dwordx4 v[192:193], off
	s_add_i32 m0, s57, 0x2000
	s_add_u32 s58, s24, 0x40000
	v_lshl_add_u64 v[194:195], s[24:25], 0, v[214:215]
	s_addc_u32 s59, s25, 0
	s_add_i32 s57, s48, s30
	global_load_lds_dwordx4 v[194:195], off
	v_lshl_add_u64 v[196:197], s[58:59], 0, v[210:211]
	s_mov_b32 m0, s57
	v_lshl_add_u64 v[198:199], s[26:27], 0, v[212:213]
	global_load_lds_dwordx4 v[196:197], off
	v_lshl_add_u64 v[196:197], s[58:59], 0, v[214:215]
	s_add_i32 m0, s57, 0x2000
	s_nop 0
	global_load_lds_dwordx4 v[196:197], off
	v_lshl_add_u64 v[196:197], s[26:27], 0, v[208:209]
	s_mov_b32 m0, s31
	s_nop 0
	global_load_lds_dwordx4 v[196:197], off
	s_mov_b32 m0, s34
	s_nop 0
	global_load_lds_dwordx4 v[198:199], off
	s_waitcnt vmcnt(8)
	s_waitcnt lgkmcnt(0)
	s_barrier
; #define PG8_STAGE(bufoff, gbase, voff) do { _Pragma("unroll") for (int _i = 0; _i < 2; ++_i) \
;         __builtin_amdgcn_global_load_lds((const unsigned*)((const char*)(gbase) + (voff)[_i]), (LAS unsigned*)(lds + (bufoff) + ldsw + _i * 8192), 16, 0, 0); } while (0)
; #define PG8_LDA(dst, b, h) do { _Pragma("unroll") for (int m = 0; m < 4; ++m) _Pragma("unroll") for (int k = 0; k < 2; ++k) dst[m][k] = *(const LAS bf16x8*)(lds + PG8_SA(b, h) + aoff + m * 2048 + k * 1024); } while (0)
; #define PG8_LDB(dst, b, h) do { _Pragma("unroll") for (int n = 0; n < 2; ++n) _Pragma("unroll") for (int k = 0; k < 2; ++k) dst[n][k] = *(const LAS bf16x8*)(lds + PG8_SB(b, h) + boff + n * 2048 + k * 1024); } while (0)
; #define PG8_MMA(ai, bj, At, Bt) do { __builtin_amdgcn_s_setprio(1); _Pragma("unroll") for (int m = 0; m < 4; ++m) _Pragma("unroll") for (int n = 0; n < 2; ++n) _Pragma("unroll") for (int k = 0; k < 2; ++k) \
;         acc[ai][bj][m][n] = __builtin_amdgcn_mfma_f32_16x16x32_bf16(Bt[n][k], At[m][k], acc[ai][bj][m][n], 0, 0, 0); __builtin_amdgcn_s_setprio(0); } while (0)
; #define PG8_WAIT_V(n) asm volatile("s_waitcnt vmcnt(" #n ")" ::: "memory")
; #define PG8_WAIT_L(n) asm volatile("s_waitcnt lgkmcnt(" #n ")" ::: "memory")
; #define PG8_BAR __builtin_amdgcn_s_barrier()
; #define PG8_SCHED __builtin_amdgcn_sched_barrier(0)
; template <class Epi>
; __device__ __forceinline__ void gemm_phase(LAS unsigned char* lds, const Gemm g, const StaticOrder& S, const Epi& E) {
;     ...
;             PG8_WAIT_V(8); PG8_WAIT_L(0); PG8_BAR; PG8_MMA(1, 0, At, B0); PG8_MMA(1, 1, At, B1); PG8_BAR; PG8_SCHED;
;             PG8_LDB(B0, 1, 0); PG8_LDB(B1, 1, 1); PG8_SCHED; PG8_LDA(At, 1, 0); PG8_STAGE(PG8_SA(0, 1), a2 + hstepA, voffA);
;             PG8_WAIT_V(8); PG8_WAIT_L(0); PG8_BAR; PG8_MMA(0, 0, At, B0); PG8_MMA(0, 1, At, B1); PG8_BAR; PG8_SCHED;
	s_setprio 1
	s_waitcnt lgkmcnt(0)
	v_mfma_f32_16x16x32_bf16 v[60:63], v[96:99], v[160:163], v[60:63]
	v_mfma_f32_16x16x32_bf16 v[60:63], v[100:103], v[164:167], v[60:63]
	v_mfma_f32_16x16x32_bf16 v[44:47], v[100:103], v[172:175], v[44:47]
	v_mfma_f32_16x16x32_bf16 v[44:47], v[96:99], v[168:171], v[44:47]
	v_mfma_f32_16x16x32_bf16 v[28:31], v[96:99], v[176:179], v[28:31]
	v_mfma_f32_16x16x32_bf16 v[28:31], v[100:103], v[180:183], v[28:31]
	v_mfma_f32_16x16x32_bf16 v[12:15], v[100:103], v[188:191], v[12:15]
	v_mfma_f32_16x16x32_bf16 v[12:15], v[96:99], v[184:187], v[12:15]
	v_mfma_f32_16x16x32_bf16 v[8:11], v[104:107], v[184:187], v[8:11]
	v_mfma_f32_16x16x32_bf16 v[8:11], v[116:119], v[188:191], v[8:11]
	v_mfma_f32_16x16x32_bf16 v[24:27], v[116:119], v[180:183], v[24:27]
	v_mfma_f32_16x16x32_bf16 v[24:27], v[104:107], v[176:179], v[24:27]
	v_mfma_f32_16x16x32_bf16 v[40:43], v[104:107], v[168:171], v[40:43]
	v_mfma_f32_16x16x32_bf16 v[40:43], v[116:119], v[172:175], v[40:43]
	v_mfma_f32_16x16x32_bf16 v[56:59], v[116:119], v[164:167], v[56:59]
	v_mfma_f32_16x16x32_bf16 v[56:59], v[104:107], v[160:163], v[56:59]
	s_setprio 0
	s_setprio 1
	v_mfma_f32_16x16x32_bf16 v[52:55], v[120:123], v[160:163], v[52:55]
	v_mfma_f32_16x16x32_bf16 v[52:55], v[124:127], v[164:167], v[52:55]
	v_mfma_f32_16x16x32_bf16 v[36:39], v[124:127], v[172:175], v[36:39]
	v_mfma_f32_16x16x32_bf16 v[36:39], v[120:123], v[168:171], v[36:39]
	v_mfma_f32_16x16x32_bf16 v[20:23], v[120:123], v[176:179], v[20:23]
	v_mfma_f32_16x16x32_bf16 v[20:23], v[124:127], v[180:183], v[20:23]
	v_mfma_f32_16x16x32_bf16 v[4:7], v[124:127], v[188:191], v[4:7]
	v_mfma_f32_16x16x32_bf16 v[4:7], v[120:123], v[184:187], v[4:7]
	v_mfma_f32_16x16x32_bf16 v[0:3], v[136:139], v[184:187], v[0:3]
	v_mfma_f32_16x16x32_bf16 v[0:3], v[148:151], v[188:191], v[0:3]
	v_mfma_f32_16x16x32_bf16 v[16:19], v[148:151], v[180:183], v[16:19]
	v_mfma_f32_16x16x32_bf16 v[16:19], v[136:139], v[176:179], v[16:19]
	v_mfma_f32_16x16x32_bf16 v[32:35], v[136:139], v[168:171], v[32:35]
	v_mfma_f32_16x16x32_bf16 v[32:35], v[148:151], v[172:175], v[32:35]
	v_mfma_f32_16x16x32_bf16 v[48:51], v[148:151], v[164:167], v[48:51]
	v_mfma_f32_16x16x32_bf16 v[48:51], v[136:139], v[160:163], v[48:51]
	s_setprio 0
	s_barrier
	s_add_i32 s57, 0, 0x18000
	s_add_i32 s58, 0, 0x1c000
	v_add_u32_e32 v116, s57, v229
	v_add_u32_e32 v148, s58, v229
	ds_read_b128 v[96:99], v116
	ds_read_b128 v[100:103], v116 offset:1024
	ds_read_b128 v[104:107], v116 offset:2048
	ds_read_b128 v[116:119], v116 offset:3072
	ds_read_b128 v[120:123], v148
	ds_read_b128 v[124:127], v148 offset:1024
	ds_read_b128 v[136:139], v148 offset:2048
	ds_read_b128 v[148:151], v148 offset:3072
	s_add_u32 s26, s26, 0x40000
	s_addc_u32 s27, s27, 0
	s_mov_b32 m0, s35
	v_lshl_add_u64 v[200:201], s[26:27], 0, v[208:209]
	ds_read_b128 v[160:163], v232 offset:32768
	ds_read_b128 v[164:167], v232 offset:33792
	ds_read_b128 v[168:171], v232 offset:34816
	ds_read_b128 v[172:175], v232 offset:35840
	ds_read_b128 v[176:179], v232 offset:36864
	ds_read_b128 v[180:183], v232 offset:37888
	ds_read_b128 v[184:187], v232 offset:38912
	ds_read_b128 v[188:191], v232 offset:39936
	global_load_lds_dwordx4 v[200:201], off
	v_lshl_add_u64 v[200:201], s[26:27], 0, v[212:213]
	s_mov_b32 m0, s36
	s_nop 0
	global_load_lds_dwordx4 v[200:201], off
	s_waitcnt vmcnt(8)
	s_waitcnt lgkmcnt(0)
	s_barrier
	s_setprio 1
	s_waitcnt lgkmcnt(0)
	v_mfma_f32_16x16x32_bf16 v[156:159], v[96:99], v[160:163], v[156:159]
	v_mfma_f32_16x16x32_bf16 v[156:159], v[100:103], v[164:167], v[156:159]
	v_mfma_f32_16x16x32_bf16 v[132:135], v[100:103], v[172:175], v[132:135]
	v_mfma_f32_16x16x32_bf16 v[132:135], v[96:99], v[168:171], v[132:135]
	v_mfma_f32_16x16x32_bf16 v[92:95], v[96:99], v[176:179], v[92:95]
	v_mfma_f32_16x16x32_bf16 v[92:95], v[100:103], v[180:183], v[92:95]
	v_mfma_f32_16x16x32_bf16 v[76:79], v[100:103], v[188:191], v[76:79]
	v_mfma_f32_16x16x32_bf16 v[76:79], v[96:99], v[184:187], v[76:79]
	v_mfma_f32_16x16x32_bf16 v[72:75], v[104:107], v[184:187], v[72:75]
	v_mfma_f32_16x16x32_bf16 v[72:75], v[116:119], v[188:191], v[72:75]
	v_mfma_f32_16x16x32_bf16 v[88:91], v[116:119], v[180:183], v[88:91]
	v_mfma_f32_16x16x32_bf16 v[88:91], v[104:107], v[176:179], v[88:91]
	v_mfma_f32_16x16x32_bf16 v[128:131], v[104:107], v[168:171], v[128:131]
	v_mfma_f32_16x16x32_bf16 v[128:131], v[116:119], v[172:175], v[128:131]
	v_mfma_f32_16x16x32_bf16 v[152:155], v[116:119], v[164:167], v[152:155]
	v_mfma_f32_16x16x32_bf16 v[152:155], v[104:107], v[160:163], v[152:155]
	s_setprio 0
	s_setprio 1
	v_mfma_f32_16x16x32_bf16 v[144:147], v[120:123], v[160:163], v[144:147]
	v_mfma_f32_16x16x32_bf16 v[144:147], v[124:127], v[164:167], v[144:147]
	v_mfma_f32_16x16x32_bf16 v[112:115], v[124:127], v[172:175], v[112:115]
	v_mfma_f32_16x16x32_bf16 v[112:115], v[120:123], v[168:171], v[112:115]
	v_mfma_f32_16x16x32_bf16 v[84:87], v[120:123], v[176:179], v[84:87]
	v_mfma_f32_16x16x32_bf16 v[84:87], v[124:127], v[180:183], v[84:87]
	v_mfma_f32_16x16x32_bf16 v[68:71], v[124:127], v[188:191], v[68:71]
	v_mfma_f32_16x16x32_bf16 v[68:71], v[120:123], v[184:187], v[68:71]
	v_mfma_f32_16x16x32_bf16 v[64:67], v[136:139], v[184:187], v[64:67]
	v_mfma_f32_16x16x32_bf16 v[64:67], v[148:151], v[188:191], v[64:67]
	v_mfma_f32_16x16x32_bf16 v[80:83], v[148:151], v[180:183], v[80:83]
	v_mfma_f32_16x16x32_bf16 v[80:83], v[136:139], v[176:179], v[80:83]
	v_mfma_f32_16x16x32_bf16 v[108:111], v[136:139], v[168:171], v[108:111]
	v_mfma_f32_16x16x32_bf16 v[108:111], v[148:151], v[172:175], v[108:111]
	v_mfma_f32_16x16x32_bf16 v[140:143], v[148:151], v[164:167], v[140:143]
	v_mfma_f32_16x16x32_bf16 v[140:143], v[136:139], v[160:163], v[140:143]
	s_setprio 0
	s_barrier
; #define PG8_STAGE(bufoff, gbase, voff) do { _Pragma("unroll") for (int _i = 0; _i < 2; ++_i) \
;         __builtin_amdgcn_global_load_lds((const unsigned*)((const char*)(gbase) + (voff)[_i]), (LAS unsigned*)(lds + (bufoff) + ldsw + _i * 8192), 16, 0, 0); } while (0)
; #define PG8_LDA(dst, b, h) do { _Pragma("unroll") for (int m = 0; m < 4; ++m) _Pragma("unroll") for (int k = 0; k < 2; ++k) dst[m][k] = *(const LAS bf16x8*)(lds + PG8_SA(b, h) + aoff + m * 2048 + k * 1024); } while (0)
; #define PG8_MMA(ai, bj, At, Bt) do { __builtin_amdgcn_s_setprio(1); _Pragma("unroll") for (int m = 0; m < 4; ++m) _Pragma("unroll") for (int n = 0; n < 2; ++n) _Pragma("unroll") for (int k = 0; k < 2; ++k) \
;         acc[ai][bj][m][n] = __builtin_amdgcn_mfma_f32_16x16x32_bf16(Bt[n][k], At[m][k], acc[ai][bj][m][n], 0, 0, 0); __builtin_amdgcn_s_setprio(0); } while (0)
; #define PG8_WAIT_V(n) asm volatile("s_waitcnt vmcnt(" #n ")" ::: "memory")
; #define PG8_WAIT_L(n) asm volatile("s_waitcnt lgkmcnt(" #n ")" ::: "memory")
; #define PG8_BAR __builtin_amdgcn_s_barrier()
; #define PG8_SCHED __builtin_amdgcn_sched_barrier(0)
; template <class Epi>
; __device__ __forceinline__ void gemm_phase(LAS unsigned char* lds, const Gemm g, const StaticOrder& S, const Epi& E) {
;     ...
;             PG8_LDA(At, 1, 1); PG8_STAGE(PG8_SB(1, 0), b3, voffB); PG8_STAGE(PG8_SB(1, 1), b3 + hstepB, voffB); PG8_STAGE(PG8_SA(1, 0), a3, voffA);
;             PG8_WAIT_V(8); PG8_WAIT_L(0); PG8_BAR; PG8_MMA(1, 0, At, B0); PG8_MMA(1, 1, At, B1); PG8_BAR; PG8_SCHED;
	s_add_i32 s26, s57, s30
	v_lshl_add_u64 v[192:193], v[192:193], 0, s[10:11]
	s_mov_b32 m0, s26
	ds_read_b128 v[160:163], v232 offset:49152
	ds_read_b128 v[164:167], v232 offset:50176
	ds_read_b128 v[168:171], v232 offset:51200
	ds_read_b128 v[172:175], v232 offset:52224
	ds_read_b128 v[176:179], v232 offset:53248
	ds_read_b128 v[180:183], v232 offset:54272
	ds_read_b128 v[184:187], v232 offset:55296
	ds_read_b128 v[188:191], v232 offset:56320
	global_load_lds_dwordx4 v[192:193], off
	s_add_i32 m0, s26, 0x2000
	s_add_u32 s24, s24, 0x40080
	v_lshl_add_u64 v[192:193], v[194:195], 0, s[10:11]
	s_addc_u32 s25, s25, 0
	s_add_i32 s26, s58, s30
	global_load_lds_dwordx4 v[192:193], off
	v_lshl_add_u64 v[192:193], s[24:25], 0, v[210:211]
	s_mov_b32 m0, s26
	s_nop 0
	global_load_lds_dwordx4 v[192:193], off
	v_lshl_add_u64 v[192:193], s[24:25], 0, v[214:215]
	s_add_i32 m0, s26, 0x2000
	s_nop 0
	global_load_lds_dwordx4 v[192:193], off
	v_lshl_add_u64 v[192:193], v[196:197], 0, s[10:11]
	s_mov_b32 m0, s40
	s_nop 0
	global_load_lds_dwordx4 v[192:193], off
	v_lshl_add_u64 v[192:193], v[198:199], 0, s[10:11]
	s_mov_b32 m0, s41
	s_nop 0
	global_load_lds_dwordx4 v[192:193], off
	s_waitcnt vmcnt(8)
	s_waitcnt lgkmcnt(0)
	s_barrier
	s_setprio 1
	s_waitcnt lgkmcnt(0)
	v_mfma_f32_16x16x32_bf16 v[60:63], v[96:99], v[160:163], v[60:63]
	v_mfma_f32_16x16x32_bf16 v[60:63], v[100:103], v[164:167], v[60:63]
	v_mfma_f32_16x16x32_bf16 v[44:47], v[100:103], v[172:175], v[44:47]
	v_mfma_f32_16x16x32_bf16 v[44:47], v[96:99], v[168:171], v[44:47]
	v_mfma_f32_16x16x32_bf16 v[28:31], v[96:99], v[176:179], v[28:31]
	v_mfma_f32_16x16x32_bf16 v[28:31], v[100:103], v[180:183], v[28:31]
	v_mfma_f32_16x16x32_bf16 v[12:15], v[100:103], v[188:191], v[12:15]
	v_mfma_f32_16x16x32_bf16 v[12:15], v[96:99], v[184:187], v[12:15]
	v_mfma_f32_16x16x32_bf16 v[8:11], v[104:107], v[184:187], v[8:11]
	v_mfma_f32_16x16x32_bf16 v[8:11], v[116:119], v[188:191], v[8:11]
	v_mfma_f32_16x16x32_bf16 v[24:27], v[116:119], v[180:183], v[24:27]
	v_mfma_f32_16x16x32_bf16 v[24:27], v[104:107], v[176:179], v[24:27]
	v_mfma_f32_16x16x32_bf16 v[40:43], v[104:107], v[168:171], v[40:43]
	v_mfma_f32_16x16x32_bf16 v[40:43], v[116:119], v[172:175], v[40:43]
	v_mfma_f32_16x16x32_bf16 v[56:59], v[116:119], v[164:167], v[56:59]
	v_mfma_f32_16x16x32_bf16 v[56:59], v[104:107], v[160:163], v[56:59]
	s_setprio 0
	s_setprio 1
	v_mfma_f32_16x16x32_bf16 v[52:55], v[120:123], v[160:163], v[52:55]
	v_mfma_f32_16x16x32_bf16 v[52:55], v[124:127], v[164:167], v[52:55]
	v_mfma_f32_16x16x32_bf16 v[36:39], v[124:127], v[172:175], v[36:39]
	v_mfma_f32_16x16x32_bf16 v[36:39], v[120:123], v[168:171], v[36:39]
	v_mfma_f32_16x16x32_bf16 v[20:23], v[120:123], v[176:179], v[20:23]
	v_mfma_f32_16x16x32_bf16 v[20:23], v[124:127], v[180:183], v[20:23]
	v_mfma_f32_16x16x32_bf16 v[4:7], v[124:127], v[188:191], v[4:7]
	v_mfma_f32_16x16x32_bf16 v[4:7], v[120:123], v[184:187], v[4:7]
	v_mfma_f32_16x16x32_bf16 v[0:3], v[136:139], v[184:187], v[0:3]
	v_mfma_f32_16x16x32_bf16 v[0:3], v[148:151], v[188:191], v[0:3]
	v_mfma_f32_16x16x32_bf16 v[16:19], v[148:151], v[180:183], v[16:19]
	v_mfma_f32_16x16x32_bf16 v[16:19], v[136:139], v[176:179], v[16:19]
	v_mfma_f32_16x16x32_bf16 v[32:35], v[136:139], v[168:171], v[32:35]
	v_mfma_f32_16x16x32_bf16 v[32:35], v[148:151], v[172:175], v[32:35]
	v_mfma_f32_16x16x32_bf16 v[48:51], v[148:151], v[164:167], v[48:51]
	v_mfma_f32_16x16x32_bf16 v[48:51], v[136:139], v[160:163], v[48:51]
	s_setprio 0
	s_barrier
	s_add_u32 s4, s4, 0x100
	s_addc_u32 s5, s5, 0
	s_add_u32 s54, s54, 0x100
	s_addc_u32 s55, s55, 0
	s_cmp_ge_i32 s56, s39
	s_mov_b32 s24, s56
	s_cbranch_scc0 .LBB0_912

; #define PG8_STAGE(bufoff, gbase, voff) do { _Pragma("unroll") for (int _i = 0; _i < 2; ++_i) \
;         __builtin_amdgcn_global_load_lds((const unsigned*)((const char*)(gbase) + (voff)[_i]), (LAS unsigned*)(lds + (bufoff) + ldsw + _i * 8192), 16, 0, 0); } while (0)
; #define PG8_LDA(dst, b, h) do { _Pragma("unroll") for (int m = 0; m < 4; ++m) _Pragma("unroll") for (int k = 0; k < 2; ++k) dst[m][k] = *(const LAS bf16x8*)(lds + PG8_SA(b, h) + aoff + m * 2048 + k * 1024); } while (0)
; #define PG8_LDB(dst, b, h) do { _Pragma("unroll") for (int n = 0; n < 2; ++n) _Pragma("unroll") for (int k = 0; k < 2; ++k) dst[n][k] = *(const LAS bf16x8*)(lds + PG8_SB(b, h) + boff + n * 2048 + k * 1024); } while (0)
; #define PG8_MMA(ai, bj, At, Bt) do { __builtin_amdgcn_s_setprio(1); _Pragma("unroll") for (int m = 0; m < 4; ++m) _Pragma("unroll") for (int n = 0; n < 2; ++n) _Pragma("unroll") for (int k = 0; k < 2; ++k) \
;         acc[ai][bj][m][n] = __builtin_amdgcn_mfma_f32_16x16x32_bf16(Bt[n][k], At[m][k], acc[ai][bj][m][n], 0, 0, 0); __builtin_amdgcn_s_setprio(0); } while (0)
; #define PG8_WAIT_V(n) asm volatile("s_waitcnt vmcnt(" #n ")" ::: "memory")
; #define PG8_WAIT_L(n) asm volatile("s_waitcnt lgkmcnt(" #n ")" ::: "memory")
; #define PG8_BAR __builtin_amdgcn_s_barrier()
; #define PG8_SCHED __builtin_amdgcn_sched_barrier(0)
; template <class Epi>
; __device__ __forceinline__ void gemm_phase(LAS unsigned char* lds, const Gemm g, const StaticOrder& S, const Epi& E) {
;     ...
;             const bool last = (t == nt - 2);
;             const char* a1 = cA + (size_t)(t + 1) * kstep;
;             const char* a2 = last ? nA : cA + (size_t)(t + 2) * kstep; const char* b2 = last ? nB : cB + (size_t)(t + 2) * kstep;
;             const char* a3 = a2 + kstep; const char* b3 = b2 + kstep;
;             PG8_LDB(B0, 0, 0); PG8_LDB(B1, 0, 1); PG8_SCHED; PG8_LDA(At, 0, 0); PG8_STAGE(PG8_SA(1, 1), a1 + hstepA, voffA);
;             PG8_WAIT_V(8); PG8_WAIT_L(0); PG8_BAR; PG8_MMA(0, 0, At, B0); PG8_MMA(0, 1, At, B1); PG8_BAR; PG8_SCHED;
;             PG8_LDA(At, 0, 1); PG8_STAGE(PG8_SB(0, 0), b2, voffB); PG8_STAGE(PG8_SB(0, 1), b2 + hstepB, voffB); PG8_STAGE(PG8_SA(0, 0), a2, voffA);
;             PG8_WAIT_V(8); PG8_WAIT_L(0); PG8_BAR; PG8_MMA(1, 0, At, B0); PG8_MMA(1, 1, At, B1); PG8_BAR; PG8_SCHED;
.LBB0_1046:
	ds_read_b128 v[128:131], v185
	ds_read_b128 v[132:135], v185 offset:1024
	ds_read_b128 v[136:139], v185 offset:2048
	ds_read_b128 v[140:143], v185 offset:3072
	ds_read_b128 v[144:147], v186
	ds_read_b128 v[148:151], v186 offset:1024
	ds_read_b128 v[152:155], v186 offset:2048
	ds_read_b128 v[156:159], v186 offset:3072
	s_add_i32 s73, s46, 2
	s_add_u32 s47, s12, 0xfff80080
	s_addc_u32 s48, s13, -1
	s_cmp_eq_u32 s62, s46
	s_cselect_b32 s46, s41, s71
	s_cselect_b32 s49, s1, s48
	s_cselect_b32 s48, s33, s47
	s_cselect_b32 s47, s39, s72
	v_lshl_add_u64 v[182:183], s[12:13], 0, v[174:175]
	s_add_i32 m0, s5, 0xc000
	ds_read_b128 v[190:193], v187
	ds_read_b128 v[194:197], v187 offset:1024
	ds_read_b128 v[198:201], v187 offset:2048
	ds_read_b128 v[208:211], v187 offset:3072
	ds_read_b128 v[212:215], v187 offset:4096
	ds_read_b128 v[216:219], v187 offset:5120
	ds_read_b128 v[220:223], v187 offset:6144
	ds_read_b128 v[224:227], v187 offset:7168
	global_load_lds_dwordx4 v[182:183], off
	v_lshl_add_u64 v[182:183], s[12:13], 0, v[176:177]
	s_add_i32 m0, s5, 0xe000
	s_nop 0
	global_load_lds_dwordx4 v[182:183], off
	s_waitcnt vmcnt(8)
	s_waitcnt lgkmcnt(0)
	s_barrier
	s_setprio 1
	s_waitcnt lgkmcnt(0)
	v_mfma_f32_16x16x32_bf16 v[120:123], v[128:131], v[190:193], v[120:123]
	v_mfma_f32_16x16x32_bf16 v[120:123], v[132:135], v[194:197], v[120:123]
	v_mfma_f32_16x16x32_bf16 v[108:111], v[132:135], v[208:211], v[108:111]
	v_mfma_f32_16x16x32_bf16 v[108:111], v[128:131], v[198:201], v[108:111]
	v_mfma_f32_16x16x32_bf16 v[92:95], v[128:131], v[212:215], v[92:95]
	v_mfma_f32_16x16x32_bf16 v[92:95], v[132:135], v[216:219], v[92:95]
	v_mfma_f32_16x16x32_bf16 v[76:79], v[132:135], v[224:227], v[76:79]
	v_mfma_f32_16x16x32_bf16 v[76:79], v[128:131], v[220:223], v[76:79]
	v_mfma_f32_16x16x32_bf16 v[72:75], v[136:139], v[220:223], v[72:75]
	v_mfma_f32_16x16x32_bf16 v[72:75], v[140:143], v[224:227], v[72:75]
	v_mfma_f32_16x16x32_bf16 v[88:91], v[140:143], v[216:219], v[88:91]
	v_mfma_f32_16x16x32_bf16 v[88:91], v[136:139], v[212:215], v[88:91]
	v_mfma_f32_16x16x32_bf16 v[104:107], v[136:139], v[198:201], v[104:107]
	v_mfma_f32_16x16x32_bf16 v[104:107], v[140:143], v[208:211], v[104:107]
	v_mfma_f32_16x16x32_bf16 v[124:127], v[140:143], v[194:197], v[124:127]
	v_mfma_f32_16x16x32_bf16 v[124:127], v[136:139], v[190:193], v[124:127]
	s_setprio 0
	s_setprio 1
	v_mfma_f32_16x16x32_bf16 v[116:119], v[144:147], v[190:193], v[116:119]
	v_mfma_f32_16x16x32_bf16 v[116:119], v[148:151], v[194:197], v[116:119]
	v_mfma_f32_16x16x32_bf16 v[100:103], v[148:151], v[208:211], v[100:103]
	v_mfma_f32_16x16x32_bf16 v[100:103], v[144:147], v[198:201], v[100:103]
	v_mfma_f32_16x16x32_bf16 v[84:87], v[144:147], v[212:215], v[84:87]
	v_mfma_f32_16x16x32_bf16 v[84:87], v[148:151], v[216:219], v[84:87]
	v_mfma_f32_16x16x32_bf16 v[68:71], v[148:151], v[224:227], v[68:71]
	v_mfma_f32_16x16x32_bf16 v[68:71], v[144:147], v[220:223], v[68:71]
	v_mfma_f32_16x16x32_bf16 v[64:67], v[152:155], v[220:223], v[64:67]
	v_mfma_f32_16x16x32_bf16 v[64:67], v[156:159], v[224:227], v[64:67]
	v_mfma_f32_16x16x32_bf16 v[80:83], v[156:159], v[216:219], v[80:83]
	v_mfma_f32_16x16x32_bf16 v[80:83], v[152:155], v[212:215], v[80:83]
	v_mfma_f32_16x16x32_bf16 v[96:99], v[152:155], v[198:201], v[96:99]
	v_mfma_f32_16x16x32_bf16 v[96:99], v[156:159], v[208:211], v[96:99]
	v_mfma_f32_16x16x32_bf16 v[112:115], v[156:159], v[194:197], v[112:115]
	v_mfma_f32_16x16x32_bf16 v[112:115], v[152:155], v[190:193], v[112:115]
	s_setprio 0
	s_barrier
	s_add_i32 s76, s65, s54
	v_lshl_add_u64 v[182:183], s[46:47], 0, v[162:163]
	s_mov_b32 m0, s76
	ds_read_b128 v[190:193], v187 offset:16384
	ds_read_b128 v[194:197], v187 offset:17408
	ds_read_b128 v[198:201], v187 offset:18432
	ds_read_b128 v[208:211], v187 offset:19456
	ds_read_b128 v[212:215], v187 offset:20480
	ds_read_b128 v[216:219], v187 offset:21504
	ds_read_b128 v[220:223], v187 offset:22528
	ds_read_b128 v[224:227], v187 offset:23552
	global_load_lds_dwordx4 v[182:183], off
	s_add_i32 m0, s76, 0x2000
	s_add_u32 s76, s46, 0x80000
	v_lshl_add_u64 v[202:203], s[46:47], 0, v[166:167]
	s_addc_u32 s77, s47, 0
	s_add_i32 s78, s66, s54
	global_load_lds_dwordx4 v[202:203], off
	v_lshl_add_u64 v[230:231], s[76:77], 0, v[162:163]
	s_mov_b32 m0, s78
	v_lshl_add_u64 v[232:233], s[48:49], 0, v[164:165]
	global_load_lds_dwordx4 v[230:231], off
	v_lshl_add_u64 v[230:231], s[76:77], 0, v[166:167]
	s_add_i32 m0, s78, 0x2000
	s_nop 0
	global_load_lds_dwordx4 v[230:231], off
	v_lshl_add_u64 v[230:231], s[48:49], 0, v[160:161]
	s_mov_b32 m0, s5
	s_nop 0
	global_load_lds_dwordx4 v[230:231], off
	s_mov_b32 m0, s55
	s_nop 0
	global_load_lds_dwordx4 v[232:233], off
	s_waitcnt vmcnt(8)
	s_waitcnt lgkmcnt(0)
	s_barrier
; #define PG8_STAGE(bufoff, gbase, voff) do { _Pragma("unroll") for (int _i = 0; _i < 2; ++_i) \
;         __builtin_amdgcn_global_load_lds((const unsigned*)((const char*)(gbase) + (voff)[_i]), (LAS unsigned*)(lds + (bufoff) + ldsw + _i * 8192), 16, 0, 0); } while (0)
; #define PG8_LDA(dst, b, h) do { _Pragma("unroll") for (int m = 0; m < 4; ++m) _Pragma("unroll") for (int k = 0; k < 2; ++k) dst[m][k] = *(const LAS bf16x8*)(lds + PG8_SA(b, h) + aoff + m * 2048 + k * 1024); } while (0)
; #define PG8_LDB(dst, b, h) do { _Pragma("unroll") for (int n = 0; n < 2; ++n) _Pragma("unroll") for (int k = 0; k < 2; ++k) dst[n][k] = *(const LAS bf16x8*)(lds + PG8_SB(b, h) + boff + n * 2048 + k * 1024); } while (0)
; #define PG8_MMA(ai, bj, At, Bt) do { __builtin_amdgcn_s_setprio(1); _Pragma("unroll") for (int m = 0; m < 4; ++m) _Pragma("unroll") for (int n = 0; n < 2; ++n) _Pragma("unroll") for (int k = 0; k < 2; ++k) \
;         acc[ai][bj][m][n] = __builtin_amdgcn_mfma_f32_16x16x32_bf16(Bt[n][k], At[m][k], acc[ai][bj][m][n], 0, 0, 0); __builtin_amdgcn_s_setprio(0); } while (0)
; #define PG8_WAIT_V(n) asm volatile("s_waitcnt vmcnt(" #n ")" ::: "memory")
; #define PG8_WAIT_L(n) asm volatile("s_waitcnt lgkmcnt(" #n ")" ::: "memory")
; #define PG8_BAR __builtin_amdgcn_s_barrier()
; #define PG8_SCHED __builtin_amdgcn_sched_barrier(0)
; template <class Epi>
; __device__ __forceinline__ void gemm_phase(LAS unsigned char* lds, const Gemm g, const StaticOrder& S, const Epi& E) {
;     ...
;             PG8_WAIT_V(8); PG8_WAIT_L(0); PG8_BAR; PG8_MMA(1, 0, At, B0); PG8_MMA(1, 1, At, B1); PG8_BAR; PG8_SCHED;
;             PG8_LDB(B0, 1, 0); PG8_LDB(B1, 1, 1); PG8_SCHED; PG8_LDA(At, 1, 0); PG8_STAGE(PG8_SA(0, 1), a2 + hstepA, voffA);
;             PG8_WAIT_V(8); PG8_WAIT_L(0); PG8_BAR; PG8_MMA(0, 0, At, B0); PG8_MMA(0, 1, At, B1); PG8_BAR; PG8_SCHED;
	s_setprio 1
	s_waitcnt lgkmcnt(0)
	v_mfma_f32_16x16x32_bf16 v[60:63], v[128:131], v[190:193], v[60:63]
	v_mfma_f32_16x16x32_bf16 v[60:63], v[132:135], v[194:197], v[60:63]
	v_mfma_f32_16x16x32_bf16 v[44:47], v[132:135], v[208:211], v[44:47]
	v_mfma_f32_16x16x32_bf16 v[44:47], v[128:131], v[198:201], v[44:47]
	v_mfma_f32_16x16x32_bf16 v[28:31], v[128:131], v[212:215], v[28:31]
	v_mfma_f32_16x16x32_bf16 v[28:31], v[132:135], v[216:219], v[28:31]
	v_mfma_f32_16x16x32_bf16 v[12:15], v[132:135], v[224:227], v[12:15]
	v_mfma_f32_16x16x32_bf16 v[12:15], v[128:131], v[220:223], v[12:15]
	v_mfma_f32_16x16x32_bf16 v[8:11], v[136:139], v[220:223], v[8:11]
	v_mfma_f32_16x16x32_bf16 v[8:11], v[140:143], v[224:227], v[8:11]
	v_mfma_f32_16x16x32_bf16 v[24:27], v[140:143], v[216:219], v[24:27]
	v_mfma_f32_16x16x32_bf16 v[24:27], v[136:139], v[212:215], v[24:27]
	v_mfma_f32_16x16x32_bf16 v[40:43], v[136:139], v[198:201], v[40:43]
	v_mfma_f32_16x16x32_bf16 v[40:43], v[140:143], v[208:211], v[40:43]
	v_mfma_f32_16x16x32_bf16 v[56:59], v[140:143], v[194:197], v[56:59]
	v_mfma_f32_16x16x32_bf16 v[56:59], v[136:139], v[190:193], v[56:59]
	s_setprio 0
	s_setprio 1
	v_mfma_f32_16x16x32_bf16 v[52:55], v[144:147], v[190:193], v[52:55]
	v_mfma_f32_16x16x32_bf16 v[52:55], v[148:151], v[194:197], v[52:55]
	v_mfma_f32_16x16x32_bf16 v[36:39], v[148:151], v[208:211], v[36:39]
	v_mfma_f32_16x16x32_bf16 v[36:39], v[144:147], v[198:201], v[36:39]
	v_mfma_f32_16x16x32_bf16 v[20:23], v[144:147], v[212:215], v[20:23]
	v_mfma_f32_16x16x32_bf16 v[20:23], v[148:151], v[216:219], v[20:23]
	v_mfma_f32_16x16x32_bf16 v[4:7], v[148:151], v[224:227], v[4:7]
	v_mfma_f32_16x16x32_bf16 v[4:7], v[144:147], v[220:223], v[4:7]
	v_mfma_f32_16x16x32_bf16 v[0:3], v[152:155], v[220:223], v[0:3]
	v_mfma_f32_16x16x32_bf16 v[0:3], v[156:159], v[224:227], v[0:3]
	v_mfma_f32_16x16x32_bf16 v[16:19], v[156:159], v[216:219], v[16:19]
	v_mfma_f32_16x16x32_bf16 v[16:19], v[152:155], v[212:215], v[16:19]
	v_mfma_f32_16x16x32_bf16 v[32:35], v[152:155], v[198:201], v[32:35]
	v_mfma_f32_16x16x32_bf16 v[32:35], v[156:159], v[208:211], v[32:35]
	v_mfma_f32_16x16x32_bf16 v[48:51], v[156:159], v[194:197], v[48:51]
	v_mfma_f32_16x16x32_bf16 v[48:51], v[152:155], v[190:193], v[48:51]
	s_setprio 0
	s_barrier
	s_add_i32 s76, 0, 0x18000
	s_add_i32 s77, 0, 0x1c000
	v_add_u32_e32 v140, s76, v184
	v_add_u32_e32 v156, s77, v184
	ds_read_b128 v[128:131], v140
	ds_read_b128 v[132:135], v140 offset:1024
	ds_read_b128 v[136:139], v140 offset:2048
	ds_read_b128 v[140:143], v140 offset:3072
	ds_read_b128 v[144:147], v156
	ds_read_b128 v[148:151], v156 offset:1024
	ds_read_b128 v[152:155], v156 offset:2048
	ds_read_b128 v[156:159], v156 offset:3072
	s_add_u32 s48, s48, 0x80000
	s_addc_u32 s49, s49, 0
	s_mov_b32 m0, s56
	v_lshl_add_u64 v[234:235], s[48:49], 0, v[160:161]
	ds_read_b128 v[190:193], v187 offset:32768
	ds_read_b128 v[194:197], v187 offset:33792
	ds_read_b128 v[198:201], v187 offset:34816
	ds_read_b128 v[208:211], v187 offset:35840
	ds_read_b128 v[212:215], v187 offset:36864
	ds_read_b128 v[216:219], v187 offset:37888
	ds_read_b128 v[220:223], v187 offset:38912
	ds_read_b128 v[224:227], v187 offset:39936
	global_load_lds_dwordx4 v[234:235], off
	v_lshl_add_u64 v[234:235], s[48:49], 0, v[164:165]
	s_mov_b32 m0, s57
	s_nop 0
	global_load_lds_dwordx4 v[234:235], off
	s_waitcnt vmcnt(8)
	s_waitcnt lgkmcnt(0)
	s_barrier
	s_setprio 1
	s_waitcnt lgkmcnt(0)
	v_mfma_f32_16x16x32_bf16 v[120:123], v[128:131], v[190:193], v[120:123]
	v_mfma_f32_16x16x32_bf16 v[120:123], v[132:135], v[194:197], v[120:123]
	v_mfma_f32_16x16x32_bf16 v[108:111], v[132:135], v[208:211], v[108:111]
	v_mfma_f32_16x16x32_bf16 v[108:111], v[128:131], v[198:201], v[108:111]
	v_mfma_f32_16x16x32_bf16 v[92:95], v[128:131], v[212:215], v[92:95]
	v_mfma_f32_16x16x32_bf16 v[92:95], v[132:135], v[216:219], v[92:95]
	v_mfma_f32_16x16x32_bf16 v[76:79], v[132:135], v[224:227], v[76:79]
	v_mfma_f32_16x16x32_bf16 v[76:79], v[128:131], v[220:223], v[76:79]
	v_mfma_f32_16x16x32_bf16 v[72:75], v[136:139], v[220:223], v[72:75]
	v_mfma_f32_16x16x32_bf16 v[72:75], v[140:143], v[224:227], v[72:75]
	v_mfma_f32_16x16x32_bf16 v[88:91], v[140:143], v[216:219], v[88:91]
	v_mfma_f32_16x16x32_bf16 v[88:91], v[136:139], v[212:215], v[88:91]
	v_mfma_f32_16x16x32_bf16 v[104:107], v[136:139], v[198:201], v[104:107]
	v_mfma_f32_16x16x32_bf16 v[104:107], v[140:143], v[208:211], v[104:107]
	v_mfma_f32_16x16x32_bf16 v[124:127], v[140:143], v[194:197], v[124:127]
	v_mfma_f32_16x16x32_bf16 v[124:127], v[136:139], v[190:193], v[124:127]
	s_setprio 0
	s_setprio 1
	v_mfma_f32_16x16x32_bf16 v[116:119], v[144:147], v[190:193], v[116:119]
	v_mfma_f32_16x16x32_bf16 v[116:119], v[148:151], v[194:197], v[116:119]
	v_mfma_f32_16x16x32_bf16 v[100:103], v[148:151], v[208:211], v[100:103]
	v_mfma_f32_16x16x32_bf16 v[100:103], v[144:147], v[198:201], v[100:103]
	v_mfma_f32_16x16x32_bf16 v[84:87], v[144:147], v[212:215], v[84:87]
	v_mfma_f32_16x16x32_bf16 v[84:87], v[148:151], v[216:219], v[84:87]
	v_mfma_f32_16x16x32_bf16 v[68:71], v[148:151], v[224:227], v[68:71]
	v_mfma_f32_16x16x32_bf16 v[68:71], v[144:147], v[220:223], v[68:71]
	v_mfma_f32_16x16x32_bf16 v[64:67], v[152:155], v[220:223], v[64:67]
	v_mfma_f32_16x16x32_bf16 v[64:67], v[156:159], v[224:227], v[64:67]
	v_mfma_f32_16x16x32_bf16 v[80:83], v[156:159], v[216:219], v[80:83]
	v_mfma_f32_16x16x32_bf16 v[80:83], v[152:155], v[212:215], v[80:83]
	v_mfma_f32_16x16x32_bf16 v[96:99], v[152:155], v[198:201], v[96:99]
	v_mfma_f32_16x16x32_bf16 v[96:99], v[156:159], v[208:211], v[96:99]
	v_mfma_f32_16x16x32_bf16 v[112:115], v[156:159], v[194:197], v[112:115]
	v_mfma_f32_16x16x32_bf16 v[112:115], v[152:155], v[190:193], v[112:115]
	s_setprio 0
	s_barrier
; #define PG8_STAGE(bufoff, gbase, voff) do { _Pragma("unroll") for (int _i = 0; _i < 2; ++_i) \
;         __builtin_amdgcn_global_load_lds((const unsigned*)((const char*)(gbase) + (voff)[_i]), (LAS unsigned*)(lds + (bufoff) + ldsw + _i * 8192), 16, 0, 0); } while (0)
; #define PG8_LDA(dst, b, h) do { _Pragma("unroll") for (int m = 0; m < 4; ++m) _Pragma("unroll") for (int k = 0; k < 2; ++k) dst[m][k] = *(const LAS bf16x8*)(lds + PG8_SA(b, h) + aoff + m * 2048 + k * 1024); } while (0)
; #define PG8_MMA(ai, bj, At, Bt) do { __builtin_amdgcn_s_setprio(1); _Pragma("unroll") for (int m = 0; m < 4; ++m) _Pragma("unroll") for (int n = 0; n < 2; ++n) _Pragma("unroll") for (int k = 0; k < 2; ++k) \
;         acc[ai][bj][m][n] = __builtin_amdgcn_mfma_f32_16x16x32_bf16(Bt[n][k], At[m][k], acc[ai][bj][m][n], 0, 0, 0); __builtin_amdgcn_s_setprio(0); } while (0)
; #define PG8_WAIT_V(n) asm volatile("s_waitcnt vmcnt(" #n ")" ::: "memory")
; #define PG8_WAIT_L(n) asm volatile("s_waitcnt lgkmcnt(" #n ")" ::: "memory")
; #define PG8_BAR __builtin_amdgcn_s_barrier()
; #define PG8_SCHED __builtin_amdgcn_sched_barrier(0)
; template <class Epi>
; __device__ __forceinline__ void gemm_phase(LAS unsigned char* lds, const Gemm g, const StaticOrder& S, const Epi& E) {
;     ...
;             PG8_LDA(At, 1, 1); PG8_STAGE(PG8_SB(1, 0), b3, voffB); PG8_STAGE(PG8_SB(1, 1), b3 + hstepB, voffB); PG8_STAGE(PG8_SA(1, 0), a3, voffA);
;             PG8_WAIT_V(8); PG8_WAIT_L(0); PG8_BAR; PG8_MMA(1, 0, At, B0); PG8_MMA(1, 1, At, B1); PG8_BAR; PG8_SCHED;
	s_add_i32 s48, s76, s54
	v_lshl_add_u64 v[182:183], v[182:183], 0, s[16:17]
	s_mov_b32 m0, s48
	ds_read_b128 v[190:193], v187 offset:49152
	ds_read_b128 v[194:197], v187 offset:50176
	ds_read_b128 v[198:201], v187 offset:51200
	ds_read_b128 v[208:211], v187 offset:52224
	ds_read_b128 v[212:215], v187 offset:53248
	ds_read_b128 v[216:219], v187 offset:54272
	ds_read_b128 v[220:223], v187 offset:55296
	ds_read_b128 v[224:227], v187 offset:56320
	global_load_lds_dwordx4 v[182:183], off
	s_add_i32 m0, s48, 0x2000
	s_add_u32 s46, s46, 0x80080
	v_lshl_add_u64 v[182:183], v[202:203], 0, s[16:17]
	s_addc_u32 s47, s47, 0
	s_add_i32 s48, s77, s54
	global_load_lds_dwordx4 v[182:183], off
	v_lshl_add_u64 v[182:183], s[46:47], 0, v[162:163]
	s_mov_b32 m0, s48
	s_nop 0
	global_load_lds_dwordx4 v[182:183], off
	v_lshl_add_u64 v[182:183], s[46:47], 0, v[166:167]
	s_add_i32 m0, s48, 0x2000
	s_nop 0
	global_load_lds_dwordx4 v[182:183], off
	v_lshl_add_u64 v[182:183], v[230:231], 0, s[16:17]
	s_mov_b32 m0, s60
	s_nop 0
	global_load_lds_dwordx4 v[182:183], off
	v_lshl_add_u64 v[182:183], v[232:233], 0, s[16:17]
	s_mov_b32 m0, s61
	s_nop 0
	global_load_lds_dwordx4 v[182:183], off
	s_waitcnt vmcnt(8)
	s_waitcnt lgkmcnt(0)
	s_barrier
	s_setprio 1
	s_waitcnt lgkmcnt(0)
	v_mfma_f32_16x16x32_bf16 v[60:63], v[128:131], v[190:193], v[60:63]
	v_mfma_f32_16x16x32_bf16 v[60:63], v[132:135], v[194:197], v[60:63]
	v_mfma_f32_16x16x32_bf16 v[44:47], v[132:135], v[208:211], v[44:47]
	v_mfma_f32_16x16x32_bf16 v[44:47], v[128:131], v[198:201], v[44:47]
	v_mfma_f32_16x16x32_bf16 v[28:31], v[128:131], v[212:215], v[28:31]
	v_mfma_f32_16x16x32_bf16 v[28:31], v[132:135], v[216:219], v[28:31]
	v_mfma_f32_16x16x32_bf16 v[12:15], v[132:135], v[224:227], v[12:15]
	v_mfma_f32_16x16x32_bf16 v[12:15], v[128:131], v[220:223], v[12:15]
	v_mfma_f32_16x16x32_bf16 v[8:11], v[136:139], v[220:223], v[8:11]
	v_mfma_f32_16x16x32_bf16 v[8:11], v[140:143], v[224:227], v[8:11]
	v_mfma_f32_16x16x32_bf16 v[24:27], v[140:143], v[216:219], v[24:27]
	v_mfma_f32_16x16x32_bf16 v[24:27], v[136:139], v[212:215], v[24:27]
	v_mfma_f32_16x16x32_bf16 v[40:43], v[136:139], v[198:201], v[40:43]
	v_mfma_f32_16x16x32_bf16 v[40:43], v[140:143], v[208:211], v[40:43]
	v_mfma_f32_16x16x32_bf16 v[56:59], v[140:143], v[194:197], v[56:59]
	v_mfma_f32_16x16x32_bf16 v[56:59], v[136:139], v[190:193], v[56:59]
	s_setprio 0
	s_setprio 1
	v_mfma_f32_16x16x32_bf16 v[52:55], v[144:147], v[190:193], v[52:55]
	v_mfma_f32_16x16x32_bf16 v[52:55], v[148:151], v[194:197], v[52:55]
	v_mfma_f32_16x16x32_bf16 v[36:39], v[148:151], v[208:211], v[36:39]
	v_mfma_f32_16x16x32_bf16 v[36:39], v[144:147], v[198:201], v[36:39]
	v_mfma_f32_16x16x32_bf16 v[20:23], v[144:147], v[212:215], v[20:23]
	v_mfma_f32_16x16x32_bf16 v[20:23], v[148:151], v[216:219], v[20:23]
	v_mfma_f32_16x16x32_bf16 v[4:7], v[148:151], v[224:227], v[4:7]
	v_mfma_f32_16x16x32_bf16 v[4:7], v[144:147], v[220:223], v[4:7]
	v_mfma_f32_16x16x32_bf16 v[0:3], v[152:155], v[220:223], v[0:3]
	v_mfma_f32_16x16x32_bf16 v[0:3], v[156:159], v[224:227], v[0:3]
	v_mfma_f32_16x16x32_bf16 v[16:19], v[156:159], v[216:219], v[16:19]
	v_mfma_f32_16x16x32_bf16 v[16:19], v[152:155], v[212:215], v[16:19]
	v_mfma_f32_16x16x32_bf16 v[32:35], v[152:155], v[198:201], v[32:35]
	v_mfma_f32_16x16x32_bf16 v[32:35], v[156:159], v[208:211], v[32:35]
	v_mfma_f32_16x16x32_bf16 v[48:51], v[156:159], v[194:197], v[48:51]
	v_mfma_f32_16x16x32_bf16 v[48:51], v[152:155], v[190:193], v[48:51]
	s_setprio 0
	s_barrier
	s_add_u32 s12, s12, 0x100
	s_addc_u32 s13, s13, 0
	s_add_u32 s71, s71, 0x100
	s_addc_u32 s72, s72, 0
	s_cmp_ge_i32 s73, s59
	s_mov_b32 s46, s73
	s_cbranch_scc0 .LBB0_1046

; #define PG8_STAGE(bufoff, gbase, voff) do { _Pragma("unroll") for (int _i = 0; _i < 2; ++_i) \
;         __builtin_amdgcn_global_load_lds((const unsigned*)((const char*)(gbase) + (voff)[_i]), (LAS unsigned*)(lds + (bufoff) + ldsw + _i * 8192), 16, 0, 0); } while (0)
; #define PG8_LDA(dst, b, h) do { _Pragma("unroll") for (int m = 0; m < 4; ++m) _Pragma("unroll") for (int k = 0; k < 2; ++k) dst[m][k] = *(const LAS bf16x8*)(lds + PG8_SA(b, h) + aoff + m * 2048 + k * 1024); } while (0)
; #define PG8_LDB(dst, b, h) do { _Pragma("unroll") for (int n = 0; n < 2; ++n) _Pragma("unroll") for (int k = 0; k < 2; ++k) dst[n][k] = *(const LAS bf16x8*)(lds + PG8_SB(b, h) + boff + n * 2048 + k * 1024); } while (0)
; #define PG8_MMA(ai, bj, At, Bt) do { __builtin_amdgcn_s_setprio(1); _Pragma("unroll") for (int m = 0; m < 4; ++m) _Pragma("unroll") for (int n = 0; n < 2; ++n) _Pragma("unroll") for (int k = 0; k < 2; ++k) \
;         acc[ai][bj][m][n] = __builtin_amdgcn_mfma_f32_16x16x32_bf16(Bt[n][k], At[m][k], acc[ai][bj][m][n], 0, 0, 0); __builtin_amdgcn_s_setprio(0); } while (0)
; #define PG8_WAIT_V(n) asm volatile("s_waitcnt vmcnt(" #n ")" ::: "memory")
; #define PG8_WAIT_L(n) asm volatile("s_waitcnt lgkmcnt(" #n ")" ::: "memory")
; #define PG8_BAR __builtin_amdgcn_s_barrier()
; #define PG8_SCHED __builtin_amdgcn_sched_barrier(0)
; template <class Epi>
; __device__ __forceinline__ void gemm_phase(LAS unsigned char* lds, const Gemm g, const StaticOrder& S, const Epi& E) {
;     ...
;             const bool last = (t == nt - 2);
;             const char* a1 = cA + (size_t)(t + 1) * kstep;
;             const char* a2 = last ? nA : cA + (size_t)(t + 2) * kstep; const char* b2 = last ? nB : cB + (size_t)(t + 2) * kstep;
;             const char* a3 = a2 + kstep; const char* b3 = b2 + kstep;
;             PG8_LDB(B0, 0, 0); PG8_LDB(B1, 0, 1); PG8_SCHED; PG8_LDA(At, 0, 0); PG8_STAGE(PG8_SA(1, 1), a1 + hstepA, voffA);
;             PG8_WAIT_V(8); PG8_WAIT_L(0); PG8_BAR; PG8_MMA(0, 0, At, B0); PG8_MMA(0, 1, At, B1); PG8_BAR; PG8_SCHED;
;             PG8_LDA(At, 0, 1); PG8_STAGE(PG8_SB(0, 0), b2, voffB); PG8_STAGE(PG8_SB(0, 1), b2 + hstepB, voffB); PG8_STAGE(PG8_SA(0, 0), a2, voffA);
;             PG8_WAIT_V(8); PG8_WAIT_L(0); PG8_BAR; PG8_MMA(1, 0, At, B0); PG8_MMA(1, 1, At, B1); PG8_BAR; PG8_SCHED;
.LBB0_1131:
	ds_read_b128 v[164:167], v182
	ds_read_b128 v[168:171], v182 offset:1024
	ds_read_b128 v[172:175], v182 offset:2048
	ds_read_b128 v[176:179], v182 offset:3072
	ds_read_b128 v[186:189], v183
	ds_read_b128 v[190:193], v183 offset:1024
	ds_read_b128 v[194:197], v183 offset:2048
	ds_read_b128 v[198:201], v183 offset:3072
	s_add_i32 s22, s12, 2
	s_add_u32 s13, s10, 0xfff80080
	s_addc_u32 s14, s11, -1
	s_cmp_eq_u32 s58, s12
	s_cselect_b32 s12, s19, s20
	s_cselect_b32 s15, s16, s14
	s_cselect_b32 s14, s17, s13
	s_cselect_b32 s13, s18, s21
	v_lshl_add_u64 v[202:203], s[10:11], 0, v[140:141]
	s_add_i32 m0, s33, 0xc000
	ds_read_b128 v[208:211], v184
	ds_read_b128 v[212:215], v184 offset:1024
	ds_read_b128 v[216:219], v184 offset:2048
	ds_read_b128 v[220:223], v184 offset:3072
	ds_read_b128 v[224:227], v184 offset:4096
	ds_read_b128 v[230:233], v184 offset:5120
	ds_read_b128 v[234:237], v184 offset:6144
	ds_read_b128 v[238:241], v184 offset:7168
	global_load_lds_dwordx4 v[202:203], off
	v_lshl_add_u64 v[202:203], s[10:11], 0, v[142:143]
	s_add_i32 m0, s33, 0xe000
	s_nop 0
	global_load_lds_dwordx4 v[202:203], off
	s_waitcnt vmcnt(8)
	s_waitcnt lgkmcnt(0)
	s_barrier
	s_setprio 1
	s_waitcnt lgkmcnt(0)
	v_mfma_f32_16x16x32_bf16 v[120:123], v[164:167], v[208:211], v[120:123]
	v_mfma_f32_16x16x32_bf16 v[120:123], v[168:171], v[212:215], v[120:123]
	v_mfma_f32_16x16x32_bf16 v[108:111], v[168:171], v[220:223], v[108:111]
	v_mfma_f32_16x16x32_bf16 v[108:111], v[164:167], v[216:219], v[108:111]
	v_mfma_f32_16x16x32_bf16 v[92:95], v[164:167], v[224:227], v[92:95]
	v_mfma_f32_16x16x32_bf16 v[92:95], v[168:171], v[230:233], v[92:95]
	v_mfma_f32_16x16x32_bf16 v[76:79], v[168:171], v[238:241], v[76:79]
	v_mfma_f32_16x16x32_bf16 v[76:79], v[164:167], v[234:237], v[76:79]
	v_mfma_f32_16x16x32_bf16 v[68:71], v[172:175], v[234:237], v[68:71]
	v_mfma_f32_16x16x32_bf16 v[68:71], v[176:179], v[238:241], v[68:71]
	v_mfma_f32_16x16x32_bf16 v[84:87], v[176:179], v[230:233], v[84:87]
	v_mfma_f32_16x16x32_bf16 v[84:87], v[172:175], v[224:227], v[84:87]
	v_mfma_f32_16x16x32_bf16 v[100:103], v[172:175], v[216:219], v[100:103]
	v_mfma_f32_16x16x32_bf16 v[100:103], v[176:179], v[220:223], v[100:103]
	v_mfma_f32_16x16x32_bf16 v[116:119], v[176:179], v[212:215], v[116:119]
	v_mfma_f32_16x16x32_bf16 v[116:119], v[172:175], v[208:211], v[116:119]
	s_setprio 0
	s_setprio 1
	v_mfma_f32_16x16x32_bf16 v[124:127], v[186:189], v[208:211], v[124:127]
	v_mfma_f32_16x16x32_bf16 v[124:127], v[190:193], v[212:215], v[124:127]
	v_mfma_f32_16x16x32_bf16 v[104:107], v[190:193], v[220:223], v[104:107]
	v_mfma_f32_16x16x32_bf16 v[104:107], v[186:189], v[216:219], v[104:107]
	v_mfma_f32_16x16x32_bf16 v[88:91], v[186:189], v[224:227], v[88:91]
	v_mfma_f32_16x16x32_bf16 v[88:91], v[190:193], v[230:233], v[88:91]
	v_mfma_f32_16x16x32_bf16 v[72:75], v[190:193], v[238:241], v[72:75]
	v_mfma_f32_16x16x32_bf16 v[72:75], v[186:189], v[234:237], v[72:75]
	v_mfma_f32_16x16x32_bf16 v[64:67], v[194:197], v[234:237], v[64:67]
	v_mfma_f32_16x16x32_bf16 v[64:67], v[198:201], v[238:241], v[64:67]
	v_mfma_f32_16x16x32_bf16 v[80:83], v[198:201], v[230:233], v[80:83]
	v_mfma_f32_16x16x32_bf16 v[80:83], v[194:197], v[224:227], v[80:83]
	v_mfma_f32_16x16x32_bf16 v[96:99], v[194:197], v[216:219], v[96:99]
	v_mfma_f32_16x16x32_bf16 v[96:99], v[198:201], v[220:223], v[96:99]
	v_mfma_f32_16x16x32_bf16 v[112:115], v[198:201], v[212:215], v[112:115]
	v_mfma_f32_16x16x32_bf16 v[112:115], v[194:197], v[208:211], v[112:115]
	s_setprio 0
	s_barrier
	s_add_i32 s23, s62, s37
	v_lshl_add_u64 v[202:203], s[12:13], 0, v[132:133]
	s_mov_b32 m0, s23
	ds_read_b128 v[208:211], v184 offset:16384
	ds_read_b128 v[212:215], v184 offset:17408
	ds_read_b128 v[216:219], v184 offset:18432
	ds_read_b128 v[220:223], v184 offset:19456
	ds_read_b128 v[224:227], v184 offset:20480
	ds_read_b128 v[230:233], v184 offset:21504
	ds_read_b128 v[234:237], v184 offset:22528
	ds_read_b128 v[238:241], v184 offset:23552
	global_load_lds_dwordx4 v[202:203], off
	s_add_i32 m0, s23, 0x2000
	s_add_u32 s50, s12, 0x80000
	v_lshl_add_u64 v[242:243], s[12:13], 0, v[128:129]
	s_addc_u32 s51, s13, 0
	s_add_i32 s23, s63, s37
	global_load_lds_dwordx4 v[242:243], off
	v_lshl_add_u64 v[244:245], s[50:51], 0, v[132:133]
	s_mov_b32 m0, s23
	v_lshl_add_u64 v[246:247], s[14:15], 0, v[130:131]
	global_load_lds_dwordx4 v[244:245], off
	v_lshl_add_u64 v[244:245], s[50:51], 0, v[128:129]
	s_add_i32 m0, s23, 0x2000
	s_nop 0
	global_load_lds_dwordx4 v[244:245], off
	v_lshl_add_u64 v[244:245], s[14:15], 0, v[134:135]
	s_mov_b32 m0, s33
	s_nop 0
	global_load_lds_dwordx4 v[244:245], off
	s_mov_b32 m0, s52
	s_nop 0
	global_load_lds_dwordx4 v[246:247], off
	s_waitcnt vmcnt(8)
	s_waitcnt lgkmcnt(0)
	s_barrier
; #define PG8_STAGE(bufoff, gbase, voff) do { _Pragma("unroll") for (int _i = 0; _i < 2; ++_i) \
;         __builtin_amdgcn_global_load_lds((const unsigned*)((const char*)(gbase) + (voff)[_i]), (LAS unsigned*)(lds + (bufoff) + ldsw + _i * 8192), 16, 0, 0); } while (0)
; #define PG8_LDA(dst, b, h) do { _Pragma("unroll") for (int m = 0; m < 4; ++m) _Pragma("unroll") for (int k = 0; k < 2; ++k) dst[m][k] = *(const LAS bf16x8*)(lds + PG8_SA(b, h) + aoff + m * 2048 + k * 1024); } while (0)
; #define PG8_LDB(dst, b, h) do { _Pragma("unroll") for (int n = 0; n < 2; ++n) _Pragma("unroll") for (int k = 0; k < 2; ++k) dst[n][k] = *(const LAS bf16x8*)(lds + PG8_SB(b, h) + boff + n * 2048 + k * 1024); } while (0)
; #define PG8_MMA(ai, bj, At, Bt) do { __builtin_amdgcn_s_setprio(1); _Pragma("unroll") for (int m = 0; m < 4; ++m) _Pragma("unroll") for (int n = 0; n < 2; ++n) _Pragma("unroll") for (int k = 0; k < 2; ++k) \
;         acc[ai][bj][m][n] = __builtin_amdgcn_mfma_f32_16x16x32_bf16(Bt[n][k], At[m][k], acc[ai][bj][m][n], 0, 0, 0); __builtin_amdgcn_s_setprio(0); } while (0)
; #define PG8_WAIT_V(n) asm volatile("s_waitcnt vmcnt(" #n ")" ::: "memory")
; #define PG8_WAIT_L(n) asm volatile("s_waitcnt lgkmcnt(" #n ")" ::: "memory")
; #define PG8_BAR __builtin_amdgcn_s_barrier()
; #define PG8_SCHED __builtin_amdgcn_sched_barrier(0)
; template <class Epi>
; __device__ __forceinline__ void gemm_phase(LAS unsigned char* lds, const Gemm g, const StaticOrder& S, const Epi& E) {
;     ...
;             PG8_WAIT_V(8); PG8_WAIT_L(0); PG8_BAR; PG8_MMA(1, 0, At, B0); PG8_MMA(1, 1, At, B1); PG8_BAR; PG8_SCHED;
;             PG8_LDB(B0, 1, 0); PG8_LDB(B1, 1, 1); PG8_SCHED; PG8_LDA(At, 1, 0); PG8_STAGE(PG8_SA(0, 1), a2 + hstepA, voffA);
;             PG8_WAIT_V(8); PG8_WAIT_L(0); PG8_BAR; PG8_MMA(0, 0, At, B0); PG8_MMA(0, 1, At, B1); PG8_BAR; PG8_SCHED;
	s_setprio 1
	s_waitcnt lgkmcnt(0)
	v_mfma_f32_16x16x32_bf16 v[60:63], v[164:167], v[208:211], v[60:63]
	v_mfma_f32_16x16x32_bf16 v[60:63], v[168:171], v[212:215], v[60:63]
	v_mfma_f32_16x16x32_bf16 v[44:47], v[168:171], v[220:223], v[44:47]
	v_mfma_f32_16x16x32_bf16 v[44:47], v[164:167], v[216:219], v[44:47]
	v_mfma_f32_16x16x32_bf16 v[28:31], v[164:167], v[224:227], v[28:31]
	v_mfma_f32_16x16x32_bf16 v[28:31], v[168:171], v[230:233], v[28:31]
	v_mfma_f32_16x16x32_bf16 v[12:15], v[168:171], v[238:241], v[12:15]
	v_mfma_f32_16x16x32_bf16 v[12:15], v[164:167], v[234:237], v[12:15]
	v_mfma_f32_16x16x32_bf16 v[4:7], v[172:175], v[234:237], v[4:7]
	v_mfma_f32_16x16x32_bf16 v[4:7], v[176:179], v[238:241], v[4:7]
	v_mfma_f32_16x16x32_bf16 v[20:23], v[176:179], v[230:233], v[20:23]
	v_mfma_f32_16x16x32_bf16 v[20:23], v[172:175], v[224:227], v[20:23]
	v_mfma_f32_16x16x32_bf16 v[36:39], v[172:175], v[216:219], v[36:39]
	v_mfma_f32_16x16x32_bf16 v[36:39], v[176:179], v[220:223], v[36:39]
	v_mfma_f32_16x16x32_bf16 v[52:55], v[176:179], v[212:215], v[52:55]
	v_mfma_f32_16x16x32_bf16 v[52:55], v[172:175], v[208:211], v[52:55]
	s_setprio 0
	s_setprio 1
	v_mfma_f32_16x16x32_bf16 v[56:59], v[186:189], v[208:211], v[56:59]
	v_mfma_f32_16x16x32_bf16 v[56:59], v[190:193], v[212:215], v[56:59]
	v_mfma_f32_16x16x32_bf16 v[40:43], v[190:193], v[220:223], v[40:43]
	v_mfma_f32_16x16x32_bf16 v[40:43], v[186:189], v[216:219], v[40:43]
	v_mfma_f32_16x16x32_bf16 v[24:27], v[186:189], v[224:227], v[24:27]
	v_mfma_f32_16x16x32_bf16 v[24:27], v[190:193], v[230:233], v[24:27]
	v_mfma_f32_16x16x32_bf16 v[8:11], v[190:193], v[238:241], v[8:11]
	v_mfma_f32_16x16x32_bf16 v[8:11], v[186:189], v[234:237], v[8:11]
	v_mfma_f32_16x16x32_bf16 v[0:3], v[194:197], v[234:237], v[0:3]
	v_mfma_f32_16x16x32_bf16 v[0:3], v[198:201], v[238:241], v[0:3]
	v_mfma_f32_16x16x32_bf16 v[16:19], v[198:201], v[230:233], v[16:19]
	v_mfma_f32_16x16x32_bf16 v[16:19], v[194:197], v[224:227], v[16:19]
	v_mfma_f32_16x16x32_bf16 v[32:35], v[194:197], v[216:219], v[32:35]
	v_mfma_f32_16x16x32_bf16 v[32:35], v[198:201], v[220:223], v[32:35]
	v_mfma_f32_16x16x32_bf16 v[48:51], v[198:201], v[212:215], v[48:51]
	v_mfma_f32_16x16x32_bf16 v[48:51], v[194:197], v[208:211], v[48:51]
	s_setprio 0
	s_barrier
	s_add_i32 s23, 0, 0x18000
	s_add_i32 s25, 0, 0x1c000
	v_add_u32_e32 v176, s23, v180
	v_add_u32_e32 v185, s25, v180
	ds_read_b128 v[164:167], v176
	ds_read_b128 v[168:171], v176 offset:1024
	ds_read_b128 v[172:175], v176 offset:2048
	ds_read_b128 v[176:179], v176 offset:3072
	ds_read_b128 v[186:189], v185
	ds_read_b128 v[190:193], v185 offset:1024
	ds_read_b128 v[194:197], v185 offset:2048
	ds_read_b128 v[198:201], v185 offset:3072
	s_add_u32 s14, s14, 0x80000
	s_addc_u32 s15, s15, 0
	s_mov_b32 m0, s53
	v_lshl_add_u64 v[248:249], s[14:15], 0, v[134:135]
	ds_read_b128 v[208:211], v184 offset:32768
	ds_read_b128 v[212:215], v184 offset:33792
	ds_read_b128 v[216:219], v184 offset:34816
	ds_read_b128 v[220:223], v184 offset:35840
	ds_read_b128 v[224:227], v184 offset:36864
	ds_read_b128 v[230:233], v184 offset:37888
	ds_read_b128 v[234:237], v184 offset:38912
	ds_read_b128 v[238:241], v184 offset:39936
	global_load_lds_dwordx4 v[248:249], off
	v_lshl_add_u64 v[248:249], s[14:15], 0, v[130:131]
	s_mov_b32 m0, s54
	s_nop 0
	global_load_lds_dwordx4 v[248:249], off
	s_waitcnt vmcnt(8)
	s_waitcnt lgkmcnt(0)
	s_barrier
	s_setprio 1
	s_waitcnt lgkmcnt(0)
	v_mfma_f32_16x16x32_bf16 v[120:123], v[164:167], v[208:211], v[120:123]
	v_mfma_f32_16x16x32_bf16 v[120:123], v[168:171], v[212:215], v[120:123]
	v_mfma_f32_16x16x32_bf16 v[108:111], v[168:171], v[220:223], v[108:111]
	v_mfma_f32_16x16x32_bf16 v[108:111], v[164:167], v[216:219], v[108:111]
	v_mfma_f32_16x16x32_bf16 v[92:95], v[164:167], v[224:227], v[92:95]
	v_mfma_f32_16x16x32_bf16 v[92:95], v[168:171], v[230:233], v[92:95]
	v_mfma_f32_16x16x32_bf16 v[76:79], v[168:171], v[238:241], v[76:79]
	v_mfma_f32_16x16x32_bf16 v[76:79], v[164:167], v[234:237], v[76:79]
	v_mfma_f32_16x16x32_bf16 v[68:71], v[172:175], v[234:237], v[68:71]
	v_mfma_f32_16x16x32_bf16 v[68:71], v[176:179], v[238:241], v[68:71]
	v_mfma_f32_16x16x32_bf16 v[84:87], v[176:179], v[230:233], v[84:87]
	v_mfma_f32_16x16x32_bf16 v[84:87], v[172:175], v[224:227], v[84:87]
	v_mfma_f32_16x16x32_bf16 v[100:103], v[172:175], v[216:219], v[100:103]
	v_mfma_f32_16x16x32_bf16 v[100:103], v[176:179], v[220:223], v[100:103]
	v_mfma_f32_16x16x32_bf16 v[116:119], v[176:179], v[212:215], v[116:119]
	v_mfma_f32_16x16x32_bf16 v[116:119], v[172:175], v[208:211], v[116:119]
	s_setprio 0
	s_setprio 1
	v_mfma_f32_16x16x32_bf16 v[124:127], v[186:189], v[208:211], v[124:127]
	v_mfma_f32_16x16x32_bf16 v[124:127], v[190:193], v[212:215], v[124:127]
	v_mfma_f32_16x16x32_bf16 v[104:107], v[190:193], v[220:223], v[104:107]
	v_mfma_f32_16x16x32_bf16 v[104:107], v[186:189], v[216:219], v[104:107]
	v_mfma_f32_16x16x32_bf16 v[88:91], v[186:189], v[224:227], v[88:91]
	v_mfma_f32_16x16x32_bf16 v[88:91], v[190:193], v[230:233], v[88:91]
	v_mfma_f32_16x16x32_bf16 v[72:75], v[190:193], v[238:241], v[72:75]
	v_mfma_f32_16x16x32_bf16 v[72:75], v[186:189], v[234:237], v[72:75]
	v_mfma_f32_16x16x32_bf16 v[64:67], v[194:197], v[234:237], v[64:67]
	v_mfma_f32_16x16x32_bf16 v[64:67], v[198:201], v[238:241], v[64:67]
	v_mfma_f32_16x16x32_bf16 v[80:83], v[198:201], v[230:233], v[80:83]
	v_mfma_f32_16x16x32_bf16 v[80:83], v[194:197], v[224:227], v[80:83]
	v_mfma_f32_16x16x32_bf16 v[96:99], v[194:197], v[216:219], v[96:99]
	v_mfma_f32_16x16x32_bf16 v[96:99], v[198:201], v[220:223], v[96:99]
	v_mfma_f32_16x16x32_bf16 v[112:115], v[198:201], v[212:215], v[112:115]
	v_mfma_f32_16x16x32_bf16 v[112:115], v[194:197], v[208:211], v[112:115]
	s_setprio 0
	s_barrier
; #define PG8_STAGE(bufoff, gbase, voff) do { _Pragma("unroll") for (int _i = 0; _i < 2; ++_i) \
;         __builtin_amdgcn_global_load_lds((const unsigned*)((const char*)(gbase) + (voff)[_i]), (LAS unsigned*)(lds + (bufoff) + ldsw + _i * 8192), 16, 0, 0); } while (0)
; #define PG8_LDA(dst, b, h) do { _Pragma("unroll") for (int m = 0; m < 4; ++m) _Pragma("unroll") for (int k = 0; k < 2; ++k) dst[m][k] = *(const LAS bf16x8*)(lds + PG8_SA(b, h) + aoff + m * 2048 + k * 1024); } while (0)
; #define PG8_MMA(ai, bj, At, Bt) do { __builtin_amdgcn_s_setprio(1); _Pragma("unroll") for (int m = 0; m < 4; ++m) _Pragma("unroll") for (int n = 0; n < 2; ++n) _Pragma("unroll") for (int k = 0; k < 2; ++k) \
;         acc[ai][bj][m][n] = __builtin_amdgcn_mfma_f32_16x16x32_bf16(Bt[n][k], At[m][k], acc[ai][bj][m][n], 0, 0, 0); __builtin_amdgcn_s_setprio(0); } while (0)
; #define PG8_WAIT_V(n) asm volatile("s_waitcnt vmcnt(" #n ")" ::: "memory")
; #define PG8_WAIT_L(n) asm volatile("s_waitcnt lgkmcnt(" #n ")" ::: "memory")
; #define PG8_BAR __builtin_amdgcn_s_barrier()
; #define PG8_SCHED __builtin_amdgcn_sched_barrier(0)
; template <class Epi>
; __device__ __forceinline__ void gemm_phase(LAS unsigned char* lds, const Gemm g, const StaticOrder& S, const Epi& E) {
;     ...
;             PG8_LDA(At, 1, 1); PG8_STAGE(PG8_SB(1, 0), b3, voffB); PG8_STAGE(PG8_SB(1, 1), b3 + hstepB, voffB); PG8_STAGE(PG8_SA(1, 0), a3, voffA);
;             PG8_WAIT_V(8); PG8_WAIT_L(0); PG8_BAR; PG8_MMA(1, 0, At, B0); PG8_MMA(1, 1, At, B1); PG8_BAR; PG8_SCHED;
	s_add_i32 s14, s23, s37
	v_lshl_add_u64 v[202:203], v[202:203], 0, s[4:5]
	s_mov_b32 m0, s14
	ds_read_b128 v[208:211], v184 offset:49152
	ds_read_b128 v[212:215], v184 offset:50176
	ds_read_b128 v[216:219], v184 offset:51200
	ds_read_b128 v[220:223], v184 offset:52224
	ds_read_b128 v[224:227], v184 offset:53248
	ds_read_b128 v[230:233], v184 offset:54272
	ds_read_b128 v[234:237], v184 offset:55296
	ds_read_b128 v[238:241], v184 offset:56320
	global_load_lds_dwordx4 v[202:203], off
	s_add_i32 m0, s14, 0x2000
	s_add_u32 s12, s12, 0x80080
	v_lshl_add_u64 v[202:203], v[242:243], 0, s[4:5]
	s_addc_u32 s13, s13, 0
	s_add_i32 s14, s25, s37
	global_load_lds_dwordx4 v[202:203], off
	v_lshl_add_u64 v[202:203], s[12:13], 0, v[132:133]
	s_mov_b32 m0, s14
	s_nop 0
	global_load_lds_dwordx4 v[202:203], off
	v_lshl_add_u64 v[202:203], s[12:13], 0, v[128:129]
	s_add_i32 m0, s14, 0x2000
	s_nop 0
	global_load_lds_dwordx4 v[202:203], off
	v_lshl_add_u64 v[202:203], v[244:245], 0, s[4:5]
	s_mov_b32 m0, s56
	s_nop 0
	global_load_lds_dwordx4 v[202:203], off
	v_lshl_add_u64 v[202:203], v[246:247], 0, s[4:5]
	s_mov_b32 m0, s57
	s_nop 0
	global_load_lds_dwordx4 v[202:203], off
	s_waitcnt vmcnt(8)
	s_waitcnt lgkmcnt(0)
	s_barrier
	s_setprio 1
	s_waitcnt lgkmcnt(0)
	v_mfma_f32_16x16x32_bf16 v[60:63], v[164:167], v[208:211], v[60:63]
	v_mfma_f32_16x16x32_bf16 v[60:63], v[168:171], v[212:215], v[60:63]
	v_mfma_f32_16x16x32_bf16 v[44:47], v[168:171], v[220:223], v[44:47]
	v_mfma_f32_16x16x32_bf16 v[44:47], v[164:167], v[216:219], v[44:47]
	v_mfma_f32_16x16x32_bf16 v[28:31], v[164:167], v[224:227], v[28:31]
	v_mfma_f32_16x16x32_bf16 v[28:31], v[168:171], v[230:233], v[28:31]
	v_mfma_f32_16x16x32_bf16 v[12:15], v[168:171], v[238:241], v[12:15]
	v_mfma_f32_16x16x32_bf16 v[12:15], v[164:167], v[234:237], v[12:15]
	v_mfma_f32_16x16x32_bf16 v[4:7], v[172:175], v[234:237], v[4:7]
	v_mfma_f32_16x16x32_bf16 v[4:7], v[176:179], v[238:241], v[4:7]
	v_mfma_f32_16x16x32_bf16 v[20:23], v[176:179], v[230:233], v[20:23]
	v_mfma_f32_16x16x32_bf16 v[20:23], v[172:175], v[224:227], v[20:23]
	v_mfma_f32_16x16x32_bf16 v[36:39], v[172:175], v[216:219], v[36:39]
	v_mfma_f32_16x16x32_bf16 v[36:39], v[176:179], v[220:223], v[36:39]
	v_mfma_f32_16x16x32_bf16 v[52:55], v[176:179], v[212:215], v[52:55]
	v_mfma_f32_16x16x32_bf16 v[52:55], v[172:175], v[208:211], v[52:55]
	s_setprio 0
	s_setprio 1
	v_mfma_f32_16x16x32_bf16 v[56:59], v[186:189], v[208:211], v[56:59]
	v_mfma_f32_16x16x32_bf16 v[56:59], v[190:193], v[212:215], v[56:59]
	v_mfma_f32_16x16x32_bf16 v[40:43], v[190:193], v[220:223], v[40:43]
	v_mfma_f32_16x16x32_bf16 v[40:43], v[186:189], v[216:219], v[40:43]
	v_mfma_f32_16x16x32_bf16 v[24:27], v[186:189], v[224:227], v[24:27]
	v_mfma_f32_16x16x32_bf16 v[24:27], v[190:193], v[230:233], v[24:27]
	v_mfma_f32_16x16x32_bf16 v[8:11], v[190:193], v[238:241], v[8:11]
	v_mfma_f32_16x16x32_bf16 v[8:11], v[186:189], v[234:237], v[8:11]
	v_mfma_f32_16x16x32_bf16 v[0:3], v[194:197], v[234:237], v[0:3]
	v_mfma_f32_16x16x32_bf16 v[0:3], v[198:201], v[238:241], v[0:3]
	v_mfma_f32_16x16x32_bf16 v[16:19], v[198:201], v[230:233], v[16:19]
	v_mfma_f32_16x16x32_bf16 v[16:19], v[194:197], v[224:227], v[16:19]
	v_mfma_f32_16x16x32_bf16 v[32:35], v[194:197], v[216:219], v[32:35]
	v_mfma_f32_16x16x32_bf16 v[32:35], v[198:201], v[220:223], v[32:35]
	v_mfma_f32_16x16x32_bf16 v[48:51], v[198:201], v[212:215], v[48:51]
	v_mfma_f32_16x16x32_bf16 v[48:51], v[194:197], v[208:211], v[48:51]
	s_setprio 0
	s_barrier
	s_add_u32 s10, s10, 0x100
	s_addc_u32 s11, s11, 0
	s_add_u32 s20, s20, 0x100
	s_addc_u32 s21, s21, 0
	s_cmp_ge_i32 s22, s55
	s_mov_b32 s12, s22
	s_cbranch_scc0 .LBB0_1131

; #define PG8_STAGE(bufoff, gbase, voff) do { _Pragma("unroll") for (int _i = 0; _i < 2; ++_i) \
;         __builtin_amdgcn_global_load_lds((const unsigned*)((const char*)(gbase) + (voff)[_i]), (LAS unsigned*)(lds + (bufoff) + ldsw + _i * 8192), 16, 0, 0); } while (0)
; #define PG8_LDA(dst, b, h) do { _Pragma("unroll") for (int m = 0; m < 4; ++m) _Pragma("unroll") for (int k = 0; k < 2; ++k) dst[m][k] = *(const LAS bf16x8*)(lds + PG8_SA(b, h) + aoff + m * 2048 + k * 1024); } while (0)
; #define PG8_LDB(dst, b, h) do { _Pragma("unroll") for (int n = 0; n < 2; ++n) _Pragma("unroll") for (int k = 0; k < 2; ++k) dst[n][k] = *(const LAS bf16x8*)(lds + PG8_SB(b, h) + boff + n * 2048 + k * 1024); } while (0)
; #define PG8_MMA(ai, bj, At, Bt) do { __builtin_amdgcn_s_setprio(1); _Pragma("unroll") for (int m = 0; m < 4; ++m) _Pragma("unroll") for (int n = 0; n < 2; ++n) _Pragma("unroll") for (int k = 0; k < 2; ++k) \
;         acc[ai][bj][m][n] = __builtin_amdgcn_mfma_f32_16x16x32_bf16(Bt[n][k], At[m][k], acc[ai][bj][m][n], 0, 0, 0); __builtin_amdgcn_s_setprio(0); } while (0)
; #define PG8_WAIT_V(n) asm volatile("s_waitcnt vmcnt(" #n ")" ::: "memory")
; #define PG8_WAIT_L(n) asm volatile("s_waitcnt lgkmcnt(" #n ")" ::: "memory")
; #define PG8_BAR __builtin_amdgcn_s_barrier()
; #define PG8_SCHED __builtin_amdgcn_sched_barrier(0)
; template <class Epi>
; __device__ __forceinline__ void gemm_phase(LAS unsigned char* lds, const Gemm g, const StaticOrder& S, const Epi& E) {
;     ...
;             const bool last = (t == nt - 2);
;             const char* a1 = cA + (size_t)(t + 1) * kstep;
;             const char* a2 = last ? nA : cA + (size_t)(t + 2) * kstep; const char* b2 = last ? nB : cB + (size_t)(t + 2) * kstep;
;             const char* a3 = a2 + kstep; const char* b3 = b2 + kstep;
;             PG8_LDB(B0, 0, 0); PG8_LDB(B1, 0, 1); PG8_SCHED; PG8_LDA(At, 0, 0); PG8_STAGE(PG8_SA(1, 1), a1 + hstepA, voffA);
;             PG8_WAIT_V(8); PG8_WAIT_L(0); PG8_BAR; PG8_MMA(0, 0, At, B0); PG8_MMA(0, 1, At, B1); PG8_BAR; PG8_SCHED;
;             PG8_LDA(At, 0, 1); PG8_STAGE(PG8_SB(0, 0), b2, voffB); PG8_STAGE(PG8_SB(0, 1), b2 + hstepB, voffB); PG8_STAGE(PG8_SA(0, 0), a2, voffA);
;             PG8_WAIT_V(8); PG8_WAIT_L(0); PG8_BAR; PG8_MMA(1, 0, At, B0); PG8_MMA(1, 1, At, B1); PG8_BAR; PG8_SCHED;
.LBB0_1161:
	ds_read_b128 v[152:155], v149
	ds_read_b128 v[156:159], v149 offset:1024
	ds_read_b128 v[160:163], v149 offset:2048
	ds_read_b128 v[164:167], v149 offset:3072
	ds_read_b128 v[168:171], v150
	ds_read_b128 v[172:175], v150 offset:1024
	ds_read_b128 v[176:179], v150 offset:2048
	ds_read_b128 v[180:183], v150 offset:3072
	s_add_i32 s83, s46, 2
	s_add_u32 s47, s44, 0xffff0080
	s_addc_u32 s48, s45, -1
	s_cmp_eq_u32 s65, s46
	s_cselect_b32 s46, s78, s79
	s_cselect_b32 s49, s35, s48
	s_cselect_b32 s48, s37, s47
	s_cselect_b32 s47, s39, s82
	v_lshl_add_u64 v[220:221], s[44:45], 0, v[140:141]
	s_add_i32 m0, s56, 0xc000
	ds_read_b128 v[184:187], v151
	ds_read_b128 v[188:191], v151 offset:1024
	ds_read_b128 v[192:195], v151 offset:2048
	ds_read_b128 v[196:199], v151 offset:3072
	ds_read_b128 v[200:203], v151 offset:4096
	ds_read_b128 v[208:211], v151 offset:5120
	ds_read_b128 v[212:215], v151 offset:6144
	ds_read_b128 v[216:219], v151 offset:7168
	global_load_lds_dwordx4 v[220:221], off
	v_lshl_add_u64 v[220:221], s[44:45], 0, v[142:143]
	s_add_i32 m0, s56, 0xe000
	s_nop 0
	global_load_lds_dwordx4 v[220:221], off
	s_waitcnt vmcnt(8)
	s_waitcnt lgkmcnt(0)
	s_barrier
	s_setprio 1
	s_waitcnt lgkmcnt(0)
	v_mfma_f32_16x16x32_bf16 v[120:123], v[152:155], v[184:187], v[120:123]
	v_mfma_f32_16x16x32_bf16 v[120:123], v[156:159], v[188:191], v[120:123]
	v_mfma_f32_16x16x32_bf16 v[108:111], v[156:159], v[196:199], v[108:111]
	v_mfma_f32_16x16x32_bf16 v[108:111], v[152:155], v[192:195], v[108:111]
	v_mfma_f32_16x16x32_bf16 v[92:95], v[152:155], v[200:203], v[92:95]
	v_mfma_f32_16x16x32_bf16 v[92:95], v[156:159], v[208:211], v[92:95]
	v_mfma_f32_16x16x32_bf16 v[76:79], v[156:159], v[216:219], v[76:79]
	v_mfma_f32_16x16x32_bf16 v[76:79], v[152:155], v[212:215], v[76:79]
	v_mfma_f32_16x16x32_bf16 v[72:75], v[160:163], v[212:215], v[72:75]
	v_mfma_f32_16x16x32_bf16 v[72:75], v[164:167], v[216:219], v[72:75]
	v_mfma_f32_16x16x32_bf16 v[88:91], v[164:167], v[208:211], v[88:91]
	v_mfma_f32_16x16x32_bf16 v[88:91], v[160:163], v[200:203], v[88:91]
	v_mfma_f32_16x16x32_bf16 v[104:107], v[160:163], v[192:195], v[104:107]
	v_mfma_f32_16x16x32_bf16 v[104:107], v[164:167], v[196:199], v[104:107]
	v_mfma_f32_16x16x32_bf16 v[124:127], v[164:167], v[188:191], v[124:127]
	v_mfma_f32_16x16x32_bf16 v[124:127], v[160:163], v[184:187], v[124:127]
	s_setprio 0
	s_setprio 1
	v_mfma_f32_16x16x32_bf16 v[116:119], v[168:171], v[184:187], v[116:119]
	v_mfma_f32_16x16x32_bf16 v[116:119], v[172:175], v[188:191], v[116:119]
	v_mfma_f32_16x16x32_bf16 v[100:103], v[172:175], v[196:199], v[100:103]
	v_mfma_f32_16x16x32_bf16 v[100:103], v[168:171], v[192:195], v[100:103]
	v_mfma_f32_16x16x32_bf16 v[84:87], v[168:171], v[200:203], v[84:87]
	v_mfma_f32_16x16x32_bf16 v[84:87], v[172:175], v[208:211], v[84:87]
	v_mfma_f32_16x16x32_bf16 v[68:71], v[172:175], v[216:219], v[68:71]
	v_mfma_f32_16x16x32_bf16 v[68:71], v[168:171], v[212:215], v[68:71]
	v_mfma_f32_16x16x32_bf16 v[64:67], v[176:179], v[212:215], v[64:67]
	v_mfma_f32_16x16x32_bf16 v[64:67], v[180:183], v[216:219], v[64:67]
	v_mfma_f32_16x16x32_bf16 v[80:83], v[180:183], v[208:211], v[80:83]
	v_mfma_f32_16x16x32_bf16 v[80:83], v[176:179], v[200:203], v[80:83]
	v_mfma_f32_16x16x32_bf16 v[96:99], v[176:179], v[192:195], v[96:99]
	v_mfma_f32_16x16x32_bf16 v[96:99], v[180:183], v[196:199], v[96:99]
	v_mfma_f32_16x16x32_bf16 v[112:115], v[180:183], v[188:191], v[112:115]
	v_mfma_f32_16x16x32_bf16 v[112:115], v[176:179], v[184:187], v[112:115]
	s_setprio 0
	s_barrier
	s_add_i32 s84, s67, s51
	v_lshl_add_u64 v[220:221], s[46:47], 0, v[130:131]
	s_mov_b32 m0, s84
	ds_read_b128 v[184:187], v151 offset:16384
	ds_read_b128 v[188:191], v151 offset:17408
	ds_read_b128 v[192:195], v151 offset:18432
	ds_read_b128 v[196:199], v151 offset:19456
	ds_read_b128 v[200:203], v151 offset:20480
	ds_read_b128 v[208:211], v151 offset:21504
	ds_read_b128 v[212:215], v151 offset:22528
	ds_read_b128 v[216:219], v151 offset:23552
	global_load_lds_dwordx4 v[220:221], off
	s_add_i32 m0, s84, 0x2000
	s_add_u32 s84, s46, 0x10000
	v_lshl_add_u64 v[222:223], s[46:47], 0, v[134:135]
	s_addc_u32 s85, s47, 0
	s_add_i32 s86, s68, s51
	global_load_lds_dwordx4 v[222:223], off
	v_lshl_add_u64 v[224:225], s[84:85], 0, v[130:131]
	s_mov_b32 m0, s86
	v_lshl_add_u64 v[226:227], s[48:49], 0, v[132:133]
	global_load_lds_dwordx4 v[224:225], off
	v_lshl_add_u64 v[224:225], s[84:85], 0, v[134:135]
	s_add_i32 m0, s86, 0x2000
	s_nop 0
	global_load_lds_dwordx4 v[224:225], off
	v_lshl_add_u64 v[224:225], s[48:49], 0, v[128:129]
	s_mov_b32 m0, s56
	s_nop 0
	global_load_lds_dwordx4 v[224:225], off
	s_mov_b32 m0, s57
	s_nop 0
	global_load_lds_dwordx4 v[226:227], off
	s_waitcnt vmcnt(8)
	s_waitcnt lgkmcnt(0)
	s_barrier
; #define PG8_STAGE(bufoff, gbase, voff) do { _Pragma("unroll") for (int _i = 0; _i < 2; ++_i) \
;         __builtin_amdgcn_global_load_lds((const unsigned*)((const char*)(gbase) + (voff)[_i]), (LAS unsigned*)(lds + (bufoff) + ldsw + _i * 8192), 16, 0, 0); } while (0)
; #define PG8_LDA(dst, b, h) do { _Pragma("unroll") for (int m = 0; m < 4; ++m) _Pragma("unroll") for (int k = 0; k < 2; ++k) dst[m][k] = *(const LAS bf16x8*)(lds + PG8_SA(b, h) + aoff + m * 2048 + k * 1024); } while (0)
; #define PG8_LDB(dst, b, h) do { _Pragma("unroll") for (int n = 0; n < 2; ++n) _Pragma("unroll") for (int k = 0; k < 2; ++k) dst[n][k] = *(const LAS bf16x8*)(lds + PG8_SB(b, h) + boff + n * 2048 + k * 1024); } while (0)
; #define PG8_MMA(ai, bj, At, Bt) do { __builtin_amdgcn_s_setprio(1); _Pragma("unroll") for (int m = 0; m < 4; ++m) _Pragma("unroll") for (int n = 0; n < 2; ++n) _Pragma("unroll") for (int k = 0; k < 2; ++k) \
;         acc[ai][bj][m][n] = __builtin_amdgcn_mfma_f32_16x16x32_bf16(Bt[n][k], At[m][k], acc[ai][bj][m][n], 0, 0, 0); __builtin_amdgcn_s_setprio(0); } while (0)
; #define PG8_WAIT_V(n) asm volatile("s_waitcnt vmcnt(" #n ")" ::: "memory")
; #define PG8_WAIT_L(n) asm volatile("s_waitcnt lgkmcnt(" #n ")" ::: "memory")
; #define PG8_BAR __builtin_amdgcn_s_barrier()
; #define PG8_SCHED __builtin_amdgcn_sched_barrier(0)
; template <class Epi>
; __device__ __forceinline__ void gemm_phase(LAS unsigned char* lds, const Gemm g, const StaticOrder& S, const Epi& E) {
;     ...
;             PG8_WAIT_V(8); PG8_WAIT_L(0); PG8_BAR; PG8_MMA(1, 0, At, B0); PG8_MMA(1, 1, At, B1); PG8_BAR; PG8_SCHED;
;             PG8_LDB(B0, 1, 0); PG8_LDB(B1, 1, 1); PG8_SCHED; PG8_LDA(At, 1, 0); PG8_STAGE(PG8_SA(0, 1), a2 + hstepA, voffA);
;             PG8_WAIT_V(8); PG8_WAIT_L(0); PG8_BAR; PG8_MMA(0, 0, At, B0); PG8_MMA(0, 1, At, B1); PG8_BAR; PG8_SCHED;
	s_setprio 1
	s_waitcnt lgkmcnt(0)
	v_mfma_f32_16x16x32_bf16 v[60:63], v[152:155], v[184:187], v[60:63]
	v_mfma_f32_16x16x32_bf16 v[60:63], v[156:159], v[188:191], v[60:63]
	v_mfma_f32_16x16x32_bf16 v[44:47], v[156:159], v[196:199], v[44:47]
	v_mfma_f32_16x16x32_bf16 v[44:47], v[152:155], v[192:195], v[44:47]
	v_mfma_f32_16x16x32_bf16 v[28:31], v[152:155], v[200:203], v[28:31]
	v_mfma_f32_16x16x32_bf16 v[28:31], v[156:159], v[208:211], v[28:31]
	v_mfma_f32_16x16x32_bf16 v[12:15], v[156:159], v[216:219], v[12:15]
	v_mfma_f32_16x16x32_bf16 v[12:15], v[152:155], v[212:215], v[12:15]
	v_mfma_f32_16x16x32_bf16 v[8:11], v[160:163], v[212:215], v[8:11]
	v_mfma_f32_16x16x32_bf16 v[8:11], v[164:167], v[216:219], v[8:11]
	v_mfma_f32_16x16x32_bf16 v[24:27], v[164:167], v[208:211], v[24:27]
	v_mfma_f32_16x16x32_bf16 v[24:27], v[160:163], v[200:203], v[24:27]
	v_mfma_f32_16x16x32_bf16 v[40:43], v[160:163], v[192:195], v[40:43]
	v_mfma_f32_16x16x32_bf16 v[40:43], v[164:167], v[196:199], v[40:43]
	v_mfma_f32_16x16x32_bf16 v[56:59], v[164:167], v[188:191], v[56:59]
	v_mfma_f32_16x16x32_bf16 v[56:59], v[160:163], v[184:187], v[56:59]
	s_setprio 0
	s_setprio 1
	v_mfma_f32_16x16x32_bf16 v[52:55], v[168:171], v[184:187], v[52:55]
	v_mfma_f32_16x16x32_bf16 v[52:55], v[172:175], v[188:191], v[52:55]
	v_mfma_f32_16x16x32_bf16 v[36:39], v[172:175], v[196:199], v[36:39]
	v_mfma_f32_16x16x32_bf16 v[36:39], v[168:171], v[192:195], v[36:39]
	v_mfma_f32_16x16x32_bf16 v[20:23], v[168:171], v[200:203], v[20:23]
	v_mfma_f32_16x16x32_bf16 v[20:23], v[172:175], v[208:211], v[20:23]
	v_mfma_f32_16x16x32_bf16 v[4:7], v[172:175], v[216:219], v[4:7]
	v_mfma_f32_16x16x32_bf16 v[4:7], v[168:171], v[212:215], v[4:7]
	v_mfma_f32_16x16x32_bf16 v[0:3], v[176:179], v[212:215], v[0:3]
	v_mfma_f32_16x16x32_bf16 v[0:3], v[180:183], v[216:219], v[0:3]
	v_mfma_f32_16x16x32_bf16 v[16:19], v[180:183], v[208:211], v[16:19]
	v_mfma_f32_16x16x32_bf16 v[16:19], v[176:179], v[200:203], v[16:19]
	v_mfma_f32_16x16x32_bf16 v[32:35], v[176:179], v[192:195], v[32:35]
	v_mfma_f32_16x16x32_bf16 v[32:35], v[180:183], v[196:199], v[32:35]
	v_mfma_f32_16x16x32_bf16 v[48:51], v[180:183], v[188:191], v[48:51]
	v_mfma_f32_16x16x32_bf16 v[48:51], v[176:179], v[184:187], v[48:51]
	s_setprio 0
	s_barrier
	s_add_i32 s84, 0, 0x18000
	s_add_i32 s85, 0, 0x1c000
	v_add_u32_e32 v164, s84, v148
	v_add_u32_e32 v180, s85, v148
	ds_read_b128 v[152:155], v164
	ds_read_b128 v[156:159], v164 offset:1024
	ds_read_b128 v[160:163], v164 offset:2048
	ds_read_b128 v[164:167], v164 offset:3072
	ds_read_b128 v[168:171], v180
	ds_read_b128 v[172:175], v180 offset:1024
	ds_read_b128 v[176:179], v180 offset:2048
	ds_read_b128 v[180:183], v180 offset:3072
	s_add_u32 s48, s48, 0x10000
	s_addc_u32 s49, s49, 0
	s_mov_b32 m0, s58
	v_lshl_add_u64 v[230:231], s[48:49], 0, v[128:129]
	ds_read_b128 v[184:187], v151 offset:32768
	ds_read_b128 v[188:191], v151 offset:33792
	ds_read_b128 v[192:195], v151 offset:34816
	ds_read_b128 v[196:199], v151 offset:35840
	ds_read_b128 v[200:203], v151 offset:36864
	ds_read_b128 v[208:211], v151 offset:37888
	ds_read_b128 v[212:215], v151 offset:38912
	ds_read_b128 v[216:219], v151 offset:39936
	global_load_lds_dwordx4 v[230:231], off
	v_lshl_add_u64 v[230:231], s[48:49], 0, v[132:133]
	s_mov_b32 m0, s59
	s_nop 0
	global_load_lds_dwordx4 v[230:231], off
	s_waitcnt vmcnt(8)
	s_waitcnt lgkmcnt(0)
	s_barrier
	s_setprio 1
	s_waitcnt lgkmcnt(0)
	v_mfma_f32_16x16x32_bf16 v[120:123], v[152:155], v[184:187], v[120:123]
	v_mfma_f32_16x16x32_bf16 v[120:123], v[156:159], v[188:191], v[120:123]
	v_mfma_f32_16x16x32_bf16 v[108:111], v[156:159], v[196:199], v[108:111]
	v_mfma_f32_16x16x32_bf16 v[108:111], v[152:155], v[192:195], v[108:111]
	v_mfma_f32_16x16x32_bf16 v[92:95], v[152:155], v[200:203], v[92:95]
	v_mfma_f32_16x16x32_bf16 v[92:95], v[156:159], v[208:211], v[92:95]
	v_mfma_f32_16x16x32_bf16 v[76:79], v[156:159], v[216:219], v[76:79]
	v_mfma_f32_16x16x32_bf16 v[76:79], v[152:155], v[212:215], v[76:79]
	v_mfma_f32_16x16x32_bf16 v[72:75], v[160:163], v[212:215], v[72:75]
	v_mfma_f32_16x16x32_bf16 v[72:75], v[164:167], v[216:219], v[72:75]
	v_mfma_f32_16x16x32_bf16 v[88:91], v[164:167], v[208:211], v[88:91]
	v_mfma_f32_16x16x32_bf16 v[88:91], v[160:163], v[200:203], v[88:91]
	v_mfma_f32_16x16x32_bf16 v[104:107], v[160:163], v[192:195], v[104:107]
	v_mfma_f32_16x16x32_bf16 v[104:107], v[164:167], v[196:199], v[104:107]
	v_mfma_f32_16x16x32_bf16 v[124:127], v[164:167], v[188:191], v[124:127]
	v_mfma_f32_16x16x32_bf16 v[124:127], v[160:163], v[184:187], v[124:127]
	s_setprio 0
	s_setprio 1
	v_mfma_f32_16x16x32_bf16 v[116:119], v[168:171], v[184:187], v[116:119]
	v_mfma_f32_16x16x32_bf16 v[116:119], v[172:175], v[188:191], v[116:119]
	v_mfma_f32_16x16x32_bf16 v[100:103], v[172:175], v[196:199], v[100:103]
	v_mfma_f32_16x16x32_bf16 v[100:103], v[168:171], v[192:195], v[100:103]
	v_mfma_f32_16x16x32_bf16 v[84:87], v[168:171], v[200:203], v[84:87]
	v_mfma_f32_16x16x32_bf16 v[84:87], v[172:175], v[208:211], v[84:87]
	v_mfma_f32_16x16x32_bf16 v[68:71], v[172:175], v[216:219], v[68:71]
	v_mfma_f32_16x16x32_bf16 v[68:71], v[168:171], v[212:215], v[68:71]
	v_mfma_f32_16x16x32_bf16 v[64:67], v[176:179], v[212:215], v[64:67]
	v_mfma_f32_16x16x32_bf16 v[64:67], v[180:183], v[216:219], v[64:67]
	v_mfma_f32_16x16x32_bf16 v[80:83], v[180:183], v[208:211], v[80:83]
	v_mfma_f32_16x16x32_bf16 v[80:83], v[176:179], v[200:203], v[80:83]
	v_mfma_f32_16x16x32_bf16 v[96:99], v[176:179], v[192:195], v[96:99]
	v_mfma_f32_16x16x32_bf16 v[96:99], v[180:183], v[196:199], v[96:99]
	v_mfma_f32_16x16x32_bf16 v[112:115], v[180:183], v[188:191], v[112:115]
	v_mfma_f32_16x16x32_bf16 v[112:115], v[176:179], v[184:187], v[112:115]
	s_setprio 0
	s_barrier
; #define PG8_STAGE(bufoff, gbase, voff) do { _Pragma("unroll") for (int _i = 0; _i < 2; ++_i) \
;         __builtin_amdgcn_global_load_lds((const unsigned*)((const char*)(gbase) + (voff)[_i]), (LAS unsigned*)(lds + (bufoff) + ldsw + _i * 8192), 16, 0, 0); } while (0)
; #define PG8_LDA(dst, b, h) do { _Pragma("unroll") for (int m = 0; m < 4; ++m) _Pragma("unroll") for (int k = 0; k < 2; ++k) dst[m][k] = *(const LAS bf16x8*)(lds + PG8_SA(b, h) + aoff + m * 2048 + k * 1024); } while (0)
; #define PG8_MMA(ai, bj, At, Bt) do { __builtin_amdgcn_s_setprio(1); _Pragma("unroll") for (int m = 0; m < 4; ++m) _Pragma("unroll") for (int n = 0; n < 2; ++n) _Pragma("unroll") for (int k = 0; k < 2; ++k) \
;         acc[ai][bj][m][n] = __builtin_amdgcn_mfma_f32_16x16x32_bf16(Bt[n][k], At[m][k], acc[ai][bj][m][n], 0, 0, 0); __builtin_amdgcn_s_setprio(0); } while (0)
; #define PG8_WAIT_V(n) asm volatile("s_waitcnt vmcnt(" #n ")" ::: "memory")
; #define PG8_WAIT_L(n) asm volatile("s_waitcnt lgkmcnt(" #n ")" ::: "memory")
; #define PG8_BAR __builtin_amdgcn_s_barrier()
; #define PG8_SCHED __builtin_amdgcn_sched_barrier(0)
; template <class Epi>
; __device__ __forceinline__ void gemm_phase(LAS unsigned char* lds, const Gemm g, const StaticOrder& S, const Epi& E) {
;     ...
;             PG8_LDA(At, 1, 1); PG8_STAGE(PG8_SB(1, 0), b3, voffB); PG8_STAGE(PG8_SB(1, 1), b3 + hstepB, voffB); PG8_STAGE(PG8_SA(1, 0), a3, voffA);
;             PG8_WAIT_V(8); PG8_WAIT_L(0); PG8_BAR; PG8_MMA(1, 0, At, B0); PG8_MMA(1, 1, At, B1); PG8_BAR; PG8_SCHED;
	s_add_i32 s48, s84, s51
	v_lshl_add_u64 v[220:221], v[220:221], 0, s[12:13]
	s_mov_b32 m0, s48
	ds_read_b128 v[184:187], v151 offset:49152
	ds_read_b128 v[188:191], v151 offset:50176
	ds_read_b128 v[192:195], v151 offset:51200
	ds_read_b128 v[196:199], v151 offset:52224
	ds_read_b128 v[200:203], v151 offset:53248
	ds_read_b128 v[208:211], v151 offset:54272
	ds_read_b128 v[212:215], v151 offset:55296
	ds_read_b128 v[216:219], v151 offset:56320
	global_load_lds_dwordx4 v[220:221], off
	s_add_i32 m0, s48, 0x2000
	s_add_u32 s46, s46, 0x10080
	v_lshl_add_u64 v[220:221], v[222:223], 0, s[12:13]
	s_addc_u32 s47, s47, 0
	s_add_i32 s48, s85, s51
	global_load_lds_dwordx4 v[220:221], off
	v_lshl_add_u64 v[220:221], s[46:47], 0, v[130:131]
	s_mov_b32 m0, s48
	s_nop 0
	global_load_lds_dwordx4 v[220:221], off
	v_lshl_add_u64 v[220:221], s[46:47], 0, v[134:135]
	s_add_i32 m0, s48, 0x2000
	s_nop 0
	global_load_lds_dwordx4 v[220:221], off
	v_lshl_add_u64 v[220:221], v[224:225], 0, s[12:13]
	s_mov_b32 m0, s63
	s_nop 0
	global_load_lds_dwordx4 v[220:221], off
	v_lshl_add_u64 v[220:221], v[226:227], 0, s[12:13]
	s_mov_b32 m0, s64
	s_nop 0
	global_load_lds_dwordx4 v[220:221], off
	s_waitcnt vmcnt(8)
	s_waitcnt lgkmcnt(0)
	s_barrier
	s_setprio 1
	s_waitcnt lgkmcnt(0)
	v_mfma_f32_16x16x32_bf16 v[60:63], v[152:155], v[184:187], v[60:63]
	v_mfma_f32_16x16x32_bf16 v[60:63], v[156:159], v[188:191], v[60:63]
	v_mfma_f32_16x16x32_bf16 v[44:47], v[156:159], v[196:199], v[44:47]
	v_mfma_f32_16x16x32_bf16 v[44:47], v[152:155], v[192:195], v[44:47]
	v_mfma_f32_16x16x32_bf16 v[28:31], v[152:155], v[200:203], v[28:31]
	v_mfma_f32_16x16x32_bf16 v[28:31], v[156:159], v[208:211], v[28:31]
	v_mfma_f32_16x16x32_bf16 v[12:15], v[156:159], v[216:219], v[12:15]
	v_mfma_f32_16x16x32_bf16 v[12:15], v[152:155], v[212:215], v[12:15]
	v_mfma_f32_16x16x32_bf16 v[8:11], v[160:163], v[212:215], v[8:11]
	v_mfma_f32_16x16x32_bf16 v[8:11], v[164:167], v[216:219], v[8:11]
	v_mfma_f32_16x16x32_bf16 v[24:27], v[164:167], v[208:211], v[24:27]
	v_mfma_f32_16x16x32_bf16 v[24:27], v[160:163], v[200:203], v[24:27]
	v_mfma_f32_16x16x32_bf16 v[40:43], v[160:163], v[192:195], v[40:43]
	v_mfma_f32_16x16x32_bf16 v[40:43], v[164:167], v[196:199], v[40:43]
	v_mfma_f32_16x16x32_bf16 v[56:59], v[164:167], v[188:191], v[56:59]
	v_mfma_f32_16x16x32_bf16 v[56:59], v[160:163], v[184:187], v[56:59]
	s_setprio 0
	s_setprio 1
	v_mfma_f32_16x16x32_bf16 v[52:55], v[168:171], v[184:187], v[52:55]
	v_mfma_f32_16x16x32_bf16 v[52:55], v[172:175], v[188:191], v[52:55]
	v_mfma_f32_16x16x32_bf16 v[36:39], v[172:175], v[196:199], v[36:39]
	v_mfma_f32_16x16x32_bf16 v[36:39], v[168:171], v[192:195], v[36:39]
	v_mfma_f32_16x16x32_bf16 v[20:23], v[168:171], v[200:203], v[20:23]
	v_mfma_f32_16x16x32_bf16 v[20:23], v[172:175], v[208:211], v[20:23]
	v_mfma_f32_16x16x32_bf16 v[4:7], v[172:175], v[216:219], v[4:7]
	v_mfma_f32_16x16x32_bf16 v[4:7], v[168:171], v[212:215], v[4:7]
	v_mfma_f32_16x16x32_bf16 v[0:3], v[176:179], v[212:215], v[0:3]
	v_mfma_f32_16x16x32_bf16 v[0:3], v[180:183], v[216:219], v[0:3]
	v_mfma_f32_16x16x32_bf16 v[16:19], v[180:183], v[208:211], v[16:19]
	v_mfma_f32_16x16x32_bf16 v[16:19], v[176:179], v[200:203], v[16:19]
	v_mfma_f32_16x16x32_bf16 v[32:35], v[176:179], v[192:195], v[32:35]
	v_mfma_f32_16x16x32_bf16 v[32:35], v[180:183], v[196:199], v[32:35]
	v_mfma_f32_16x16x32_bf16 v[48:51], v[180:183], v[188:191], v[48:51]
	v_mfma_f32_16x16x32_bf16 v[48:51], v[176:179], v[184:187], v[48:51]
	s_setprio 0
	s_barrier
	s_add_u32 s44, s44, 0x100
	s_addc_u32 s45, s45, 0
	s_add_u32 s79, s79, 0x100
	s_addc_u32 s82, s82, 0
	s_cmp_ge_i32 s83, s61
	s_mov_b32 s46, s83
	s_cbranch_scc0 .LBB0_1161

; #define PG8_STAGE(bufoff, gbase, voff) do { _Pragma("unroll") for (int _i = 0; _i < 2; ++_i) \
;         __builtin_amdgcn_global_load_lds((const unsigned*)((const char*)(gbase) + (voff)[_i]), (LAS unsigned*)(lds + (bufoff) + ldsw + _i * 8192), 16, 0, 0); } while (0)
; #define PG8_LDA(dst, b, h) do { _Pragma("unroll") for (int m = 0; m < 4; ++m) _Pragma("unroll") for (int k = 0; k < 2; ++k) dst[m][k] = *(const LAS bf16x8*)(lds + PG8_SA(b, h) + aoff + m * 2048 + k * 1024); } while (0)
; #define PG8_LDB(dst, b, h) do { _Pragma("unroll") for (int n = 0; n < 2; ++n) _Pragma("unroll") for (int k = 0; k < 2; ++k) dst[n][k] = *(const LAS bf16x8*)(lds + PG8_SB(b, h) + boff + n * 2048 + k * 1024); } while (0)
; #define PG8_MMA(ai, bj, At, Bt) do { __builtin_amdgcn_s_setprio(1); _Pragma("unroll") for (int m = 0; m < 4; ++m) _Pragma("unroll") for (int n = 0; n < 2; ++n) _Pragma("unroll") for (int k = 0; k < 2; ++k) \
;         acc[ai][bj][m][n] = __builtin_amdgcn_mfma_f32_16x16x32_bf16(Bt[n][k], At[m][k], acc[ai][bj][m][n], 0, 0, 0); __builtin_amdgcn_s_setprio(0); } while (0)
; #define PG8_WAIT_V(n) asm volatile("s_waitcnt vmcnt(" #n ")" ::: "memory")
; #define PG8_WAIT_L(n) asm volatile("s_waitcnt lgkmcnt(" #n ")" ::: "memory")
; #define PG8_BAR __builtin_amdgcn_s_barrier()
; #define PG8_SCHED __builtin_amdgcn_sched_barrier(0)
; template <class Epi>
; __device__ __forceinline__ void gemm_phase(LAS unsigned char* lds, const Gemm g, const StaticOrder& S, const Epi& E) {
;     ...
;             const bool last = (t == nt - 2);
;             const char* a1 = cA + (size_t)(t + 1) * kstep;
;             const char* a2 = last ? nA : cA + (size_t)(t + 2) * kstep; const char* b2 = last ? nB : cB + (size_t)(t + 2) * kstep;
;             const char* a3 = a2 + kstep; const char* b3 = b2 + kstep;
;             PG8_LDB(B0, 0, 0); PG8_LDB(B1, 0, 1); PG8_SCHED; PG8_LDA(At, 0, 0); PG8_STAGE(PG8_SA(1, 1), a1 + hstepA, voffA);
;             PG8_WAIT_V(8); PG8_WAIT_L(0); PG8_BAR; PG8_MMA(0, 0, At, B0); PG8_MMA(0, 1, At, B1); PG8_BAR; PG8_SCHED;
;             PG8_LDA(At, 0, 1); PG8_STAGE(PG8_SB(0, 0), b2, voffB); PG8_STAGE(PG8_SB(0, 1), b2 + hstepB, voffB); PG8_STAGE(PG8_SA(0, 0), a2, voffA);
;             PG8_WAIT_V(8); PG8_WAIT_L(0); PG8_BAR; PG8_MMA(1, 0, At, B0); PG8_MMA(1, 1, At, B1); PG8_BAR; PG8_SCHED;
.LBB0_1244:
	ds_read_b128 v[150:153], v187
	ds_read_b128 v[154:157], v187 offset:1024
	ds_read_b128 v[158:161], v187 offset:2048
	ds_read_b128 v[162:165], v187 offset:3072
	ds_read_b128 v[166:169], v188
	ds_read_b128 v[170:173], v188 offset:1024
	ds_read_b128 v[174:177], v188 offset:2048
	ds_read_b128 v[178:181], v188 offset:3072
	s_add_i32 s84, s52, 2
	s_add_u32 s12, s4, 0x100
	s_addc_u32 s13, s5, 0
	s_cmp_eq_u32 s67, s52
	s_cselect_b32 s52, s50, s1
	s_cselect_b32 s55, s49, s13
	s_cselect_b32 s54, s48, s12
	s_cselect_b32 s53, s51, s77
	v_lshl_add_u64 v[224:225], s[4:5], 0, v[142:143]
	s_add_i32 m0, s59, 0xc000
	ds_read_b128 v[182:185], v189
	ds_read_b128 v[192:195], v189 offset:1024
	ds_read_b128 v[196:199], v189 offset:2048
	ds_read_b128 v[200:203], v189 offset:3072
	ds_read_b128 v[208:211], v189 offset:4096
	ds_read_b128 v[212:215], v189 offset:5120
	ds_read_b128 v[216:219], v189 offset:6144
	ds_read_b128 v[220:223], v189 offset:7168
	global_load_lds_dwordx4 v[224:225], off
	v_lshl_add_u64 v[224:225], s[4:5], 0, v[144:145]
	s_add_i32 m0, s59, 0xe000
	s_nop 0
	global_load_lds_dwordx4 v[224:225], off
	s_waitcnt vmcnt(8)
	s_waitcnt lgkmcnt(0)
	s_barrier
	s_setprio 1
	s_waitcnt lgkmcnt(0)
	v_mfma_f32_16x16x32_bf16 v[124:127], v[150:153], v[182:185], v[124:127]
	v_mfma_f32_16x16x32_bf16 v[124:127], v[154:157], v[192:195], v[124:127]
	v_mfma_f32_16x16x32_bf16 v[116:119], v[154:157], v[200:203], v[116:119]
	v_mfma_f32_16x16x32_bf16 v[116:119], v[150:153], v[196:199], v[116:119]
	v_mfma_f32_16x16x32_bf16 v[104:107], v[150:153], v[208:211], v[104:107]
	v_mfma_f32_16x16x32_bf16 v[104:107], v[154:157], v[212:215], v[104:107]
	v_mfma_f32_16x16x32_bf16 v[88:91], v[154:157], v[220:223], v[88:91]
	v_mfma_f32_16x16x32_bf16 v[88:91], v[150:153], v[216:219], v[88:91]
	v_mfma_f32_16x16x32_bf16 v[80:83], v[158:161], v[216:219], v[80:83]
	v_mfma_f32_16x16x32_bf16 v[80:83], v[162:165], v[220:223], v[80:83]
	v_mfma_f32_16x16x32_bf16 v[96:99], v[162:165], v[212:215], v[96:99]
	v_mfma_f32_16x16x32_bf16 v[96:99], v[158:161], v[208:211], v[96:99]
	v_mfma_f32_16x16x32_bf16 v[112:115], v[158:161], v[196:199], v[112:115]
	v_mfma_f32_16x16x32_bf16 v[112:115], v[162:165], v[200:203], v[112:115]
	v_mfma_f32_16x16x32_bf16 v[120:123], v[162:165], v[192:195], v[120:123]
	v_mfma_f32_16x16x32_bf16 v[120:123], v[158:161], v[182:185], v[120:123]
	s_setprio 0
	s_setprio 1
	v_mfma_f32_16x16x32_bf16 v[108:111], v[166:169], v[182:185], v[108:111]
	v_mfma_f32_16x16x32_bf16 v[108:111], v[170:173], v[192:195], v[108:111]
	v_mfma_f32_16x16x32_bf16 v[92:95], v[170:173], v[200:203], v[92:95]
	v_mfma_f32_16x16x32_bf16 v[92:95], v[166:169], v[196:199], v[92:95]
	v_mfma_f32_16x16x32_bf16 v[76:79], v[166:169], v[208:211], v[76:79]
	v_mfma_f32_16x16x32_bf16 v[76:79], v[170:173], v[212:215], v[76:79]
	v_mfma_f32_16x16x32_bf16 v[68:71], v[170:173], v[220:223], v[68:71]
	v_mfma_f32_16x16x32_bf16 v[68:71], v[166:169], v[216:219], v[68:71]
	v_mfma_f32_16x16x32_bf16 v[64:67], v[174:177], v[216:219], v[64:67]
	v_mfma_f32_16x16x32_bf16 v[64:67], v[178:181], v[220:223], v[64:67]
	v_mfma_f32_16x16x32_bf16 v[72:75], v[178:181], v[212:215], v[72:75]
	v_mfma_f32_16x16x32_bf16 v[72:75], v[174:177], v[208:211], v[72:75]
	v_mfma_f32_16x16x32_bf16 v[84:87], v[174:177], v[196:199], v[84:87]
	v_mfma_f32_16x16x32_bf16 v[84:87], v[178:181], v[200:203], v[84:87]
	v_mfma_f32_16x16x32_bf16 v[100:103], v[178:181], v[192:195], v[100:103]
	v_mfma_f32_16x16x32_bf16 v[100:103], v[174:177], v[182:185], v[100:103]
	s_setprio 0
	s_barrier
	s_add_i32 s4, s70, s58
	v_lshl_add_u64 v[224:225], s[52:53], 0, v[130:131]
	s_mov_b32 m0, s4
	ds_read_b128 v[182:185], v189 offset:16384
	ds_read_b128 v[192:195], v189 offset:17408
	ds_read_b128 v[196:199], v189 offset:18432
	ds_read_b128 v[200:203], v189 offset:19456
	ds_read_b128 v[208:211], v189 offset:20480
	ds_read_b128 v[212:215], v189 offset:21504
	ds_read_b128 v[216:219], v189 offset:22528
	ds_read_b128 v[220:223], v189 offset:23552
	global_load_lds_dwordx4 v[224:225], off
	s_add_i32 m0, s4, 0x2000
	s_add_u32 s4, s52, 0x158000
	v_lshl_add_u64 v[226:227], s[52:53], 0, v[134:135]
	s_addc_u32 s5, s53, 0
	s_add_i32 s85, s71, s58
	global_load_lds_dwordx4 v[226:227], off
	v_lshl_add_u64 v[230:231], s[4:5], 0, v[130:131]
	s_mov_b32 m0, s85
	v_lshl_add_u64 v[232:233], s[54:55], 0, v[132:133]
	global_load_lds_dwordx4 v[230:231], off
	v_lshl_add_u64 v[230:231], s[4:5], 0, v[134:135]
	s_add_i32 m0, s85, 0x2000
	s_nop 0
	global_load_lds_dwordx4 v[230:231], off
	v_lshl_add_u64 v[230:231], s[54:55], 0, v[128:129]
	s_mov_b32 m0, s59
	s_nop 0
	global_load_lds_dwordx4 v[230:231], off
	s_mov_b32 m0, s60
	s_nop 0
	global_load_lds_dwordx4 v[232:233], off
	s_waitcnt vmcnt(8)
	s_waitcnt lgkmcnt(0)
	s_barrier
; #define PG8_STAGE(bufoff, gbase, voff) do { _Pragma("unroll") for (int _i = 0; _i < 2; ++_i) \
;         __builtin_amdgcn_global_load_lds((const unsigned*)((const char*)(gbase) + (voff)[_i]), (LAS unsigned*)(lds + (bufoff) + ldsw + _i * 8192), 16, 0, 0); } while (0)
; #define PG8_LDA(dst, b, h) do { _Pragma("unroll") for (int m = 0; m < 4; ++m) _Pragma("unroll") for (int k = 0; k < 2; ++k) dst[m][k] = *(const LAS bf16x8*)(lds + PG8_SA(b, h) + aoff + m * 2048 + k * 1024); } while (0)
; #define PG8_LDB(dst, b, h) do { _Pragma("unroll") for (int n = 0; n < 2; ++n) _Pragma("unroll") for (int k = 0; k < 2; ++k) dst[n][k] = *(const LAS bf16x8*)(lds + PG8_SB(b, h) + boff + n * 2048 + k * 1024); } while (0)
; #define PG8_MMA(ai, bj, At, Bt) do { __builtin_amdgcn_s_setprio(1); _Pragma("unroll") for (int m = 0; m < 4; ++m) _Pragma("unroll") for (int n = 0; n < 2; ++n) _Pragma("unroll") for (int k = 0; k < 2; ++k) \
;         acc[ai][bj][m][n] = __builtin_amdgcn_mfma_f32_16x16x32_bf16(Bt[n][k], At[m][k], acc[ai][bj][m][n], 0, 0, 0); __builtin_amdgcn_s_setprio(0); } while (0)
; #define PG8_WAIT_V(n) asm volatile("s_waitcnt vmcnt(" #n ")" ::: "memory")
; #define PG8_WAIT_L(n) asm volatile("s_waitcnt lgkmcnt(" #n ")" ::: "memory")
; #define PG8_BAR __builtin_amdgcn_s_barrier()
; #define PG8_SCHED __builtin_amdgcn_sched_barrier(0)
; template <class Epi>
; __device__ __forceinline__ void gemm_phase(LAS unsigned char* lds, const Gemm g, const StaticOrder& S, const Epi& E) {
;     ...
;             PG8_WAIT_V(8); PG8_WAIT_L(0); PG8_BAR; PG8_MMA(1, 0, At, B0); PG8_MMA(1, 1, At, B1); PG8_BAR; PG8_SCHED;
;             PG8_LDB(B0, 1, 0); PG8_LDB(B1, 1, 1); PG8_SCHED; PG8_LDA(At, 1, 0); PG8_STAGE(PG8_SA(0, 1), a2 + hstepA, voffA);
;             PG8_WAIT_V(8); PG8_WAIT_L(0); PG8_BAR; PG8_MMA(0, 0, At, B0); PG8_MMA(0, 1, At, B1); PG8_BAR; PG8_SCHED;
	s_setprio 1
	s_waitcnt lgkmcnt(0)
	v_mfma_f32_16x16x32_bf16 v[60:63], v[150:153], v[182:185], v[60:63]
	v_mfma_f32_16x16x32_bf16 v[60:63], v[154:157], v[192:195], v[60:63]
	v_mfma_f32_16x16x32_bf16 v[52:55], v[154:157], v[200:203], v[52:55]
	v_mfma_f32_16x16x32_bf16 v[52:55], v[150:153], v[196:199], v[52:55]
	v_mfma_f32_16x16x32_bf16 v[40:43], v[150:153], v[208:211], v[40:43]
	v_mfma_f32_16x16x32_bf16 v[40:43], v[154:157], v[212:215], v[40:43]
	v_mfma_f32_16x16x32_bf16 v[24:27], v[154:157], v[220:223], v[24:27]
	v_mfma_f32_16x16x32_bf16 v[24:27], v[150:153], v[216:219], v[24:27]
	v_mfma_f32_16x16x32_bf16 v[16:19], v[158:161], v[216:219], v[16:19]
	v_mfma_f32_16x16x32_bf16 v[16:19], v[162:165], v[220:223], v[16:19]
	v_mfma_f32_16x16x32_bf16 v[32:35], v[162:165], v[212:215], v[32:35]
	v_mfma_f32_16x16x32_bf16 v[32:35], v[158:161], v[208:211], v[32:35]
	v_mfma_f32_16x16x32_bf16 v[48:51], v[158:161], v[196:199], v[48:51]
	v_mfma_f32_16x16x32_bf16 v[48:51], v[162:165], v[200:203], v[48:51]
	v_mfma_f32_16x16x32_bf16 v[56:59], v[162:165], v[192:195], v[56:59]
	v_mfma_f32_16x16x32_bf16 v[56:59], v[158:161], v[182:185], v[56:59]
	s_setprio 0
	s_setprio 1
	v_mfma_f32_16x16x32_bf16 v[44:47], v[166:169], v[182:185], v[44:47]
	v_mfma_f32_16x16x32_bf16 v[44:47], v[170:173], v[192:195], v[44:47]
	v_mfma_f32_16x16x32_bf16 v[28:31], v[170:173], v[200:203], v[28:31]
	v_mfma_f32_16x16x32_bf16 v[28:31], v[166:169], v[196:199], v[28:31]
	v_mfma_f32_16x16x32_bf16 v[12:15], v[166:169], v[208:211], v[12:15]
	v_mfma_f32_16x16x32_bf16 v[12:15], v[170:173], v[212:215], v[12:15]
	v_mfma_f32_16x16x32_bf16 v[4:7], v[170:173], v[220:223], v[4:7]
	v_mfma_f32_16x16x32_bf16 v[4:7], v[166:169], v[216:219], v[4:7]
	v_mfma_f32_16x16x32_bf16 v[0:3], v[174:177], v[216:219], v[0:3]
	v_mfma_f32_16x16x32_bf16 v[0:3], v[178:181], v[220:223], v[0:3]
	v_mfma_f32_16x16x32_bf16 v[8:11], v[178:181], v[212:215], v[8:11]
	v_mfma_f32_16x16x32_bf16 v[8:11], v[174:177], v[208:211], v[8:11]
	v_mfma_f32_16x16x32_bf16 v[20:23], v[174:177], v[196:199], v[20:23]
	v_mfma_f32_16x16x32_bf16 v[20:23], v[178:181], v[200:203], v[20:23]
	v_mfma_f32_16x16x32_bf16 v[36:39], v[178:181], v[192:195], v[36:39]
	v_mfma_f32_16x16x32_bf16 v[36:39], v[174:177], v[182:185], v[36:39]
	s_setprio 0
	s_barrier
	s_add_i32 s85, 0, 0x18000
	s_add_i32 s86, 0, 0x1c000
	v_add_u32_e32 v162, s85, v186
	v_add_u32_e32 v178, s86, v186
	ds_read_b128 v[150:153], v162
	ds_read_b128 v[154:157], v162 offset:1024
	ds_read_b128 v[158:161], v162 offset:2048
	ds_read_b128 v[162:165], v162 offset:3072
	ds_read_b128 v[166:169], v178
	ds_read_b128 v[170:173], v178 offset:1024
	ds_read_b128 v[174:177], v178 offset:2048
	ds_read_b128 v[178:181], v178 offset:3072
	s_add_u32 s4, s54, 0x158000
	s_addc_u32 s5, s55, 0
	s_mov_b32 m0, s61
	v_lshl_add_u64 v[234:235], s[4:5], 0, v[128:129]
	ds_read_b128 v[182:185], v189 offset:32768
	ds_read_b128 v[192:195], v189 offset:33792
	ds_read_b128 v[196:199], v189 offset:34816
	ds_read_b128 v[200:203], v189 offset:35840
	ds_read_b128 v[208:211], v189 offset:36864
	ds_read_b128 v[212:215], v189 offset:37888
	ds_read_b128 v[216:219], v189 offset:38912
	ds_read_b128 v[220:223], v189 offset:39936
	global_load_lds_dwordx4 v[234:235], off
	v_lshl_add_u64 v[234:235], s[4:5], 0, v[132:133]
	s_mov_b32 m0, s62
	s_nop 0
	global_load_lds_dwordx4 v[234:235], off
	s_waitcnt vmcnt(8)
	s_waitcnt lgkmcnt(0)
	s_barrier
	s_setprio 1
	s_waitcnt lgkmcnt(0)
	v_mfma_f32_16x16x32_bf16 v[124:127], v[150:153], v[182:185], v[124:127]
	v_mfma_f32_16x16x32_bf16 v[124:127], v[154:157], v[192:195], v[124:127]
	v_mfma_f32_16x16x32_bf16 v[116:119], v[154:157], v[200:203], v[116:119]
	v_mfma_f32_16x16x32_bf16 v[116:119], v[150:153], v[196:199], v[116:119]
	v_mfma_f32_16x16x32_bf16 v[104:107], v[150:153], v[208:211], v[104:107]
	v_mfma_f32_16x16x32_bf16 v[104:107], v[154:157], v[212:215], v[104:107]
	v_mfma_f32_16x16x32_bf16 v[88:91], v[154:157], v[220:223], v[88:91]
	v_mfma_f32_16x16x32_bf16 v[88:91], v[150:153], v[216:219], v[88:91]
	v_mfma_f32_16x16x32_bf16 v[80:83], v[158:161], v[216:219], v[80:83]
	v_mfma_f32_16x16x32_bf16 v[80:83], v[162:165], v[220:223], v[80:83]
	v_mfma_f32_16x16x32_bf16 v[96:99], v[162:165], v[212:215], v[96:99]
	v_mfma_f32_16x16x32_bf16 v[96:99], v[158:161], v[208:211], v[96:99]
	v_mfma_f32_16x16x32_bf16 v[112:115], v[158:161], v[196:199], v[112:115]
	v_mfma_f32_16x16x32_bf16 v[112:115], v[162:165], v[200:203], v[112:115]
	v_mfma_f32_16x16x32_bf16 v[120:123], v[162:165], v[192:195], v[120:123]
	v_mfma_f32_16x16x32_bf16 v[120:123], v[158:161], v[182:185], v[120:123]
	s_setprio 0
	s_setprio 1
	v_mfma_f32_16x16x32_bf16 v[108:111], v[166:169], v[182:185], v[108:111]
	v_mfma_f32_16x16x32_bf16 v[108:111], v[170:173], v[192:195], v[108:111]
	v_mfma_f32_16x16x32_bf16 v[92:95], v[170:173], v[200:203], v[92:95]
	v_mfma_f32_16x16x32_bf16 v[92:95], v[166:169], v[196:199], v[92:95]
	v_mfma_f32_16x16x32_bf16 v[76:79], v[166:169], v[208:211], v[76:79]
	v_mfma_f32_16x16x32_bf16 v[76:79], v[170:173], v[212:215], v[76:79]
	v_mfma_f32_16x16x32_bf16 v[68:71], v[170:173], v[220:223], v[68:71]
	v_mfma_f32_16x16x32_bf16 v[68:71], v[166:169], v[216:219], v[68:71]
	v_mfma_f32_16x16x32_bf16 v[64:67], v[174:177], v[216:219], v[64:67]
	v_mfma_f32_16x16x32_bf16 v[64:67], v[178:181], v[220:223], v[64:67]
	v_mfma_f32_16x16x32_bf16 v[72:75], v[178:181], v[212:215], v[72:75]
	v_mfma_f32_16x16x32_bf16 v[72:75], v[174:177], v[208:211], v[72:75]
	v_mfma_f32_16x16x32_bf16 v[84:87], v[174:177], v[196:199], v[84:87]
	v_mfma_f32_16x16x32_bf16 v[84:87], v[178:181], v[200:203], v[84:87]
	v_mfma_f32_16x16x32_bf16 v[100:103], v[178:181], v[192:195], v[100:103]
	v_mfma_f32_16x16x32_bf16 v[100:103], v[174:177], v[182:185], v[100:103]
	s_setprio 0
	s_barrier
; #define PG8_STAGE(bufoff, gbase, voff) do { _Pragma("unroll") for (int _i = 0; _i < 2; ++_i) \
;         __builtin_amdgcn_global_load_lds((const unsigned*)((const char*)(gbase) + (voff)[_i]), (LAS unsigned*)(lds + (bufoff) + ldsw + _i * 8192), 16, 0, 0); } while (0)
; #define PG8_LDA(dst, b, h) do { _Pragma("unroll") for (int m = 0; m < 4; ++m) _Pragma("unroll") for (int k = 0; k < 2; ++k) dst[m][k] = *(const LAS bf16x8*)(lds + PG8_SA(b, h) + aoff + m * 2048 + k * 1024); } while (0)
; #define PG8_MMA(ai, bj, At, Bt) do { __builtin_amdgcn_s_setprio(1); _Pragma("unroll") for (int m = 0; m < 4; ++m) _Pragma("unroll") for (int n = 0; n < 2; ++n) _Pragma("unroll") for (int k = 0; k < 2; ++k) \
;         acc[ai][bj][m][n] = __builtin_amdgcn_mfma_f32_16x16x32_bf16(Bt[n][k], At[m][k], acc[ai][bj][m][n], 0, 0, 0); __builtin_amdgcn_s_setprio(0); } while (0)
; #define PG8_WAIT_V(n) asm volatile("s_waitcnt vmcnt(" #n ")" ::: "memory")
; #define PG8_WAIT_L(n) asm volatile("s_waitcnt lgkmcnt(" #n ")" ::: "memory")
; #define PG8_BAR __builtin_amdgcn_s_barrier()
; #define PG8_SCHED __builtin_amdgcn_sched_barrier(0)
; template <class Epi>
; __device__ __forceinline__ void gemm_phase(LAS unsigned char* lds, const Gemm g, const StaticOrder& S, const Epi& E) {
;     ...
;             PG8_LDA(At, 1, 1); PG8_STAGE(PG8_SB(1, 0), b3, voffB); PG8_STAGE(PG8_SB(1, 1), b3 + hstepB, voffB); PG8_STAGE(PG8_SA(1, 0), a3, voffA);
;             PG8_WAIT_V(8); PG8_WAIT_L(0); PG8_BAR; PG8_MMA(1, 0, At, B0); PG8_MMA(1, 1, At, B1); PG8_BAR; PG8_SCHED;
;         }
	s_add_i32 s4, s85, s58
	v_lshl_add_u64 v[224:225], v[224:225], 0, s[16:17]
	s_mov_b32 m0, s4
	ds_read_b128 v[182:185], v189 offset:49152
	ds_read_b128 v[192:195], v189 offset:50176
	ds_read_b128 v[196:199], v189 offset:51200
	ds_read_b128 v[200:203], v189 offset:52224
	ds_read_b128 v[208:211], v189 offset:53248
	ds_read_b128 v[212:215], v189 offset:54272
	ds_read_b128 v[216:219], v189 offset:55296
	ds_read_b128 v[220:223], v189 offset:56320
	global_load_lds_dwordx4 v[224:225], off
	s_add_i32 m0, s4, 0x2000
	s_add_u32 s4, s52, 0x158080
	v_lshl_add_u64 v[224:225], v[226:227], 0, s[16:17]
	s_addc_u32 s5, s53, 0
	s_add_i32 s52, s86, s58
	global_load_lds_dwordx4 v[224:225], off
	v_lshl_add_u64 v[224:225], s[4:5], 0, v[130:131]
	s_mov_b32 m0, s52
	s_nop 0
	global_load_lds_dwordx4 v[224:225], off
	v_lshl_add_u64 v[224:225], s[4:5], 0, v[134:135]
	s_add_i32 m0, s52, 0x2000
	s_nop 0
	global_load_lds_dwordx4 v[224:225], off
	v_lshl_add_u64 v[224:225], v[230:231], 0, s[16:17]
	s_mov_b32 m0, s65
	s_nop 0
	global_load_lds_dwordx4 v[224:225], off
	v_lshl_add_u64 v[224:225], v[232:233], 0, s[16:17]
	s_mov_b32 m0, s66
	s_nop 0
	global_load_lds_dwordx4 v[224:225], off
	s_waitcnt vmcnt(8)
	s_waitcnt lgkmcnt(0)
	s_barrier
	s_setprio 1
	s_waitcnt lgkmcnt(0)
	v_mfma_f32_16x16x32_bf16 v[60:63], v[150:153], v[182:185], v[60:63]
	v_mfma_f32_16x16x32_bf16 v[60:63], v[154:157], v[192:195], v[60:63]
	v_mfma_f32_16x16x32_bf16 v[52:55], v[154:157], v[200:203], v[52:55]
	v_mfma_f32_16x16x32_bf16 v[52:55], v[150:153], v[196:199], v[52:55]
	v_mfma_f32_16x16x32_bf16 v[40:43], v[150:153], v[208:211], v[40:43]
	v_mfma_f32_16x16x32_bf16 v[40:43], v[154:157], v[212:215], v[40:43]
	v_mfma_f32_16x16x32_bf16 v[24:27], v[154:157], v[220:223], v[24:27]
	v_mfma_f32_16x16x32_bf16 v[24:27], v[150:153], v[216:219], v[24:27]
	v_mfma_f32_16x16x32_bf16 v[16:19], v[158:161], v[216:219], v[16:19]
	v_mfma_f32_16x16x32_bf16 v[16:19], v[162:165], v[220:223], v[16:19]
	v_mfma_f32_16x16x32_bf16 v[32:35], v[162:165], v[212:215], v[32:35]
	v_mfma_f32_16x16x32_bf16 v[32:35], v[158:161], v[208:211], v[32:35]
	v_mfma_f32_16x16x32_bf16 v[48:51], v[158:161], v[196:199], v[48:51]
	v_mfma_f32_16x16x32_bf16 v[48:51], v[162:165], v[200:203], v[48:51]
	v_mfma_f32_16x16x32_bf16 v[56:59], v[162:165], v[192:195], v[56:59]
	v_mfma_f32_16x16x32_bf16 v[56:59], v[158:161], v[182:185], v[56:59]
	s_setprio 0
	s_setprio 1
	v_mfma_f32_16x16x32_bf16 v[44:47], v[166:169], v[182:185], v[44:47]
	v_mfma_f32_16x16x32_bf16 v[44:47], v[170:173], v[192:195], v[44:47]
	v_mfma_f32_16x16x32_bf16 v[28:31], v[170:173], v[200:203], v[28:31]
	v_mfma_f32_16x16x32_bf16 v[28:31], v[166:169], v[196:199], v[28:31]
	v_mfma_f32_16x16x32_bf16 v[12:15], v[166:169], v[208:211], v[12:15]
	v_mfma_f32_16x16x32_bf16 v[12:15], v[170:173], v[212:215], v[12:15]
	v_mfma_f32_16x16x32_bf16 v[4:7], v[170:173], v[220:223], v[4:7]
	v_mfma_f32_16x16x32_bf16 v[4:7], v[166:169], v[216:219], v[4:7]
	v_mfma_f32_16x16x32_bf16 v[0:3], v[174:177], v[216:219], v[0:3]
	v_mfma_f32_16x16x32_bf16 v[0:3], v[178:181], v[220:223], v[0:3]
	v_mfma_f32_16x16x32_bf16 v[8:11], v[178:181], v[212:215], v[8:11]
	v_mfma_f32_16x16x32_bf16 v[8:11], v[174:177], v[208:211], v[8:11]
	v_mfma_f32_16x16x32_bf16 v[20:23], v[174:177], v[196:199], v[20:23]
	v_mfma_f32_16x16x32_bf16 v[20:23], v[178:181], v[200:203], v[20:23]
	v_mfma_f32_16x16x32_bf16 v[36:39], v[178:181], v[192:195], v[36:39]
	v_mfma_f32_16x16x32_bf16 v[36:39], v[174:177], v[182:185], v[36:39]
	s_setprio 0
	s_barrier
	s_add_u32 s1, s1, 0x100
	s_addc_u32 s77, s77, 0
	s_cmp_ge_i32 s84, s64
	s_mov_b64 s[4:5], s[12:13]
	s_mov_b32 s52, s84
	s_cbranch_scc0 .LBB0_1244
	v_pk_mul_f32 v[170:171], v[126:127], 0.5 op_sel_hi:[1,0]
	v_pk_mul_f32 v[172:173], v[124:125], 0.5 op_sel_hi:[1,0]
	v_pk_mul_f32 v[174:175], v[122:123], 0.5 op_sel_hi:[1,0]
	v_pk_mul_f32 v[176:177], v[120:121], 0.5 op_sel_hi:[1,0]
	v_pk_mul_f32 v[178:179], v[110:111], 0.5 op_sel_hi:[1,0]
	v_pk_mul_f32 v[180:181], v[108:109], 0.5 op_sel_hi:[1,0]
	v_pk_mul_f32 v[182:183], v[102:103], 0.5 op_sel_hi:[1,0]
	v_pk_mul_f32 v[184:185], v[100:101], 0.5 op_sel_hi:[1,0]
	v_pk_mul_f32 v[160:161], v[118:119], 0.5 op_sel_hi:[1,0]
	v_pk_mul_f32 v[158:159], v[116:117], 0.5 op_sel_hi:[1,0]
	v_pk_mul_f32 v[156:157], v[114:115], 0.5 op_sel_hi:[1,0]
	v_pk_mul_f32 v[154:155], v[112:113], 0.5 op_sel_hi:[1,0]
	v_pk_mul_f32 v[168:169], v[94:95], 0.5 op_sel_hi:[1,0]
	v_pk_mul_f32 v[166:167], v[92:93], 0.5 op_sel_hi:[1,0]
	v_pk_mul_f32 v[164:165], v[86:87], 0.5 op_sel_hi:[1,0]
	v_pk_mul_f32 v[162:163], v[84:85], 0.5 op_sel_hi:[1,0]
	v_pk_mul_f32 v[116:117], v[106:107], 0.5 op_sel_hi:[1,0]
	v_pk_mul_f32 v[118:119], v[104:105], 0.5 op_sel_hi:[1,0]
	v_pk_mul_f32 v[120:121], v[98:99], 0.5 op_sel_hi:[1,0]
	v_pk_mul_f32 v[122:123], v[96:97], 0.5 op_sel_hi:[1,0]
	v_pk_mul_f32 v[124:125], v[78:79], 0.5 op_sel_hi:[1,0]
	v_pk_mul_f32 v[126:127], v[76:77], 0.5 op_sel_hi:[1,0]
	v_pk_mul_f32 v[150:151], v[74:75], 0.5 op_sel_hi:[1,0]
	v_pk_mul_f32 v[152:153], v[72:73], 0.5 op_sel_hi:[1,0]
	v_pk_mul_f32 v[104:105], v[90:91], 0.5 op_sel_hi:[1,0]
	v_pk_mul_f32 v[102:103], v[88:89], 0.5 op_sel_hi:[1,0]
	v_pk_mul_f32 v[100:101], v[82:83], 0.5 op_sel_hi:[1,0]
	v_pk_mul_f32 v[98:99], v[80:81], 0.5 op_sel_hi:[1,0]
	v_pk_mul_f32 v[112:113], v[70:71], 0.5 op_sel_hi:[1,0]
	v_pk_mul_f32 v[110:111], v[68:69], 0.5 op_sel_hi:[1,0]
	v_pk_mul_f32 v[108:109], v[66:67], 0.5 op_sel_hi:[1,0]
	v_pk_mul_f32 v[106:107], v[64:65], 0.5 op_sel_hi:[1,0]
	v_pk_mul_f32 v[80:81], v[62:63], 0.5 op_sel_hi:[1,0]
	v_pk_mul_f32 v[82:83], v[60:61], 0.5 op_sel_hi:[1,0]
	v_pk_mul_f32 v[84:85], v[58:59], 0.5 op_sel_hi:[1,0]
	v_pk_mul_f32 v[86:87], v[56:57], 0.5 op_sel_hi:[1,0]
	v_pk_mul_f32 v[88:89], v[46:47], 0.5 op_sel_hi:[1,0]
	v_pk_mul_f32 v[90:91], v[44:45], 0.5 op_sel_hi:[1,0]
	v_pk_mul_f32 v[92:93], v[38:39], 0.5 op_sel_hi:[1,0]
	v_pk_mul_f32 v[94:95], v[36:37], 0.5 op_sel_hi:[1,0]
	v_pk_mul_f32 v[70:71], v[54:55], 0.5 op_sel_hi:[1,0]
	v_pk_mul_f32 v[68:69], v[52:53], 0.5 op_sel_hi:[1,0]
	v_pk_mul_f32 v[66:67], v[50:51], 0.5 op_sel_hi:[1,0]
	v_pk_mul_f32 v[64:65], v[48:49], 0.5 op_sel_hi:[1,0]
	v_pk_mul_f32 v[78:79], v[30:31], 0.5 op_sel_hi:[1,0]
	v_pk_mul_f32 v[76:77], v[28:29], 0.5 op_sel_hi:[1,0]
	v_pk_mul_f32 v[74:75], v[22:23], 0.5 op_sel_hi:[1,0]
	v_pk_mul_f32 v[72:73], v[20:21], 0.5 op_sel_hi:[1,0]
	v_pk_mul_f32 v[54:55], v[42:43], 0.5 op_sel_hi:[1,0]
	v_pk_mul_f32 v[52:53], v[40:41], 0.5 op_sel_hi:[1,0]
	v_pk_mul_f32 v[50:51], v[34:35], 0.5 op_sel_hi:[1,0]
	v_pk_mul_f32 v[48:49], v[32:33], 0.5 op_sel_hi:[1,0]
	v_pk_mul_f32 v[62:63], v[14:15], 0.5 op_sel_hi:[1,0]
	v_pk_mul_f32 v[60:61], v[12:13], 0.5 op_sel_hi:[1,0]
	v_pk_mul_f32 v[58:59], v[10:11], 0.5 op_sel_hi:[1,0]
	v_pk_mul_f32 v[56:57], v[8:9], 0.5 op_sel_hi:[1,0]
	v_pk_mul_f32 v[38:39], v[26:27], 0.5 op_sel_hi:[1,0]
	v_pk_mul_f32 v[36:37], v[24:25], 0.5 op_sel_hi:[1,0]
	v_pk_mul_f32 v[34:35], v[18:19], 0.5 op_sel_hi:[1,0]
	v_pk_mul_f32 v[32:33], v[16:17], 0.5 op_sel_hi:[1,0]
	v_pk_mul_f32 v[46:47], v[6:7], 0.5 op_sel_hi:[1,0]
	v_pk_mul_f32 v[44:45], v[4:5], 0.5 op_sel_hi:[1,0]
	v_pk_mul_f32 v[42:43], v[2:3], 0.5 op_sel_hi:[1,0]
	v_pk_mul_f32 v[40:41], v[0:1], 0.5 op_sel_hi:[1,0]

; #define PG8_STAGE(bufoff, gbase, voff) do { _Pragma("unroll") for (int _i = 0; _i < 2; ++_i) \
;         __builtin_amdgcn_global_load_lds((const unsigned*)((const char*)(gbase) + (voff)[_i]), (LAS unsigned*)(lds + (bufoff) + ldsw + _i * 8192), 16, 0, 0); } while (0)
; #define PG8_LDA(dst, b, h) do { _Pragma("unroll") for (int m = 0; m < 4; ++m) _Pragma("unroll") for (int k = 0; k < 2; ++k) dst[m][k] = *(const LAS bf16x8*)(lds + PG8_SA(b, h) + aoff + m * 2048 + k * 1024); } while (0)
; #define PG8_LDB(dst, b, h) do { _Pragma("unroll") for (int n = 0; n < 2; ++n) _Pragma("unroll") for (int k = 0; k < 2; ++k) dst[n][k] = *(const LAS bf16x8*)(lds + PG8_SB(b, h) + boff + n * 2048 + k * 1024); } while (0)
; #define PG8_MMA(ai, bj, At, Bt) do { __builtin_amdgcn_s_setprio(1); _Pragma("unroll") for (int m = 0; m < 4; ++m) _Pragma("unroll") for (int n = 0; n < 2; ++n) _Pragma("unroll") for (int k = 0; k < 2; ++k) \
;         acc[ai][bj][m][n] = __builtin_amdgcn_mfma_f32_16x16x32_bf16(Bt[n][k], At[m][k], acc[ai][bj][m][n], 0, 0, 0); __builtin_amdgcn_s_setprio(0); } while (0)
; #define PG8_WAIT_V(n) asm volatile("s_waitcnt vmcnt(" #n ")" ::: "memory")
; template <class Epi>
; __device__ __forceinline__ void gemm_phase(LAS unsigned char* lds, const Gemm g, const StaticOrder& S, const Epi& E) {
;     ...
;         const bool has_next = S.next(ui + 1, nxt);
;         const char* nA = has_next ? (const char*)g.A + (size_t)nxt.pm * tstepA : cA; const char* nB = has_next ? (const char*)g.Bt + (size_t)nxt.pb * tstepB : cB;
;         for (int t = 0; t < nt; t += 2) {
;             const bool last = (t == nt - 2);
;             const char* a1 = cA + (size_t)(t + 1) * kstep;
;             const char* a2 = last ? nA : cA + (size_t)(t + 2) * kstep; const char* b2 = last ? nB : cB + (size_t)(t + 2) * kstep;
;             const char* a3 = a2 + kstep; const char* b3 = b2 + kstep;
;             PG8_LDB(B0, 0, 0); PG8_LDB(B1, 0, 1); PG8_SCHED; PG8_LDA(At, 0, 0); PG8_STAGE(PG8_SA(1, 1), a1 + hstepA, voffA);
;             PG8_WAIT_V(8); PG8_WAIT_L(0); PG8_BAR; PG8_MMA(0, 0, At, B0); PG8_MMA(0, 1, At, B1); PG8_BAR; PG8_SCHED;
;             PG8_LDA(At, 0, 1); PG8_STAGE(PG8_SB(0, 0), b2, voffB); PG8_STAGE(PG8_SB(0, 1), b2 + hstepB, voffB); PG8_STAGE(PG8_SA(0, 0), a2, voffA);
;             PG8_WAIT_V(8); PG8_WAIT_L(0); PG8_BAR; PG8_MMA(1, 0, At, B0); PG8_MMA(1, 1, At, B1); PG8_BAR; PG8_SCHED;
.LBB0_1338:
	ds_read_b128 v[128:131], v173
	ds_read_b128 v[132:135], v173 offset:1024
	ds_read_b128 v[136:139], v173 offset:2048
	ds_read_b128 v[140:143], v173 offset:3072
	ds_read_b128 v[144:147], v175
	ds_read_b128 v[148:151], v175 offset:1024
	ds_read_b128 v[176:179], v175 offset:2048
	ds_read_b128 v[184:187], v175 offset:3072
	s_add_i32 s20, s10, 2
	s_add_u32 s11, s8, 0xfff80080
	s_addc_u32 s12, s9, -1
	s_cmp_eq_u32 s56, s10
	s_cselect_b32 s10, s17, s18
	s_cselect_b32 s13, s1, s12
	s_cselect_b32 s12, s15, s11
	s_cselect_b32 s11, s16, s19
	v_lshl_add_u64 v[224:225], s[8:9], 0, v[164:165]
	s_add_i32 m0, s47, 0xc000
	ds_read_b128 v[188:191], v181
	ds_read_b128 v[192:195], v181 offset:1024
	ds_read_b128 v[196:199], v181 offset:2048
	ds_read_b128 v[200:203], v181 offset:3072
	ds_read_b128 v[208:211], v181 offset:4096
	ds_read_b128 v[212:215], v181 offset:5120
	ds_read_b128 v[216:219], v181 offset:6144
	ds_read_b128 v[220:223], v181 offset:7168
	global_load_lds_dwordx4 v[224:225], off
	v_lshl_add_u64 v[224:225], s[8:9], 0, v[166:167]
	s_add_i32 m0, s47, 0xe000
	s_nop 0
	global_load_lds_dwordx4 v[224:225], off
	s_waitcnt vmcnt(8)
	s_waitcnt lgkmcnt(0)
	s_barrier
	s_setprio 1
	s_waitcnt lgkmcnt(0)
	v_mfma_f32_16x16x32_bf16 v[124:127], v[128:131], v[188:191], v[124:127]
	v_mfma_f32_16x16x32_bf16 v[124:127], v[132:135], v[192:195], v[124:127]
	v_mfma_f32_16x16x32_bf16 v[108:111], v[132:135], v[200:203], v[108:111]
	v_mfma_f32_16x16x32_bf16 v[108:111], v[128:131], v[196:199], v[108:111]
	v_mfma_f32_16x16x32_bf16 v[92:95], v[128:131], v[208:211], v[92:95]
	v_mfma_f32_16x16x32_bf16 v[92:95], v[132:135], v[212:215], v[92:95]
	v_mfma_f32_16x16x32_bf16 v[76:79], v[132:135], v[220:223], v[76:79]
	v_mfma_f32_16x16x32_bf16 v[76:79], v[128:131], v[216:219], v[76:79]
	v_mfma_f32_16x16x32_bf16 v[72:75], v[136:139], v[216:219], v[72:75]
	v_mfma_f32_16x16x32_bf16 v[72:75], v[140:143], v[220:223], v[72:75]
	v_mfma_f32_16x16x32_bf16 v[88:91], v[140:143], v[212:215], v[88:91]
	v_mfma_f32_16x16x32_bf16 v[88:91], v[136:139], v[208:211], v[88:91]
	v_mfma_f32_16x16x32_bf16 v[104:107], v[136:139], v[196:199], v[104:107]
	v_mfma_f32_16x16x32_bf16 v[104:107], v[140:143], v[200:203], v[104:107]
	v_mfma_f32_16x16x32_bf16 v[120:123], v[140:143], v[192:195], v[120:123]
	v_mfma_f32_16x16x32_bf16 v[120:123], v[136:139], v[188:191], v[120:123]
	s_setprio 0
	s_setprio 1
	v_mfma_f32_16x16x32_bf16 v[116:119], v[144:147], v[188:191], v[116:119]
	v_mfma_f32_16x16x32_bf16 v[116:119], v[148:151], v[192:195], v[116:119]
	v_mfma_f32_16x16x32_bf16 v[100:103], v[148:151], v[200:203], v[100:103]
	v_mfma_f32_16x16x32_bf16 v[100:103], v[144:147], v[196:199], v[100:103]
	v_mfma_f32_16x16x32_bf16 v[84:87], v[144:147], v[208:211], v[84:87]
	v_mfma_f32_16x16x32_bf16 v[84:87], v[148:151], v[212:215], v[84:87]
	v_mfma_f32_16x16x32_bf16 v[68:71], v[148:151], v[220:223], v[68:71]
	v_mfma_f32_16x16x32_bf16 v[68:71], v[144:147], v[216:219], v[68:71]
	v_mfma_f32_16x16x32_bf16 v[64:67], v[176:179], v[216:219], v[64:67]
	v_mfma_f32_16x16x32_bf16 v[64:67], v[184:187], v[220:223], v[64:67]
	v_mfma_f32_16x16x32_bf16 v[80:83], v[184:187], v[212:215], v[80:83]
	v_mfma_f32_16x16x32_bf16 v[80:83], v[176:179], v[208:211], v[80:83]
	v_mfma_f32_16x16x32_bf16 v[96:99], v[176:179], v[196:199], v[96:99]
	v_mfma_f32_16x16x32_bf16 v[96:99], v[184:187], v[200:203], v[96:99]
	v_mfma_f32_16x16x32_bf16 v[112:115], v[184:187], v[192:195], v[112:115]
	v_mfma_f32_16x16x32_bf16 v[112:115], v[176:179], v[188:191], v[112:115]
	s_setprio 0
	s_barrier
	s_add_i32 s21, s59, s46
	v_lshl_add_u64 v[224:225], s[10:11], 0, v[154:155]
	s_mov_b32 m0, s21
	ds_read_b128 v[188:191], v181 offset:16384
	ds_read_b128 v[192:195], v181 offset:17408
	ds_read_b128 v[196:199], v181 offset:18432
	ds_read_b128 v[200:203], v181 offset:19456
	ds_read_b128 v[208:211], v181 offset:20480
	ds_read_b128 v[212:215], v181 offset:21504
	ds_read_b128 v[216:219], v181 offset:22528
	ds_read_b128 v[220:223], v181 offset:23552
	global_load_lds_dwordx4 v[224:225], off
	s_add_i32 m0, s21, 0x2000
	s_add_u32 s68, s10, 0x80000
	v_lshl_add_u64 v[226:227], s[10:11], 0, v[158:159]
	s_addc_u32 s69, s11, 0
	s_add_i32 s21, s60, s46
	global_load_lds_dwordx4 v[226:227], off
	v_lshl_add_u64 v[230:231], s[68:69], 0, v[154:155]
	s_mov_b32 m0, s21
	v_lshl_add_u64 v[232:233], s[12:13], 0, v[156:157]
	global_load_lds_dwordx4 v[230:231], off
	v_lshl_add_u64 v[230:231], s[68:69], 0, v[158:159]
	s_add_i32 m0, s21, 0x2000
	s_nop 0
	global_load_lds_dwordx4 v[230:231], off
	v_lshl_add_u64 v[230:231], s[12:13], 0, v[152:153]
	s_mov_b32 m0, s47
	s_nop 0
	global_load_lds_dwordx4 v[230:231], off
	s_mov_b32 m0, s48
	s_nop 0
	global_load_lds_dwordx4 v[232:233], off
	s_waitcnt vmcnt(8)
	s_waitcnt lgkmcnt(0)
	s_barrier
; #define PG8_STAGE(bufoff, gbase, voff) do { _Pragma("unroll") for (int _i = 0; _i < 2; ++_i) \
;         __builtin_amdgcn_global_load_lds((const unsigned*)((const char*)(gbase) + (voff)[_i]), (LAS unsigned*)(lds + (bufoff) + ldsw + _i * 8192), 16, 0, 0); } while (0)
; #define PG8_LDA(dst, b, h) do { _Pragma("unroll") for (int m = 0; m < 4; ++m) _Pragma("unroll") for (int k = 0; k < 2; ++k) dst[m][k] = *(const LAS bf16x8*)(lds + PG8_SA(b, h) + aoff + m * 2048 + k * 1024); } while (0)
; #define PG8_LDB(dst, b, h) do { _Pragma("unroll") for (int n = 0; n < 2; ++n) _Pragma("unroll") for (int k = 0; k < 2; ++k) dst[n][k] = *(const LAS bf16x8*)(lds + PG8_SB(b, h) + boff + n * 2048 + k * 1024); } while (0)
; #define PG8_MMA(ai, bj, At, Bt) do { __builtin_amdgcn_s_setprio(1); _Pragma("unroll") for (int m = 0; m < 4; ++m) _Pragma("unroll") for (int n = 0; n < 2; ++n) _Pragma("unroll") for (int k = 0; k < 2; ++k) \
;         acc[ai][bj][m][n] = __builtin_amdgcn_mfma_f32_16x16x32_bf16(Bt[n][k], At[m][k], acc[ai][bj][m][n], 0, 0, 0); __builtin_amdgcn_s_setprio(0); } while (0)
; #define PG8_WAIT_V(n) asm volatile("s_waitcnt vmcnt(" #n ")" ::: "memory")
; #define PG8_WAIT_L(n) asm volatile("s_waitcnt lgkmcnt(" #n ")" ::: "memory")
; #define PG8_BAR __builtin_amdgcn_s_barrier()
; #define PG8_SCHED __builtin_amdgcn_sched_barrier(0)
; template <class Epi>
; __device__ __forceinline__ void gemm_phase(LAS unsigned char* lds, const Gemm g, const StaticOrder& S, const Epi& E) {
;     ...
;             PG8_WAIT_V(8); PG8_WAIT_L(0); PG8_BAR; PG8_MMA(1, 0, At, B0); PG8_MMA(1, 1, At, B1); PG8_BAR; PG8_SCHED;
;             PG8_LDB(B0, 1, 0); PG8_LDB(B1, 1, 1); PG8_SCHED; PG8_LDA(At, 1, 0); PG8_STAGE(PG8_SA(0, 1), a2 + hstepA, voffA);
;             PG8_WAIT_V(8); PG8_WAIT_L(0); PG8_BAR; PG8_MMA(0, 0, At, B0); PG8_MMA(0, 1, At, B1); PG8_BAR; PG8_SCHED;
	s_setprio 1
	s_waitcnt lgkmcnt(0)
	v_mfma_f32_16x16x32_bf16 v[60:63], v[128:131], v[188:191], v[60:63]
	v_mfma_f32_16x16x32_bf16 v[60:63], v[132:135], v[192:195], v[60:63]
	v_mfma_f32_16x16x32_bf16 v[44:47], v[132:135], v[200:203], v[44:47]
	v_mfma_f32_16x16x32_bf16 v[44:47], v[128:131], v[196:199], v[44:47]
	v_mfma_f32_16x16x32_bf16 v[28:31], v[128:131], v[208:211], v[28:31]
	v_mfma_f32_16x16x32_bf16 v[28:31], v[132:135], v[212:215], v[28:31]
	v_mfma_f32_16x16x32_bf16 v[12:15], v[132:135], v[220:223], v[12:15]
	v_mfma_f32_16x16x32_bf16 v[12:15], v[128:131], v[216:219], v[12:15]
	v_mfma_f32_16x16x32_bf16 v[8:11], v[136:139], v[216:219], v[8:11]
	v_mfma_f32_16x16x32_bf16 v[8:11], v[140:143], v[220:223], v[8:11]
	v_mfma_f32_16x16x32_bf16 v[24:27], v[140:143], v[212:215], v[24:27]
	v_mfma_f32_16x16x32_bf16 v[24:27], v[136:139], v[208:211], v[24:27]
	v_mfma_f32_16x16x32_bf16 v[40:43], v[136:139], v[196:199], v[40:43]
	v_mfma_f32_16x16x32_bf16 v[40:43], v[140:143], v[200:203], v[40:43]
	v_mfma_f32_16x16x32_bf16 v[56:59], v[140:143], v[192:195], v[56:59]
	v_mfma_f32_16x16x32_bf16 v[56:59], v[136:139], v[188:191], v[56:59]
	s_setprio 0
	s_setprio 1
	v_mfma_f32_16x16x32_bf16 v[52:55], v[144:147], v[188:191], v[52:55]
	v_mfma_f32_16x16x32_bf16 v[52:55], v[148:151], v[192:195], v[52:55]
	v_mfma_f32_16x16x32_bf16 v[36:39], v[148:151], v[200:203], v[36:39]
	v_mfma_f32_16x16x32_bf16 v[36:39], v[144:147], v[196:199], v[36:39]
	v_mfma_f32_16x16x32_bf16 v[20:23], v[144:147], v[208:211], v[20:23]
	v_mfma_f32_16x16x32_bf16 v[20:23], v[148:151], v[212:215], v[20:23]
	v_mfma_f32_16x16x32_bf16 v[4:7], v[148:151], v[220:223], v[4:7]
	v_mfma_f32_16x16x32_bf16 v[4:7], v[144:147], v[216:219], v[4:7]
	v_mfma_f32_16x16x32_bf16 v[0:3], v[176:179], v[216:219], v[0:3]
	v_mfma_f32_16x16x32_bf16 v[0:3], v[184:187], v[220:223], v[0:3]
	v_mfma_f32_16x16x32_bf16 v[16:19], v[184:187], v[212:215], v[16:19]
	v_mfma_f32_16x16x32_bf16 v[16:19], v[176:179], v[208:211], v[16:19]
	v_mfma_f32_16x16x32_bf16 v[32:35], v[176:179], v[196:199], v[32:35]
	v_mfma_f32_16x16x32_bf16 v[32:35], v[184:187], v[200:203], v[32:35]
	v_mfma_f32_16x16x32_bf16 v[48:51], v[184:187], v[192:195], v[48:51]
	v_mfma_f32_16x16x32_bf16 v[48:51], v[176:179], v[188:191], v[48:51]
	s_setprio 0
	s_barrier
	s_add_i32 s21, 0, 0x18000
	s_add_i32 s33, 0, 0x1c000
	v_add_u32_e32 v140, s21, v163
	v_add_u32_e32 v172, s33, v163
	ds_read_b128 v[128:131], v140
	ds_read_b128 v[132:135], v140 offset:1024
	ds_read_b128 v[136:139], v140 offset:2048
	ds_read_b128 v[140:143], v140 offset:3072
	ds_read_b128 v[144:147], v172
	ds_read_b128 v[148:151], v172 offset:1024
	ds_read_b128 v[176:179], v172 offset:2048
	ds_read_b128 v[184:187], v172 offset:3072
	s_add_u32 s12, s12, 0x80000
	s_addc_u32 s13, s13, 0
	s_mov_b32 m0, s49
	v_lshl_add_u64 v[234:235], s[12:13], 0, v[152:153]
	ds_read_b128 v[188:191], v181 offset:32768
	ds_read_b128 v[192:195], v181 offset:33792
	ds_read_b128 v[196:199], v181 offset:34816
	ds_read_b128 v[200:203], v181 offset:35840
	ds_read_b128 v[208:211], v181 offset:36864
	ds_read_b128 v[212:215], v181 offset:37888
	ds_read_b128 v[216:219], v181 offset:38912
	ds_read_b128 v[220:223], v181 offset:39936
	global_load_lds_dwordx4 v[234:235], off
	v_lshl_add_u64 v[234:235], s[12:13], 0, v[156:157]
	s_mov_b32 m0, s50
	s_nop 0
	global_load_lds_dwordx4 v[234:235], off
	s_waitcnt vmcnt(8)
	s_waitcnt lgkmcnt(0)
	s_barrier
	s_setprio 1
	s_waitcnt lgkmcnt(0)
	v_mfma_f32_16x16x32_bf16 v[124:127], v[128:131], v[188:191], v[124:127]
	v_mfma_f32_16x16x32_bf16 v[124:127], v[132:135], v[192:195], v[124:127]
	v_mfma_f32_16x16x32_bf16 v[108:111], v[132:135], v[200:203], v[108:111]
	v_mfma_f32_16x16x32_bf16 v[108:111], v[128:131], v[196:199], v[108:111]
	v_mfma_f32_16x16x32_bf16 v[92:95], v[128:131], v[208:211], v[92:95]
	v_mfma_f32_16x16x32_bf16 v[92:95], v[132:135], v[212:215], v[92:95]
	v_mfma_f32_16x16x32_bf16 v[76:79], v[132:135], v[220:223], v[76:79]
	v_mfma_f32_16x16x32_bf16 v[76:79], v[128:131], v[216:219], v[76:79]
	v_mfma_f32_16x16x32_bf16 v[72:75], v[136:139], v[216:219], v[72:75]
	v_mfma_f32_16x16x32_bf16 v[72:75], v[140:143], v[220:223], v[72:75]
	v_mfma_f32_16x16x32_bf16 v[88:91], v[140:143], v[212:215], v[88:91]
	v_mfma_f32_16x16x32_bf16 v[88:91], v[136:139], v[208:211], v[88:91]
	v_mfma_f32_16x16x32_bf16 v[104:107], v[136:139], v[196:199], v[104:107]
	v_mfma_f32_16x16x32_bf16 v[104:107], v[140:143], v[200:203], v[104:107]
	v_mfma_f32_16x16x32_bf16 v[120:123], v[140:143], v[192:195], v[120:123]
	v_mfma_f32_16x16x32_bf16 v[120:123], v[136:139], v[188:191], v[120:123]
	s_setprio 0
	s_setprio 1
	v_mfma_f32_16x16x32_bf16 v[116:119], v[144:147], v[188:191], v[116:119]
	v_mfma_f32_16x16x32_bf16 v[116:119], v[148:151], v[192:195], v[116:119]
	v_mfma_f32_16x16x32_bf16 v[100:103], v[148:151], v[200:203], v[100:103]
	v_mfma_f32_16x16x32_bf16 v[100:103], v[144:147], v[196:199], v[100:103]
	v_mfma_f32_16x16x32_bf16 v[84:87], v[144:147], v[208:211], v[84:87]
	v_mfma_f32_16x16x32_bf16 v[84:87], v[148:151], v[212:215], v[84:87]
	v_mfma_f32_16x16x32_bf16 v[68:71], v[148:151], v[220:223], v[68:71]
	v_mfma_f32_16x16x32_bf16 v[68:71], v[144:147], v[216:219], v[68:71]
	v_mfma_f32_16x16x32_bf16 v[64:67], v[176:179], v[216:219], v[64:67]
	v_mfma_f32_16x16x32_bf16 v[64:67], v[184:187], v[220:223], v[64:67]
	v_mfma_f32_16x16x32_bf16 v[80:83], v[184:187], v[212:215], v[80:83]
	v_mfma_f32_16x16x32_bf16 v[80:83], v[176:179], v[208:211], v[80:83]
	v_mfma_f32_16x16x32_bf16 v[96:99], v[176:179], v[196:199], v[96:99]
	v_mfma_f32_16x16x32_bf16 v[96:99], v[184:187], v[200:203], v[96:99]
	v_mfma_f32_16x16x32_bf16 v[112:115], v[184:187], v[192:195], v[112:115]
	v_mfma_f32_16x16x32_bf16 v[112:115], v[176:179], v[188:191], v[112:115]
	s_setprio 0
	s_barrier
; #define PG8_STAGE(bufoff, gbase, voff) do { _Pragma("unroll") for (int _i = 0; _i < 2; ++_i) \
;         __builtin_amdgcn_global_load_lds((const unsigned*)((const char*)(gbase) + (voff)[_i]), (LAS unsigned*)(lds + (bufoff) + ldsw + _i * 8192), 16, 0, 0); } while (0)
; #define PG8_LDA(dst, b, h) do { _Pragma("unroll") for (int m = 0; m < 4; ++m) _Pragma("unroll") for (int k = 0; k < 2; ++k) dst[m][k] = *(const LAS bf16x8*)(lds + PG8_SA(b, h) + aoff + m * 2048 + k * 1024); } while (0)
; #define PG8_MMA(ai, bj, At, Bt) do { __builtin_amdgcn_s_setprio(1); _Pragma("unroll") for (int m = 0; m < 4; ++m) _Pragma("unroll") for (int n = 0; n < 2; ++n) _Pragma("unroll") for (int k = 0; k < 2; ++k) \
;         acc[ai][bj][m][n] = __builtin_amdgcn_mfma_f32_16x16x32_bf16(Bt[n][k], At[m][k], acc[ai][bj][m][n], 0, 0, 0); __builtin_amdgcn_s_setprio(0); } while (0)
; #define PG8_WAIT_V(n) asm volatile("s_waitcnt vmcnt(" #n ")" ::: "memory")
; #define PG8_WAIT_L(n) asm volatile("s_waitcnt lgkmcnt(" #n ")" ::: "memory")
; #define PG8_BAR __builtin_amdgcn_s_barrier()
; #define PG8_SCHED __builtin_amdgcn_sched_barrier(0)
; template <class Epi>
; __device__ __forceinline__ void gemm_phase(LAS unsigned char* lds, const Gemm g, const StaticOrder& S, const Epi& E) {
;     ...
;             PG8_LDA(At, 1, 1); PG8_STAGE(PG8_SB(1, 0), b3, voffB); PG8_STAGE(PG8_SB(1, 1), b3 + hstepB, voffB); PG8_STAGE(PG8_SA(1, 0), a3, voffA);
;             PG8_WAIT_V(8); PG8_WAIT_L(0); PG8_BAR; PG8_MMA(1, 0, At, B0); PG8_MMA(1, 1, At, B1); PG8_BAR; PG8_SCHED;
;         }
	s_add_i32 s12, s21, s46
	v_lshl_add_u64 v[224:225], v[224:225], 0, s[28:29]
	s_mov_b32 m0, s12
	ds_read_b128 v[188:191], v181 offset:49152
	ds_read_b128 v[192:195], v181 offset:50176
	ds_read_b128 v[196:199], v181 offset:51200
	ds_read_b128 v[200:203], v181 offset:52224
	ds_read_b128 v[208:211], v181 offset:53248
	ds_read_b128 v[212:215], v181 offset:54272
	ds_read_b128 v[216:219], v181 offset:55296
	ds_read_b128 v[220:223], v181 offset:56320
	global_load_lds_dwordx4 v[224:225], off
	s_add_i32 m0, s12, 0x2000
	s_add_u32 s10, s10, 0x80080
	v_lshl_add_u64 v[224:225], v[226:227], 0, s[28:29]
	s_addc_u32 s11, s11, 0
	s_add_i32 s12, s33, s46
	global_load_lds_dwordx4 v[224:225], off
	v_lshl_add_u64 v[224:225], s[10:11], 0, v[154:155]
	s_mov_b32 m0, s12
	s_nop 0
	global_load_lds_dwordx4 v[224:225], off
	v_lshl_add_u64 v[224:225], s[10:11], 0, v[158:159]
	s_add_i32 m0, s12, 0x2000
	s_nop 0
	global_load_lds_dwordx4 v[224:225], off
	v_lshl_add_u64 v[224:225], v[230:231], 0, s[28:29]
	s_mov_b32 m0, s54
	s_nop 0
	global_load_lds_dwordx4 v[224:225], off
	v_lshl_add_u64 v[224:225], v[232:233], 0, s[28:29]
	s_mov_b32 m0, s55
	s_nop 0
	global_load_lds_dwordx4 v[224:225], off
	s_waitcnt vmcnt(8)
	s_waitcnt lgkmcnt(0)
	s_barrier
	s_setprio 1
	s_waitcnt lgkmcnt(0)
	v_mfma_f32_16x16x32_bf16 v[60:63], v[128:131], v[188:191], v[60:63]
	v_mfma_f32_16x16x32_bf16 v[60:63], v[132:135], v[192:195], v[60:63]
	v_mfma_f32_16x16x32_bf16 v[44:47], v[132:135], v[200:203], v[44:47]
	v_mfma_f32_16x16x32_bf16 v[44:47], v[128:131], v[196:199], v[44:47]
	v_mfma_f32_16x16x32_bf16 v[28:31], v[128:131], v[208:211], v[28:31]
	v_mfma_f32_16x16x32_bf16 v[28:31], v[132:135], v[212:215], v[28:31]
	v_mfma_f32_16x16x32_bf16 v[12:15], v[132:135], v[220:223], v[12:15]
	v_mfma_f32_16x16x32_bf16 v[12:15], v[128:131], v[216:219], v[12:15]
	v_mfma_f32_16x16x32_bf16 v[8:11], v[136:139], v[216:219], v[8:11]
	v_mfma_f32_16x16x32_bf16 v[8:11], v[140:143], v[220:223], v[8:11]
	v_mfma_f32_16x16x32_bf16 v[24:27], v[140:143], v[212:215], v[24:27]
	v_mfma_f32_16x16x32_bf16 v[24:27], v[136:139], v[208:211], v[24:27]
	v_mfma_f32_16x16x32_bf16 v[40:43], v[136:139], v[196:199], v[40:43]
	v_mfma_f32_16x16x32_bf16 v[40:43], v[140:143], v[200:203], v[40:43]
	v_mfma_f32_16x16x32_bf16 v[56:59], v[140:143], v[192:195], v[56:59]
	v_mfma_f32_16x16x32_bf16 v[56:59], v[136:139], v[188:191], v[56:59]
	s_setprio 0
	s_setprio 1
	v_mfma_f32_16x16x32_bf16 v[52:55], v[144:147], v[188:191], v[52:55]
	v_mfma_f32_16x16x32_bf16 v[52:55], v[148:151], v[192:195], v[52:55]
	v_mfma_f32_16x16x32_bf16 v[36:39], v[148:151], v[200:203], v[36:39]
	v_mfma_f32_16x16x32_bf16 v[36:39], v[144:147], v[196:199], v[36:39]
	v_mfma_f32_16x16x32_bf16 v[20:23], v[144:147], v[208:211], v[20:23]
	v_mfma_f32_16x16x32_bf16 v[20:23], v[148:151], v[212:215], v[20:23]
	v_mfma_f32_16x16x32_bf16 v[4:7], v[148:151], v[220:223], v[4:7]
	v_mfma_f32_16x16x32_bf16 v[4:7], v[144:147], v[216:219], v[4:7]
	v_mfma_f32_16x16x32_bf16 v[0:3], v[176:179], v[216:219], v[0:3]
	v_mfma_f32_16x16x32_bf16 v[0:3], v[184:187], v[220:223], v[0:3]
	v_mfma_f32_16x16x32_bf16 v[16:19], v[184:187], v[212:215], v[16:19]
	v_mfma_f32_16x16x32_bf16 v[16:19], v[176:179], v[208:211], v[16:19]
	v_mfma_f32_16x16x32_bf16 v[32:35], v[176:179], v[196:199], v[32:35]
	v_mfma_f32_16x16x32_bf16 v[32:35], v[184:187], v[200:203], v[32:35]
	v_mfma_f32_16x16x32_bf16 v[48:51], v[184:187], v[192:195], v[48:51]
	v_mfma_f32_16x16x32_bf16 v[48:51], v[176:179], v[188:191], v[48:51]
	s_setprio 0
	s_barrier
	s_add_u32 s8, s8, 0x100
	s_addc_u32 s9, s9, 0
	s_add_u32 s18, s18, 0x100
	s_addc_u32 s19, s19, 0
	s_cmp_ge_i32 s20, s53
	s_mov_b32 s10, s20
	s_cbranch_scc0 .LBB0_1338
